# v12: GEMM K-loops peeled (first MFMA per accumulator takes SrcC=0), 128 accumulator zero-init v_movs per unit dropped in all 7 GEMM instances
# speedup vs baseline: 1.0069x; 1.0035x over previous
;     __device__ bool next(int i, Unit& u) const { if (i >= n) return false; const int q = first + i; u.pm = rowbase + q % rows; u.pn = q / rows; return true; }
; #define PG8_STAGE(bufoff, gbase, voff) do { _Pragma("unroll") for (int _i = 0; _i < 2; ++_i) \
;         __builtin_amdgcn_global_load_lds((const unsigned*)((const char*)(gbase) + (voff)[_i]), (PG8_LAS unsigned*)(lds + (bufoff) + ldsw + _i * 8192), 16, 0, 0); } while (0)
; #define PG8_LDA(dst, b, h) do { _Pragma("unroll") for (int m = 0; m < 4; ++m) _Pragma("unroll") for (int k = 0; k < 2; ++k) dst[m][k] = *(const PG8_LAS bf16x8*)(lds + PG8_SA(b, h) + aoff + m * 2048 + k * 1024); } while (0)
; #define PG8_WAIT_V(n) asm volatile("s_waitcnt vmcnt(" #n ")" ::: "memory")
; template <class Epi, class Sched, bool ALIGN_EPI = false, bool SP2 = false>
; __device__ __forceinline__ void gemm_phase(PG8_LAS unsigned char* lds, const Gemm g, const Sched& S, const Epi& E) {
;     ...
;         const bool has_next = S.next(ui + 1, nxt);
;         const char* nA = has_next ? (const char*)g.A + (size_t)nxt.pm * tstep : cA; const char* nB = has_next ? (const char*)g.Bt + (size_t)nxt.pn * tstep : cB;
;         constexpr int NSEG = Epi::HAS_MID ? 2 : 1; const int tseg = nt / NSEG;
; #pragma unroll
;         for (int seg = 0; seg < NSEG; ++seg) {
;         if constexpr (Epi::HAS_MID) { if (seg == 1) E.mid(acc, cur, wr, wc, fr, fq); }
;         for (int t = seg * tseg; t < (seg + 1) * tseg; t += 2) {
;             const bool last = (t == nt - 2);
;             const char* a1 = cA + (size_t)(t + 1) * kstep;
;             const char* a2 = last ? nA : cA + (size_t)(t + 2) * kstep; const char* b2 = last ? nB : cB + (size_t)(t + 2) * kstep;
;             const char* a3 = a2 + kstep; const char* b3 = b2 + kstep;
;             if (last && has_next) S.a_ready(nxt);
;             if constexpr (SP2) {
;             PG8_LDB(B0, 0, 0); PG8_LDB(B1, 0, 1); PG8_SCHED; PG8_LDA(At, 0, 0); PG8_STAGE(PG8_SA(1, 1), a1 + hstep, voffA);
;             PG8_WAIT_V(8); PG8_WAIT_L(0); PG8_BAR; PG8_MMA(0, 0, At, B0); PG8_MMA(0, 1, At, B1); PG8_BAR; PG8_SCHED;
;             PG8_LDA(At, 0, 1); PG8_STAGE(PG8_SB(0, 0), b2, voffB); PG8_STAGE(PG8_SB(0, 1), b2 + hstep, voffB); PG8_STAGE(PG8_SA(0, 0), a2, voffA);
;             PG8_WAIT_V(8); PG8_WAIT_L(0); PG8_BAR; PG8_MMA(1, 0, At, B0); PG8_MMA(1, 1, At, B1); PG8_BAR; PG8_SCHED;
.LBB0_275:
	s_ashr_i32 s15, s14, 31
	s_lshl_b64 s[0:1], s[14:15], 20
	s_add_u32 s64, s54, s0
	s_addc_u32 s65, s55, s1
	s_and_b64 s[0:1], s[20:21], exec
	s_cselect_b32 s0, s65, s75
	s_cselect_b32 s1, s64, s74
	s_ashr_i32 s13, s12, 31
	s_lshl_b64 s[28:29], s[12:13], 20
	s_add_u32 s68, s36, s28
	s_addc_u32 s69, s37, s29
	s_and_b64 s[28:29], s[20:21], exec
	s_cselect_b32 s3, s69, s85
	s_cselect_b32 s4, s68, s84
	s_add_u32 s74, s74, 0x80080
	s_addc_u32 s75, s75, 0
	s_add_u32 s13, s84, 0x100
	s_addc_u32 s15, s85, 0
	s_mov_b32 s28, -2
	ds_read_b128 v[150:153], v158
	ds_read_b128 v[162:165], v158 offset:1024
	ds_read_b128 v[166:169], v158 offset:2048
	ds_read_b128 v[170:173], v158 offset:3072
	ds_read_b128 v[174:177], v159
	ds_read_b128 v[178:181], v159 offset:1024
	ds_read_b128 v[182:185], v159 offset:2048
	ds_read_b128 v[190:193], v159 offset:3072
	s_add_u32 s29, s74, 0xfff80080
	s_addc_u32 s57, s75, -1
	s_cmp_eq_u32 s28, 28
	s_cselect_b32 s89, s0, s57
	s_cselect_b32 s88, s1, s29
	s_cselect_b32 s85, s3, s15
	s_cselect_b32 s84, s4, s13
	v_lshl_add_u64 v[154:155], s[74:75], 0, v[142:143]
	s_add_i32 m0, s30, 0xc000
	ds_read_b128 v[194:197], v160
	ds_read_b128 v[198:201], v160 offset:1024
	ds_read_b128 v[202:205], v160 offset:2048
	ds_read_b128 v[206:209], v160 offset:3072
	ds_read_b128 v[210:213], v160 offset:4096
	ds_read_b128 v[214:217], v160 offset:5120
	ds_read_b128 v[218:221], v160 offset:6144
	ds_read_b128 v[222:225], v160 offset:7168
	global_load_lds_dwordx4 v[154:155], off
	v_lshl_add_u64 v[154:155], s[74:75], 0, v[144:145]
	s_add_i32 m0, s30, 0xe000
	s_nop 0
	global_load_lds_dwordx4 v[154:155], off
	s_waitcnt vmcnt(8)
	s_waitcnt lgkmcnt(0)
	s_barrier
	s_setprio 1
	s_waitcnt lgkmcnt(0)
	v_mfma_f32_16x16x32_bf16 v[124:127], v[150:153], v[194:197], 0
	v_mfma_f32_16x16x32_bf16 v[116:119], v[166:169], v[194:197], 0
	v_mfma_f32_16x16x32_bf16 v[108:111], v[150:153], v[202:205], 0
	v_mfma_f32_16x16x32_bf16 v[100:103], v[166:169], v[202:205], 0
	v_mfma_f32_16x16x32_bf16 v[92:95], v[150:153], v[210:213], 0
	v_mfma_f32_16x16x32_bf16 v[84:87], v[166:169], v[210:213], 0
	v_mfma_f32_16x16x32_bf16 v[76:79], v[150:153], v[218:221], 0
	v_mfma_f32_16x16x32_bf16 v[68:71], v[166:169], v[218:221], 0
	v_mfma_f32_16x16x32_bf16 v[124:127], v[162:165], v[198:201], v[124:127]
	v_mfma_f32_16x16x32_bf16 v[116:119], v[170:173], v[198:201], v[116:119]
	v_mfma_f32_16x16x32_bf16 v[108:111], v[162:165], v[206:209], v[108:111]
	v_mfma_f32_16x16x32_bf16 v[100:103], v[170:173], v[206:209], v[100:103]
	v_mfma_f32_16x16x32_bf16 v[92:95], v[162:165], v[214:217], v[92:95]
	v_mfma_f32_16x16x32_bf16 v[84:87], v[170:173], v[214:217], v[84:87]
	v_mfma_f32_16x16x32_bf16 v[76:79], v[162:165], v[222:225], v[76:79]
	v_mfma_f32_16x16x32_bf16 v[68:71], v[170:173], v[222:225], v[68:71]
	s_setprio 0
	s_setprio 1
	v_mfma_f32_16x16x32_bf16 v[120:123], v[174:177], v[194:197], 0
	v_mfma_f32_16x16x32_bf16 v[112:115], v[182:185], v[194:197], 0
	v_mfma_f32_16x16x32_bf16 v[104:107], v[174:177], v[202:205], 0
	v_mfma_f32_16x16x32_bf16 v[96:99], v[182:185], v[202:205], 0
	v_mfma_f32_16x16x32_bf16 v[88:91], v[174:177], v[210:213], 0
	v_mfma_f32_16x16x32_bf16 v[80:83], v[182:185], v[210:213], 0
	v_mfma_f32_16x16x32_bf16 v[72:75], v[174:177], v[218:221], 0
	v_mfma_f32_16x16x32_bf16 v[64:67], v[182:185], v[218:221], 0
	v_mfma_f32_16x16x32_bf16 v[120:123], v[178:181], v[198:201], v[120:123]
	v_mfma_f32_16x16x32_bf16 v[112:115], v[190:193], v[198:201], v[112:115]
	v_mfma_f32_16x16x32_bf16 v[104:107], v[178:181], v[206:209], v[104:107]
	v_mfma_f32_16x16x32_bf16 v[96:99], v[190:193], v[206:209], v[96:99]
	v_mfma_f32_16x16x32_bf16 v[88:91], v[178:181], v[214:217], v[88:91]
	v_mfma_f32_16x16x32_bf16 v[80:83], v[190:193], v[214:217], v[80:83]
	v_mfma_f32_16x16x32_bf16 v[72:75], v[178:181], v[222:225], v[72:75]
	v_mfma_f32_16x16x32_bf16 v[64:67], v[190:193], v[222:225], v[64:67]
	s_setprio 0
	s_barrier
	s_add_i32 s29, s94, s23
	v_lshl_add_u64 v[154:155], s[84:85], 0, v[130:131]
	s_mov_b32 m0, s29
	ds_read_b128 v[194:197], v160 offset:16384
	ds_read_b128 v[198:201], v160 offset:17408
	ds_read_b128 v[202:205], v160 offset:18432
	ds_read_b128 v[206:209], v160 offset:19456
	ds_read_b128 v[210:213], v160 offset:20480
	ds_read_b128 v[214:217], v160 offset:21504
	ds_read_b128 v[218:221], v160 offset:22528
	ds_read_b128 v[222:225], v160 offset:23552
	global_load_lds_dwordx4 v[154:155], off
	s_add_i32 m0, s29, 0x2000
	s_add_u32 s96, s84, 0x80000
	v_lshl_add_u64 v[186:187], s[84:85], 0, v[134:135]
	s_addc_u32 s97, s85, 0
	s_add_i32 s29, s95, s23
	global_load_lds_dwordx4 v[186:187], off
	v_lshl_add_u64 v[226:227], s[96:97], 0, v[130:131]
	s_mov_b32 m0, s29
	v_lshl_add_u64 v[228:229], s[88:89], 0, v[132:133]
	global_load_lds_dwordx4 v[226:227], off
	v_lshl_add_u64 v[226:227], s[96:97], 0, v[134:135]
	s_add_i32 m0, s29, 0x2000
	s_nop 0
	global_load_lds_dwordx4 v[226:227], off
	v_lshl_add_u64 v[226:227], s[88:89], 0, v[128:129]
	s_mov_b32 m0, s30
	s_nop 0
	global_load_lds_dwordx4 v[226:227], off
	s_mov_b32 m0, s31
	s_nop 0
	global_load_lds_dwordx4 v[228:229], off
	s_waitcnt vmcnt(8)
	s_waitcnt lgkmcnt(0)
	s_barrier
; #define PG8_STAGE(bufoff, gbase, voff) do { _Pragma("unroll") for (int _i = 0; _i < 2; ++_i) \
;         __builtin_amdgcn_global_load_lds((const unsigned*)((const char*)(gbase) + (voff)[_i]), (PG8_LAS unsigned*)(lds + (bufoff) + ldsw + _i * 8192), 16, 0, 0); } while (0)
; #define PG8_LDA(dst, b, h) do { _Pragma("unroll") for (int m = 0; m < 4; ++m) _Pragma("unroll") for (int k = 0; k < 2; ++k) dst[m][k] = *(const PG8_LAS bf16x8*)(lds + PG8_SA(b, h) + aoff + m * 2048 + k * 1024); } while (0)
; #define PG8_LDB(dst, b, h) do { _Pragma("unroll") for (int n = 0; n < 2; ++n) _Pragma("unroll") for (int k = 0; k < 2; ++k) dst[n][k] = *(const PG8_LAS bf16x8*)(lds + PG8_SB(b, h) + boff + n * 2048 + k * 1024); } while (0)
; #define PG8_MMA(ai, bj, At, Bt) do { __builtin_amdgcn_s_setprio(1); _Pragma("unroll") for (int m = 0; m < 4; ++m) _Pragma("unroll") for (int n = 0; n < 2; ++n) _Pragma("unroll") for (int k = 0; k < 2; ++k) \
;         acc[ai][bj][m][n] = __builtin_amdgcn_mfma_f32_16x16x32_bf16(Bt[n][k], At[m][k], acc[ai][bj][m][n], 0, 0, 0); __builtin_amdgcn_s_setprio(0); } while (0)
; #define PG8_BAR __builtin_amdgcn_s_barrier()
; template <class Epi, class Sched, bool ALIGN_EPI = false, bool SP2 = false>
; __device__ __forceinline__ void gemm_phase(PG8_LAS unsigned char* lds, const Gemm g, const Sched& S, const Epi& E) {
;     ...
;             if constexpr (SP2) {
;             PG8_LDB(B0, 0, 0); PG8_LDB(B1, 0, 1); PG8_SCHED; PG8_LDA(At, 0, 0); PG8_STAGE(PG8_SA(1, 1), a1 + hstep, voffA);
;             PG8_WAIT_V(8); PG8_WAIT_L(0); PG8_BAR; PG8_MMA(0, 0, At, B0); PG8_MMA(0, 1, At, B1); PG8_BAR; PG8_SCHED;
;             PG8_LDA(At, 0, 1); PG8_STAGE(PG8_SB(0, 0), b2, voffB); PG8_STAGE(PG8_SB(0, 1), b2 + hstep, voffB); PG8_STAGE(PG8_SA(0, 0), a2, voffA);
;             PG8_WAIT_V(8); PG8_WAIT_L(0); PG8_BAR; PG8_MMA(1, 0, At, B0); PG8_MMA(1, 1, At, B1); PG8_BAR; PG8_SCHED;
;             PG8_LDB(B0, 1, 0); PG8_LDB(B1, 1, 1); PG8_SCHED; PG8_LDA(At, 1, 0); PG8_STAGE(PG8_SA(0, 1), a2 + hstep, voffA);
;             PG8_WAIT_V(8); PG8_WAIT_L(0); PG8_BAR; PG8_MMA(0, 0, At, B0); PG8_MMA(0, 1, At, B1); PG8_BAR; PG8_SCHED;
;             PG8_LDA(At, 1, 1); PG8_STAGE(PG8_SB(1, 0), b3, voffB); PG8_STAGE(PG8_SB(1, 1), b3 + hstep, voffB); PG8_STAGE(PG8_SA(1, 0), a3, voffA);
;             PG8_WAIT_V(8); PG8_WAIT_L(0); PG8_BAR; PG8_MMA(1, 0, At, B0); PG8_MMA(1, 1, At, B1); PG8_BAR; PG8_SCHED;
	s_setprio 1
	s_waitcnt lgkmcnt(0)
	v_mfma_f32_16x16x32_bf16 v[60:63], v[150:153], v[194:197], 0
	v_mfma_f32_16x16x32_bf16 v[52:55], v[166:169], v[194:197], 0
	v_mfma_f32_16x16x32_bf16 v[44:47], v[150:153], v[202:205], 0
	v_mfma_f32_16x16x32_bf16 v[36:39], v[166:169], v[202:205], 0
	v_mfma_f32_16x16x32_bf16 v[28:31], v[150:153], v[210:213], 0
	v_mfma_f32_16x16x32_bf16 v[20:23], v[166:169], v[210:213], 0
	v_mfma_f32_16x16x32_bf16 v[12:15], v[150:153], v[218:221], 0
	v_mfma_f32_16x16x32_bf16 v[4:7], v[166:169], v[218:221], 0
	v_mfma_f32_16x16x32_bf16 v[60:63], v[162:165], v[198:201], v[60:63]
	v_mfma_f32_16x16x32_bf16 v[52:55], v[170:173], v[198:201], v[52:55]
	v_mfma_f32_16x16x32_bf16 v[44:47], v[162:165], v[206:209], v[44:47]
	v_mfma_f32_16x16x32_bf16 v[36:39], v[170:173], v[206:209], v[36:39]
	v_mfma_f32_16x16x32_bf16 v[28:31], v[162:165], v[214:217], v[28:31]
	v_mfma_f32_16x16x32_bf16 v[20:23], v[170:173], v[214:217], v[20:23]
	v_mfma_f32_16x16x32_bf16 v[12:15], v[162:165], v[222:225], v[12:15]
	v_mfma_f32_16x16x32_bf16 v[4:7], v[170:173], v[222:225], v[4:7]
	s_setprio 0
	s_setprio 1
	v_mfma_f32_16x16x32_bf16 v[56:59], v[174:177], v[194:197], 0
	v_mfma_f32_16x16x32_bf16 v[48:51], v[182:185], v[194:197], 0
	v_mfma_f32_16x16x32_bf16 v[40:43], v[174:177], v[202:205], 0
	v_mfma_f32_16x16x32_bf16 v[32:35], v[182:185], v[202:205], 0
	v_mfma_f32_16x16x32_bf16 v[24:27], v[174:177], v[210:213], 0
	v_mfma_f32_16x16x32_bf16 v[16:19], v[182:185], v[210:213], 0
	v_mfma_f32_16x16x32_bf16 v[8:11], v[174:177], v[218:221], 0
	v_mfma_f32_16x16x32_bf16 v[0:3], v[182:185], v[218:221], 0
	v_mfma_f32_16x16x32_bf16 v[56:59], v[178:181], v[198:201], v[56:59]
	v_mfma_f32_16x16x32_bf16 v[48:51], v[190:193], v[198:201], v[48:51]
	v_mfma_f32_16x16x32_bf16 v[40:43], v[178:181], v[206:209], v[40:43]
	v_mfma_f32_16x16x32_bf16 v[32:35], v[190:193], v[206:209], v[32:35]
	v_mfma_f32_16x16x32_bf16 v[24:27], v[178:181], v[214:217], v[24:27]
	v_mfma_f32_16x16x32_bf16 v[16:19], v[190:193], v[214:217], v[16:19]
	v_mfma_f32_16x16x32_bf16 v[8:11], v[178:181], v[222:225], v[8:11]
	v_mfma_f32_16x16x32_bf16 v[0:3], v[190:193], v[222:225], v[0:3]
	s_setprio 0
	s_barrier
	s_add_i32 s29, 0, 0x18000
	v_add_u32_e32 v136, s29, v156
	s_add_i32 s57, 0, 0x1c000
	ds_read_b128 v[150:153], v136
	ds_read_b128 v[162:165], v136 offset:1024
	ds_read_b128 v[166:169], v136 offset:2048
	ds_read_b128 v[170:173], v136 offset:3072
	v_add_u32_e32 v136, s57, v156
	ds_read_b128 v[174:177], v136
	ds_read_b128 v[178:181], v136 offset:1024
	ds_read_b128 v[182:185], v136 offset:2048
	ds_read_b128 v[190:193], v136 offset:3072
	s_add_u32 s88, s88, 0x80000
	s_addc_u32 s89, s89, 0
	s_mov_b32 m0, s33
	v_lshl_add_u64 v[230:231], s[88:89], 0, v[128:129]
	ds_read_b128 v[194:197], v160 offset:32768
	ds_read_b128 v[198:201], v160 offset:33792
	ds_read_b128 v[202:205], v160 offset:34816
	ds_read_b128 v[206:209], v160 offset:35840
	ds_read_b128 v[210:213], v160 offset:36864
	ds_read_b128 v[214:217], v160 offset:37888
	ds_read_b128 v[218:221], v160 offset:38912
	ds_read_b128 v[222:225], v160 offset:39936
	global_load_lds_dwordx4 v[230:231], off
	v_lshl_add_u64 v[230:231], s[88:89], 0, v[132:133]
	s_mov_b32 m0, s71
	s_nop 0
	global_load_lds_dwordx4 v[230:231], off
	s_waitcnt vmcnt(8)
	s_waitcnt lgkmcnt(0)
	s_barrier
	s_setprio 1
	s_waitcnt lgkmcnt(0)
	v_mfma_f32_16x16x32_bf16 v[124:127], v[150:153], v[194:197], v[124:127]
	v_mfma_f32_16x16x32_bf16 v[116:119], v[166:169], v[194:197], v[116:119]
	v_mfma_f32_16x16x32_bf16 v[108:111], v[150:153], v[202:205], v[108:111]
	v_mfma_f32_16x16x32_bf16 v[100:103], v[166:169], v[202:205], v[100:103]
	v_mfma_f32_16x16x32_bf16 v[92:95], v[150:153], v[210:213], v[92:95]
	v_mfma_f32_16x16x32_bf16 v[84:87], v[166:169], v[210:213], v[84:87]
	v_mfma_f32_16x16x32_bf16 v[76:79], v[150:153], v[218:221], v[76:79]
	v_mfma_f32_16x16x32_bf16 v[68:71], v[166:169], v[218:221], v[68:71]
	v_mfma_f32_16x16x32_bf16 v[124:127], v[162:165], v[198:201], v[124:127]
	v_mfma_f32_16x16x32_bf16 v[116:119], v[170:173], v[198:201], v[116:119]
	v_mfma_f32_16x16x32_bf16 v[108:111], v[162:165], v[206:209], v[108:111]
	v_mfma_f32_16x16x32_bf16 v[100:103], v[170:173], v[206:209], v[100:103]
	v_mfma_f32_16x16x32_bf16 v[92:95], v[162:165], v[214:217], v[92:95]
	v_mfma_f32_16x16x32_bf16 v[84:87], v[170:173], v[214:217], v[84:87]
	v_mfma_f32_16x16x32_bf16 v[76:79], v[162:165], v[222:225], v[76:79]
	v_mfma_f32_16x16x32_bf16 v[68:71], v[170:173], v[222:225], v[68:71]
	s_setprio 0
	s_setprio 1
	v_mfma_f32_16x16x32_bf16 v[120:123], v[174:177], v[194:197], v[120:123]
	v_mfma_f32_16x16x32_bf16 v[112:115], v[182:185], v[194:197], v[112:115]
	v_mfma_f32_16x16x32_bf16 v[104:107], v[174:177], v[202:205], v[104:107]
	v_mfma_f32_16x16x32_bf16 v[96:99], v[182:185], v[202:205], v[96:99]
	v_mfma_f32_16x16x32_bf16 v[88:91], v[174:177], v[210:213], v[88:91]
	v_mfma_f32_16x16x32_bf16 v[80:83], v[182:185], v[210:213], v[80:83]
	v_mfma_f32_16x16x32_bf16 v[72:75], v[174:177], v[218:221], v[72:75]
	v_mfma_f32_16x16x32_bf16 v[64:67], v[182:185], v[218:221], v[64:67]
	v_mfma_f32_16x16x32_bf16 v[120:123], v[178:181], v[198:201], v[120:123]
	v_mfma_f32_16x16x32_bf16 v[112:115], v[190:193], v[198:201], v[112:115]
	v_mfma_f32_16x16x32_bf16 v[104:107], v[178:181], v[206:209], v[104:107]
	v_mfma_f32_16x16x32_bf16 v[96:99], v[190:193], v[206:209], v[96:99]
	v_mfma_f32_16x16x32_bf16 v[88:91], v[178:181], v[214:217], v[88:91]
	v_mfma_f32_16x16x32_bf16 v[80:83], v[190:193], v[214:217], v[80:83]
	v_mfma_f32_16x16x32_bf16 v[72:75], v[178:181], v[222:225], v[72:75]
	v_mfma_f32_16x16x32_bf16 v[64:67], v[190:193], v[222:225], v[64:67]
	s_setprio 0
	s_barrier
; #define PG8_STAGE(bufoff, gbase, voff) do { _Pragma("unroll") for (int _i = 0; _i < 2; ++_i) \
;         __builtin_amdgcn_global_load_lds((const unsigned*)((const char*)(gbase) + (voff)[_i]), (PG8_LAS unsigned*)(lds + (bufoff) + ldsw + _i * 8192), 16, 0, 0); } while (0)
; #define PG8_LDA(dst, b, h) do { _Pragma("unroll") for (int m = 0; m < 4; ++m) _Pragma("unroll") for (int k = 0; k < 2; ++k) dst[m][k] = *(const PG8_LAS bf16x8*)(lds + PG8_SA(b, h) + aoff + m * 2048 + k * 1024); } while (0)
; #define PG8_LDB(dst, b, h) do { _Pragma("unroll") for (int n = 0; n < 2; ++n) _Pragma("unroll") for (int k = 0; k < 2; ++k) dst[n][k] = *(const PG8_LAS bf16x8*)(lds + PG8_SB(b, h) + boff + n * 2048 + k * 1024); } while (0)
; #define PG8_MMA(ai, bj, At, Bt) do { __builtin_amdgcn_s_setprio(1); _Pragma("unroll") for (int m = 0; m < 4; ++m) _Pragma("unroll") for (int n = 0; n < 2; ++n) _Pragma("unroll") for (int k = 0; k < 2; ++k) \
;         acc[ai][bj][m][n] = __builtin_amdgcn_mfma_f32_16x16x32_bf16(Bt[n][k], At[m][k], acc[ai][bj][m][n], 0, 0, 0); __builtin_amdgcn_s_setprio(0); } while (0)
; #define PG8_BAR __builtin_amdgcn_s_barrier()
; template <class Epi, class Sched, bool ALIGN_EPI = false, bool SP2 = false>
; __device__ __forceinline__ void gemm_phase(PG8_LAS unsigned char* lds, const Gemm g, const Sched& S, const Epi& E) {
;     ...
;             if constexpr (SP2) {
;             PG8_LDB(B0, 0, 0); PG8_LDB(B1, 0, 1); PG8_SCHED; PG8_LDA(At, 0, 0); PG8_STAGE(PG8_SA(1, 1), a1 + hstep, voffA);
;             PG8_WAIT_V(8); PG8_WAIT_L(0); PG8_BAR; PG8_MMA(0, 0, At, B0); PG8_MMA(0, 1, At, B1); PG8_BAR; PG8_SCHED;
;             PG8_LDA(At, 0, 1); PG8_STAGE(PG8_SB(0, 0), b2, voffB); PG8_STAGE(PG8_SB(0, 1), b2 + hstep, voffB); PG8_STAGE(PG8_SA(0, 0), a2, voffA);
;             PG8_WAIT_V(8); PG8_WAIT_L(0); PG8_BAR; PG8_MMA(1, 0, At, B0); PG8_MMA(1, 1, At, B1); PG8_BAR; PG8_SCHED;
;             PG8_LDB(B0, 1, 0); PG8_LDB(B1, 1, 1); PG8_SCHED; PG8_LDA(At, 1, 0); PG8_STAGE(PG8_SA(0, 1), a2 + hstep, voffA);
;             PG8_WAIT_V(8); PG8_WAIT_L(0); PG8_BAR; PG8_MMA(0, 0, At, B0); PG8_MMA(0, 1, At, B1); PG8_BAR; PG8_SCHED;
;             PG8_LDA(At, 1, 1); PG8_STAGE(PG8_SB(1, 0), b3, voffB); PG8_STAGE(PG8_SB(1, 1), b3 + hstep, voffB); PG8_STAGE(PG8_SA(1, 0), a3, voffA);
;             PG8_WAIT_V(8); PG8_WAIT_L(0); PG8_BAR; PG8_MMA(1, 0, At, B0); PG8_MMA(1, 1, At, B1); PG8_BAR; PG8_SCHED;
	s_add_i32 s29, s29, s23
	v_lshl_add_u64 v[154:155], v[154:155], 0, s[8:9]
	s_mov_b32 m0, s29
	ds_read_b128 v[194:197], v160 offset:49152
	ds_read_b128 v[198:201], v160 offset:50176
	ds_read_b128 v[202:205], v160 offset:51200
	ds_read_b128 v[206:209], v160 offset:52224
	ds_read_b128 v[210:213], v160 offset:53248
	ds_read_b128 v[214:217], v160 offset:54272
	ds_read_b128 v[218:221], v160 offset:55296
	ds_read_b128 v[222:225], v160 offset:56320
	global_load_lds_dwordx4 v[154:155], off
	s_add_i32 m0, s29, 0x2000
	s_add_u32 s84, s84, 0x80080
	v_lshl_add_u64 v[154:155], v[186:187], 0, s[8:9]
	s_addc_u32 s85, s85, 0
	s_add_i32 s29, s57, s23
	global_load_lds_dwordx4 v[154:155], off
	v_lshl_add_u64 v[154:155], s[84:85], 0, v[130:131]
	s_mov_b32 m0, s29
	s_nop 0
	global_load_lds_dwordx4 v[154:155], off
	v_lshl_add_u64 v[154:155], s[84:85], 0, v[134:135]
	s_add_i32 m0, s29, 0x2000
	s_nop 0
	global_load_lds_dwordx4 v[154:155], off
	v_lshl_add_u64 v[154:155], v[226:227], 0, s[8:9]
	s_mov_b32 m0, s92
	s_nop 0
	global_load_lds_dwordx4 v[154:155], off
	v_lshl_add_u64 v[154:155], v[228:229], 0, s[8:9]
	s_mov_b32 m0, s93
	s_nop 0
	global_load_lds_dwordx4 v[154:155], off
	s_waitcnt vmcnt(8)
	s_waitcnt lgkmcnt(0)
	s_barrier
	s_setprio 1
	s_waitcnt lgkmcnt(0)
	v_mfma_f32_16x16x32_bf16 v[60:63], v[150:153], v[194:197], v[60:63]
	v_mfma_f32_16x16x32_bf16 v[52:55], v[166:169], v[194:197], v[52:55]
	v_mfma_f32_16x16x32_bf16 v[44:47], v[150:153], v[202:205], v[44:47]
	v_mfma_f32_16x16x32_bf16 v[36:39], v[166:169], v[202:205], v[36:39]
	v_mfma_f32_16x16x32_bf16 v[28:31], v[150:153], v[210:213], v[28:31]
	v_mfma_f32_16x16x32_bf16 v[20:23], v[166:169], v[210:213], v[20:23]
	v_mfma_f32_16x16x32_bf16 v[12:15], v[150:153], v[218:221], v[12:15]
	v_mfma_f32_16x16x32_bf16 v[4:7], v[166:169], v[218:221], v[4:7]
	v_mfma_f32_16x16x32_bf16 v[60:63], v[162:165], v[198:201], v[60:63]
	v_mfma_f32_16x16x32_bf16 v[52:55], v[170:173], v[198:201], v[52:55]
	v_mfma_f32_16x16x32_bf16 v[44:47], v[162:165], v[206:209], v[44:47]
	v_mfma_f32_16x16x32_bf16 v[36:39], v[170:173], v[206:209], v[36:39]
	v_mfma_f32_16x16x32_bf16 v[28:31], v[162:165], v[214:217], v[28:31]
	v_mfma_f32_16x16x32_bf16 v[20:23], v[170:173], v[214:217], v[20:23]
	v_mfma_f32_16x16x32_bf16 v[12:15], v[162:165], v[222:225], v[12:15]
	v_mfma_f32_16x16x32_bf16 v[4:7], v[170:173], v[222:225], v[4:7]
	s_setprio 0
	s_setprio 1
	v_mfma_f32_16x16x32_bf16 v[56:59], v[174:177], v[194:197], v[56:59]
	v_mfma_f32_16x16x32_bf16 v[48:51], v[182:185], v[194:197], v[48:51]
	v_mfma_f32_16x16x32_bf16 v[40:43], v[174:177], v[202:205], v[40:43]
	v_mfma_f32_16x16x32_bf16 v[32:35], v[182:185], v[202:205], v[32:35]
	v_mfma_f32_16x16x32_bf16 v[24:27], v[174:177], v[210:213], v[24:27]
	v_mfma_f32_16x16x32_bf16 v[16:19], v[182:185], v[210:213], v[16:19]
	v_mfma_f32_16x16x32_bf16 v[8:11], v[174:177], v[218:221], v[8:11]
	v_mfma_f32_16x16x32_bf16 v[0:3], v[182:185], v[218:221], v[0:3]
	v_mfma_f32_16x16x32_bf16 v[56:59], v[178:181], v[198:201], v[56:59]
	v_mfma_f32_16x16x32_bf16 v[48:51], v[190:193], v[198:201], v[48:51]
	v_mfma_f32_16x16x32_bf16 v[40:43], v[178:181], v[206:209], v[40:43]
	v_mfma_f32_16x16x32_bf16 v[32:35], v[190:193], v[206:209], v[32:35]
	v_mfma_f32_16x16x32_bf16 v[24:27], v[178:181], v[214:217], v[24:27]
	v_mfma_f32_16x16x32_bf16 v[16:19], v[190:193], v[214:217], v[16:19]
	v_mfma_f32_16x16x32_bf16 v[8:11], v[178:181], v[222:225], v[8:11]
	v_mfma_f32_16x16x32_bf16 v[0:3], v[190:193], v[222:225], v[0:3]
	s_setprio 0
	s_barrier
	s_add_i32 s28, s28, 2
	s_add_u32 s74, s74, 0x100
	s_addc_u32 s75, s75, 0
	s_add_u32 s13, s13, 0x100
	s_addc_u32 s15, s15, 0
	s_cmp_gt_u32 s28, 29

; #define PG8_STAGE(bufoff, gbase, voff) do { _Pragma("unroll") for (int _i = 0; _i < 2; ++_i) \
;         __builtin_amdgcn_global_load_lds((const unsigned*)((const char*)(gbase) + (voff)[_i]), (PG8_LAS unsigned*)(lds + (bufoff) + ldsw + _i * 8192), 16, 0, 0); } while (0)
; #define PG8_LDA(dst, b, h) do { _Pragma("unroll") for (int m = 0; m < 4; ++m) _Pragma("unroll") for (int k = 0; k < 2; ++k) dst[m][k] = *(const PG8_LAS bf16x8*)(lds + PG8_SA(b, h) + aoff + m * 2048 + k * 1024); } while (0)
; #define PG8_LDB(dst, b, h) do { _Pragma("unroll") for (int n = 0; n < 2; ++n) _Pragma("unroll") for (int k = 0; k < 2; ++k) dst[n][k] = *(const PG8_LAS bf16x8*)(lds + PG8_SB(b, h) + boff + n * 2048 + k * 1024); } while (0)
; #define PG8_WAIT_V(n) asm volatile("s_waitcnt vmcnt(" #n ")" ::: "memory")
; #define PG8_BAR __builtin_amdgcn_s_barrier()
; template <class Epi, class Sched, bool ALIGN_EPI = false, bool SP2 = false>
; __device__ __forceinline__ void gemm_phase(PG8_LAS unsigned char* lds, const Gemm g, const Sched& S, const Epi& E) {
;     ...
;             if constexpr (SP2) {
;             PG8_LDB(B0, 0, 0); PG8_LDB(B1, 0, 1); PG8_SCHED; PG8_LDA(At, 0, 0); PG8_STAGE(PG8_SA(1, 1), a1 + hstep, voffA);
;             PG8_WAIT_V(8); PG8_WAIT_L(0); PG8_BAR; PG8_MMA(0, 0, At, B0); PG8_MMA(0, 1, At, B1); PG8_BAR; PG8_SCHED;
;             PG8_LDA(At, 0, 1); PG8_STAGE(PG8_SB(0, 0), b2, voffB); PG8_STAGE(PG8_SB(0, 1), b2 + hstep, voffB); PG8_STAGE(PG8_SA(0, 0), a2, voffA);
;             PG8_WAIT_V(8); PG8_WAIT_L(0); PG8_BAR; PG8_MMA(1, 0, At, B0); PG8_MMA(1, 1, At, B1); PG8_BAR; PG8_SCHED;
;             PG8_LDB(B0, 1, 0); PG8_LDB(B1, 1, 1); PG8_SCHED; PG8_LDA(At, 1, 0); PG8_STAGE(PG8_SA(0, 1), a2 + hstep, voffA);
;             PG8_WAIT_V(8); PG8_WAIT_L(0); PG8_BAR; PG8_MMA(0, 0, At, B0); PG8_MMA(0, 1, At, B1); PG8_BAR; PG8_SCHED;
;             PG8_LDA(At, 1, 1); PG8_STAGE(PG8_SB(1, 0), b3, voffB); PG8_STAGE(PG8_SB(1, 1), b3 + hstep, voffB); PG8_STAGE(PG8_SA(1, 0), a3, voffA);
;             PG8_WAIT_V(8); PG8_WAIT_L(0); PG8_BAR; PG8_MMA(1, 0, At, B0); PG8_MMA(1, 1, At, B1); PG8_BAR; PG8_SCHED;
;     ...
;         for (int a = 0; a < 2; ++a)
; #pragma unroll
;             for (int b = 0; b < 2; ++b)
; #pragma unroll
;                 for (int m = 0; m < 4; ++m)
; #pragma unroll
;                     for (int n = 0; n < 2; ++n) acc[a][b][m][n] = (f32x4){0.f, 0.f, 0.f, 0.f};
.LBB0_519:
	s_add_u32 s0, s40, 0x100
	s_addc_u32 s1, s41, 0
	s_mov_b32 s97, -2
	ds_read_b128 v[140:143], v150
	ds_read_b128 v[144:147], v150 offset:1024
	ds_read_b128 v[156:159], v150 offset:2048
	ds_read_b128 v[160:163], v150 offset:3072
	ds_read_b128 v[164:167], v151
	ds_read_b128 v[168:171], v151 offset:1024
	ds_read_b128 v[172:175], v151 offset:2048
	ds_read_b128 v[176:179], v151 offset:3072
	s_add_u32 s40, s14, 0x100
	s_addc_u32 s41, s15, 0
	s_cmp_eq_u32 s97, 8
	s_cselect_b32 s65, s13, s41
	s_cselect_b32 s64, s12, s40
	s_cselect_b32 s47, s3, s1
	s_cselect_b32 s46, s2, s0
	s_mov_b32 m0, s77
	v_lshl_add_u64 v[210:211], s[14:15], 0, v[136:137]
	ds_read_b128 v[180:183], v152
	ds_read_b128 v[184:187], v152 offset:1024
	ds_read_b128 v[190:193], v152 offset:2048
	ds_read_b128 v[194:197], v152 offset:3072
	ds_read_b128 v[198:201], v152 offset:4096
	ds_read_b128 v[202:205], v152 offset:5120
	ds_read_b128 v[206:209], v152 offset:6144
	ds_read_b128 v[214:217], v152 offset:7168
	global_load_lds_dwordx4 v[210:211], off
	v_lshl_add_u64 v[210:211], s[14:15], 0, v[138:139]
	s_mov_b32 m0, s78
	s_nop 0
	global_load_lds_dwordx4 v[210:211], off
	s_waitcnt vmcnt(8)
	s_waitcnt lgkmcnt(0)
	s_barrier
	s_setprio 1
	s_waitcnt lgkmcnt(0)
	v_mfma_f32_16x16x32_bf16 v[124:127], v[140:143], v[180:183], 0
	v_mfma_f32_16x16x32_bf16 v[120:123], v[156:159], v[180:183], 0
	v_mfma_f32_16x16x32_bf16 v[108:111], v[140:143], v[190:193], 0
	v_mfma_f32_16x16x32_bf16 v[104:107], v[156:159], v[190:193], 0
	v_mfma_f32_16x16x32_bf16 v[92:95], v[140:143], v[198:201], 0
	v_mfma_f32_16x16x32_bf16 v[88:91], v[156:159], v[198:201], 0
	v_mfma_f32_16x16x32_bf16 v[76:79], v[140:143], v[206:209], 0
	v_mfma_f32_16x16x32_bf16 v[72:75], v[156:159], v[206:209], 0
	v_mfma_f32_16x16x32_bf16 v[124:127], v[144:147], v[184:187], v[124:127]
	v_mfma_f32_16x16x32_bf16 v[120:123], v[160:163], v[184:187], v[120:123]
	v_mfma_f32_16x16x32_bf16 v[108:111], v[144:147], v[194:197], v[108:111]
	v_mfma_f32_16x16x32_bf16 v[104:107], v[160:163], v[194:197], v[104:107]
	v_mfma_f32_16x16x32_bf16 v[92:95], v[144:147], v[202:205], v[92:95]
	v_mfma_f32_16x16x32_bf16 v[88:91], v[160:163], v[202:205], v[88:91]
	v_mfma_f32_16x16x32_bf16 v[76:79], v[144:147], v[214:217], v[76:79]
	v_mfma_f32_16x16x32_bf16 v[72:75], v[160:163], v[214:217], v[72:75]
	s_setprio 0
	s_setprio 1
	v_mfma_f32_16x16x32_bf16 v[116:119], v[164:167], v[180:183], 0
	v_mfma_f32_16x16x32_bf16 v[112:115], v[172:175], v[180:183], 0
	v_mfma_f32_16x16x32_bf16 v[100:103], v[164:167], v[190:193], 0
	v_mfma_f32_16x16x32_bf16 v[96:99], v[172:175], v[190:193], 0
	v_mfma_f32_16x16x32_bf16 v[84:87], v[164:167], v[198:201], 0
	v_mfma_f32_16x16x32_bf16 v[80:83], v[172:175], v[198:201], 0
	v_mfma_f32_16x16x32_bf16 v[68:71], v[164:167], v[206:209], 0
	v_mfma_f32_16x16x32_bf16 v[64:67], v[172:175], v[206:209], 0
	v_mfma_f32_16x16x32_bf16 v[116:119], v[168:171], v[184:187], v[116:119]
	v_mfma_f32_16x16x32_bf16 v[112:115], v[176:179], v[184:187], v[112:115]
	v_mfma_f32_16x16x32_bf16 v[100:103], v[168:171], v[194:197], v[100:103]
	v_mfma_f32_16x16x32_bf16 v[96:99], v[176:179], v[194:197], v[96:99]
	v_mfma_f32_16x16x32_bf16 v[84:87], v[168:171], v[202:205], v[84:87]
	v_mfma_f32_16x16x32_bf16 v[80:83], v[176:179], v[202:205], v[80:83]
	v_mfma_f32_16x16x32_bf16 v[68:71], v[168:171], v[214:217], v[68:71]
	v_mfma_f32_16x16x32_bf16 v[64:67], v[176:179], v[214:217], v[64:67]
	s_setprio 0
	s_barrier
	s_mov_b32 m0, s79
	v_lshl_add_u64 v[210:211], s[46:47], 0, v[132:133]
	s_add_u32 s14, s46, 0x30000
	ds_read_b128 v[180:183], v152 offset:16384
	ds_read_b128 v[184:187], v152 offset:17408
	ds_read_b128 v[190:193], v152 offset:18432
	ds_read_b128 v[194:197], v152 offset:19456
	ds_read_b128 v[198:201], v152 offset:20480
	ds_read_b128 v[202:205], v152 offset:21504
	ds_read_b128 v[206:209], v152 offset:22528
	ds_read_b128 v[214:217], v152 offset:23552
	global_load_lds_dwordx4 v[210:211], off
	v_lshl_add_u64 v[218:219], s[46:47], 0, v[128:129]
	s_mov_b32 m0, s80
	s_addc_u32 s15, s47, 0
	global_load_lds_dwordx4 v[218:219], off
	v_lshl_add_u64 v[220:221], s[14:15], 0, v[132:133]
	s_mov_b32 m0, s81
	v_lshl_add_u64 v[222:223], s[64:65], 0, v[130:131]
	global_load_lds_dwordx4 v[220:221], off
	v_lshl_add_u64 v[220:221], s[14:15], 0, v[128:129]
	s_mov_b32 m0, s82
	s_nop 0
	global_load_lds_dwordx4 v[220:221], off
	v_lshl_add_u64 v[220:221], s[64:65], 0, v[134:135]
	s_mov_b32 m0, s56
	s_nop 0
	global_load_lds_dwordx4 v[220:221], off
	s_mov_b32 m0, s57
	s_nop 0
	global_load_lds_dwordx4 v[222:223], off
	s_waitcnt vmcnt(8)
	s_waitcnt lgkmcnt(0)
	s_barrier
; #define PG8_STAGE(bufoff, gbase, voff) do { _Pragma("unroll") for (int _i = 0; _i < 2; ++_i) \
;         __builtin_amdgcn_global_load_lds((const unsigned*)((const char*)(gbase) + (voff)[_i]), (PG8_LAS unsigned*)(lds + (bufoff) + ldsw + _i * 8192), 16, 0, 0); } while (0)
; #define PG8_LDA(dst, b, h) do { _Pragma("unroll") for (int m = 0; m < 4; ++m) _Pragma("unroll") for (int k = 0; k < 2; ++k) dst[m][k] = *(const PG8_LAS bf16x8*)(lds + PG8_SA(b, h) + aoff + m * 2048 + k * 1024); } while (0)
; #define PG8_LDB(dst, b, h) do { _Pragma("unroll") for (int n = 0; n < 2; ++n) _Pragma("unroll") for (int k = 0; k < 2; ++k) dst[n][k] = *(const PG8_LAS bf16x8*)(lds + PG8_SB(b, h) + boff + n * 2048 + k * 1024); } while (0)
; #define PG8_MMA(ai, bj, At, Bt) do { __builtin_amdgcn_s_setprio(1); _Pragma("unroll") for (int m = 0; m < 4; ++m) _Pragma("unroll") for (int n = 0; n < 2; ++n) _Pragma("unroll") for (int k = 0; k < 2; ++k) \
;         acc[ai][bj][m][n] = __builtin_amdgcn_mfma_f32_16x16x32_bf16(Bt[n][k], At[m][k], acc[ai][bj][m][n], 0, 0, 0); __builtin_amdgcn_s_setprio(0); } while (0)
; #define PG8_BAR __builtin_amdgcn_s_barrier()
; template <class Epi, class Sched, bool ALIGN_EPI = false, bool SP2 = false>
; __device__ __forceinline__ void gemm_phase(PG8_LAS unsigned char* lds, const Gemm g, const Sched& S, const Epi& E) {
;     ...
;             if constexpr (SP2) {
;             PG8_LDB(B0, 0, 0); PG8_LDB(B1, 0, 1); PG8_SCHED; PG8_LDA(At, 0, 0); PG8_STAGE(PG8_SA(1, 1), a1 + hstep, voffA);
;             PG8_WAIT_V(8); PG8_WAIT_L(0); PG8_BAR; PG8_MMA(0, 0, At, B0); PG8_MMA(0, 1, At, B1); PG8_BAR; PG8_SCHED;
;             PG8_LDA(At, 0, 1); PG8_STAGE(PG8_SB(0, 0), b2, voffB); PG8_STAGE(PG8_SB(0, 1), b2 + hstep, voffB); PG8_STAGE(PG8_SA(0, 0), a2, voffA);
;             PG8_WAIT_V(8); PG8_WAIT_L(0); PG8_BAR; PG8_MMA(1, 0, At, B0); PG8_MMA(1, 1, At, B1); PG8_BAR; PG8_SCHED;
;             PG8_LDB(B0, 1, 0); PG8_LDB(B1, 1, 1); PG8_SCHED; PG8_LDA(At, 1, 0); PG8_STAGE(PG8_SA(0, 1), a2 + hstep, voffA);
;             PG8_WAIT_V(8); PG8_WAIT_L(0); PG8_BAR; PG8_MMA(0, 0, At, B0); PG8_MMA(0, 1, At, B1); PG8_BAR; PG8_SCHED;
;             PG8_LDA(At, 1, 1); PG8_STAGE(PG8_SB(1, 0), b3, voffB); PG8_STAGE(PG8_SB(1, 1), b3 + hstep, voffB); PG8_STAGE(PG8_SA(1, 0), a3, voffA);
;             PG8_WAIT_V(8); PG8_WAIT_L(0); PG8_BAR; PG8_MMA(1, 0, At, B0); PG8_MMA(1, 1, At, B1); PG8_BAR; PG8_SCHED;
	s_setprio 1
	s_waitcnt lgkmcnt(0)
	v_mfma_f32_16x16x32_bf16 v[60:63], v[140:143], v[180:183], 0
	v_mfma_f32_16x16x32_bf16 v[56:59], v[156:159], v[180:183], 0
	v_mfma_f32_16x16x32_bf16 v[44:47], v[140:143], v[190:193], 0
	v_mfma_f32_16x16x32_bf16 v[40:43], v[156:159], v[190:193], 0
	v_mfma_f32_16x16x32_bf16 v[28:31], v[140:143], v[198:201], 0
	v_mfma_f32_16x16x32_bf16 v[24:27], v[156:159], v[198:201], 0
	v_mfma_f32_16x16x32_bf16 v[12:15], v[140:143], v[206:209], 0
	v_mfma_f32_16x16x32_bf16 v[8:11], v[156:159], v[206:209], 0
	v_mfma_f32_16x16x32_bf16 v[60:63], v[144:147], v[184:187], v[60:63]
	v_mfma_f32_16x16x32_bf16 v[56:59], v[160:163], v[184:187], v[56:59]
	v_mfma_f32_16x16x32_bf16 v[44:47], v[144:147], v[194:197], v[44:47]
	v_mfma_f32_16x16x32_bf16 v[40:43], v[160:163], v[194:197], v[40:43]
	v_mfma_f32_16x16x32_bf16 v[28:31], v[144:147], v[202:205], v[28:31]
	v_mfma_f32_16x16x32_bf16 v[24:27], v[160:163], v[202:205], v[24:27]
	v_mfma_f32_16x16x32_bf16 v[12:15], v[144:147], v[214:217], v[12:15]
	v_mfma_f32_16x16x32_bf16 v[8:11], v[160:163], v[214:217], v[8:11]
	s_setprio 0
	s_setprio 1
	v_mfma_f32_16x16x32_bf16 v[52:55], v[164:167], v[180:183], 0
	v_mfma_f32_16x16x32_bf16 v[48:51], v[172:175], v[180:183], 0
	v_mfma_f32_16x16x32_bf16 v[36:39], v[164:167], v[190:193], 0
	v_mfma_f32_16x16x32_bf16 v[32:35], v[172:175], v[190:193], 0
	v_mfma_f32_16x16x32_bf16 v[20:23], v[164:167], v[198:201], 0
	v_mfma_f32_16x16x32_bf16 v[16:19], v[172:175], v[198:201], 0
	v_mfma_f32_16x16x32_bf16 v[4:7], v[164:167], v[206:209], 0
	v_mfma_f32_16x16x32_bf16 v[0:3], v[172:175], v[206:209], 0
	v_mfma_f32_16x16x32_bf16 v[52:55], v[168:171], v[184:187], v[52:55]
	v_mfma_f32_16x16x32_bf16 v[48:51], v[176:179], v[184:187], v[48:51]
	v_mfma_f32_16x16x32_bf16 v[36:39], v[168:171], v[194:197], v[36:39]
	v_mfma_f32_16x16x32_bf16 v[32:35], v[176:179], v[194:197], v[32:35]
	v_mfma_f32_16x16x32_bf16 v[20:23], v[168:171], v[202:205], v[20:23]
	v_mfma_f32_16x16x32_bf16 v[16:19], v[176:179], v[202:205], v[16:19]
	v_mfma_f32_16x16x32_bf16 v[4:7], v[168:171], v[214:217], v[4:7]
	v_mfma_f32_16x16x32_bf16 v[0:3], v[176:179], v[214:217], v[0:3]
	s_setprio 0
	s_barrier
	ds_read_b128 v[140:143], v153
	ds_read_b128 v[144:147], v153 offset:1024
	ds_read_b128 v[156:159], v153 offset:2048
	ds_read_b128 v[160:163], v153 offset:3072
	ds_read_b128 v[164:167], v154
	ds_read_b128 v[168:171], v154 offset:1024
	ds_read_b128 v[172:175], v154 offset:2048
	ds_read_b128 v[176:179], v154 offset:3072
	s_add_u32 s14, s64, 0x30000
	s_addc_u32 s15, s65, 0
	s_mov_b32 m0, s66
	v_lshl_add_u64 v[224:225], s[14:15], 0, v[134:135]
	ds_read_b128 v[180:183], v152 offset:32768
	ds_read_b128 v[184:187], v152 offset:33792
	ds_read_b128 v[190:193], v152 offset:34816
	ds_read_b128 v[194:197], v152 offset:35840
	ds_read_b128 v[198:201], v152 offset:36864
	ds_read_b128 v[202:205], v152 offset:37888
	ds_read_b128 v[206:209], v152 offset:38912
	ds_read_b128 v[214:217], v152 offset:39936
	global_load_lds_dwordx4 v[224:225], off
	v_lshl_add_u64 v[224:225], s[14:15], 0, v[130:131]
	s_mov_b32 m0, s67
	s_nop 0
	global_load_lds_dwordx4 v[224:225], off
	s_waitcnt vmcnt(8)
	s_waitcnt lgkmcnt(0)
	s_barrier
	s_setprio 1
	s_waitcnt lgkmcnt(0)
	v_mfma_f32_16x16x32_bf16 v[124:127], v[140:143], v[180:183], v[124:127]
	v_mfma_f32_16x16x32_bf16 v[120:123], v[156:159], v[180:183], v[120:123]
	v_mfma_f32_16x16x32_bf16 v[108:111], v[140:143], v[190:193], v[108:111]
	v_mfma_f32_16x16x32_bf16 v[104:107], v[156:159], v[190:193], v[104:107]
	v_mfma_f32_16x16x32_bf16 v[92:95], v[140:143], v[198:201], v[92:95]
	v_mfma_f32_16x16x32_bf16 v[88:91], v[156:159], v[198:201], v[88:91]
	v_mfma_f32_16x16x32_bf16 v[76:79], v[140:143], v[206:209], v[76:79]
	v_mfma_f32_16x16x32_bf16 v[72:75], v[156:159], v[206:209], v[72:75]
	v_mfma_f32_16x16x32_bf16 v[124:127], v[144:147], v[184:187], v[124:127]
	v_mfma_f32_16x16x32_bf16 v[120:123], v[160:163], v[184:187], v[120:123]
	v_mfma_f32_16x16x32_bf16 v[108:111], v[144:147], v[194:197], v[108:111]
	v_mfma_f32_16x16x32_bf16 v[104:107], v[160:163], v[194:197], v[104:107]
	v_mfma_f32_16x16x32_bf16 v[92:95], v[144:147], v[202:205], v[92:95]
	v_mfma_f32_16x16x32_bf16 v[88:91], v[160:163], v[202:205], v[88:91]
	v_mfma_f32_16x16x32_bf16 v[76:79], v[144:147], v[214:217], v[76:79]
	v_mfma_f32_16x16x32_bf16 v[72:75], v[160:163], v[214:217], v[72:75]
	s_setprio 0
	s_setprio 1
	v_mfma_f32_16x16x32_bf16 v[116:119], v[164:167], v[180:183], v[116:119]
	v_mfma_f32_16x16x32_bf16 v[112:115], v[172:175], v[180:183], v[112:115]
	v_mfma_f32_16x16x32_bf16 v[100:103], v[164:167], v[190:193], v[100:103]
	v_mfma_f32_16x16x32_bf16 v[96:99], v[172:175], v[190:193], v[96:99]
	v_mfma_f32_16x16x32_bf16 v[84:87], v[164:167], v[198:201], v[84:87]
	v_mfma_f32_16x16x32_bf16 v[80:83], v[172:175], v[198:201], v[80:83]
	v_mfma_f32_16x16x32_bf16 v[68:71], v[164:167], v[206:209], v[68:71]
	v_mfma_f32_16x16x32_bf16 v[64:67], v[172:175], v[206:209], v[64:67]
	v_mfma_f32_16x16x32_bf16 v[116:119], v[168:171], v[184:187], v[116:119]
	v_mfma_f32_16x16x32_bf16 v[112:115], v[176:179], v[184:187], v[112:115]
	v_mfma_f32_16x16x32_bf16 v[100:103], v[168:171], v[194:197], v[100:103]
	v_mfma_f32_16x16x32_bf16 v[96:99], v[176:179], v[194:197], v[96:99]
	v_mfma_f32_16x16x32_bf16 v[84:87], v[168:171], v[202:205], v[84:87]
	v_mfma_f32_16x16x32_bf16 v[80:83], v[176:179], v[202:205], v[80:83]
	v_mfma_f32_16x16x32_bf16 v[68:71], v[168:171], v[214:217], v[68:71]
	v_mfma_f32_16x16x32_bf16 v[64:67], v[176:179], v[214:217], v[64:67]
	s_setprio 0
	s_barrier
; #define PG8_STAGE(bufoff, gbase, voff) do { _Pragma("unroll") for (int _i = 0; _i < 2; ++_i) \
;         __builtin_amdgcn_global_load_lds((const unsigned*)((const char*)(gbase) + (voff)[_i]), (PG8_LAS unsigned*)(lds + (bufoff) + ldsw + _i * 8192), 16, 0, 0); } while (0)
; #define PG8_LDA(dst, b, h) do { _Pragma("unroll") for (int m = 0; m < 4; ++m) _Pragma("unroll") for (int k = 0; k < 2; ++k) dst[m][k] = *(const PG8_LAS bf16x8*)(lds + PG8_SA(b, h) + aoff + m * 2048 + k * 1024); } while (0)
; #define PG8_LDB(dst, b, h) do { _Pragma("unroll") for (int n = 0; n < 2; ++n) _Pragma("unroll") for (int k = 0; k < 2; ++k) dst[n][k] = *(const PG8_LAS bf16x8*)(lds + PG8_SB(b, h) + boff + n * 2048 + k * 1024); } while (0)
; #define PG8_MMA(ai, bj, At, Bt) do { __builtin_amdgcn_s_setprio(1); _Pragma("unroll") for (int m = 0; m < 4; ++m) _Pragma("unroll") for (int n = 0; n < 2; ++n) _Pragma("unroll") for (int k = 0; k < 2; ++k) \
;         acc[ai][bj][m][n] = __builtin_amdgcn_mfma_f32_16x16x32_bf16(Bt[n][k], At[m][k], acc[ai][bj][m][n], 0, 0, 0); __builtin_amdgcn_s_setprio(0); } while (0)
; #define PG8_BAR __builtin_amdgcn_s_barrier()
; template <class Epi, class Sched, bool ALIGN_EPI = false, bool SP2 = false>
; __device__ __forceinline__ void gemm_phase(PG8_LAS unsigned char* lds, const Gemm g, const Sched& S, const Epi& E) {
;     ...
;             if constexpr (SP2) {
;             PG8_LDB(B0, 0, 0); PG8_LDB(B1, 0, 1); PG8_SCHED; PG8_LDA(At, 0, 0); PG8_STAGE(PG8_SA(1, 1), a1 + hstep, voffA);
;             PG8_WAIT_V(8); PG8_WAIT_L(0); PG8_BAR; PG8_MMA(0, 0, At, B0); PG8_MMA(0, 1, At, B1); PG8_BAR; PG8_SCHED;
;             PG8_LDA(At, 0, 1); PG8_STAGE(PG8_SB(0, 0), b2, voffB); PG8_STAGE(PG8_SB(0, 1), b2 + hstep, voffB); PG8_STAGE(PG8_SA(0, 0), a2, voffA);
;             PG8_WAIT_V(8); PG8_WAIT_L(0); PG8_BAR; PG8_MMA(1, 0, At, B0); PG8_MMA(1, 1, At, B1); PG8_BAR; PG8_SCHED;
;             PG8_LDB(B0, 1, 0); PG8_LDB(B1, 1, 1); PG8_SCHED; PG8_LDA(At, 1, 0); PG8_STAGE(PG8_SA(0, 1), a2 + hstep, voffA);
;             PG8_WAIT_V(8); PG8_WAIT_L(0); PG8_BAR; PG8_MMA(0, 0, At, B0); PG8_MMA(0, 1, At, B1); PG8_BAR; PG8_SCHED;
;             PG8_LDA(At, 1, 1); PG8_STAGE(PG8_SB(1, 0), b3, voffB); PG8_STAGE(PG8_SB(1, 1), b3 + hstep, voffB); PG8_STAGE(PG8_SA(1, 0), a3, voffA);
;             PG8_WAIT_V(8); PG8_WAIT_L(0); PG8_BAR; PG8_MMA(1, 0, At, B0); PG8_MMA(1, 1, At, B1); PG8_BAR; PG8_SCHED;
	s_add_i32 s14, s75, s33
	v_lshl_add_u64 v[210:211], v[210:211], 0, s[8:9]
	s_mov_b32 m0, s14
	ds_read_b128 v[180:183], v152 offset:49152
	ds_read_b128 v[184:187], v152 offset:50176
	ds_read_b128 v[190:193], v152 offset:51200
	ds_read_b128 v[194:197], v152 offset:52224
	ds_read_b128 v[198:201], v152 offset:53248
	ds_read_b128 v[202:205], v152 offset:54272
	ds_read_b128 v[206:209], v152 offset:55296
	ds_read_b128 v[214:217], v152 offset:56320
	global_load_lds_dwordx4 v[210:211], off
	s_add_i32 m0, s14, 0x2000
	s_add_u32 s14, s46, 0x30080
	v_lshl_add_u64 v[210:211], v[218:219], 0, s[8:9]
	s_addc_u32 s15, s47, 0
	s_add_i32 s46, s84, s33
	global_load_lds_dwordx4 v[210:211], off
	v_lshl_add_u64 v[210:211], s[14:15], 0, v[132:133]
	s_mov_b32 m0, s46
	s_nop 0
	global_load_lds_dwordx4 v[210:211], off
	v_lshl_add_u64 v[210:211], s[14:15], 0, v[128:129]
	s_add_i32 m0, s46, 0x2000
	s_nop 0
	global_load_lds_dwordx4 v[210:211], off
	v_lshl_add_u64 v[210:211], v[220:221], 0, s[8:9]
	s_mov_b32 m0, s68
	s_nop 0
	global_load_lds_dwordx4 v[210:211], off
	v_lshl_add_u64 v[210:211], v[222:223], 0, s[8:9]
	s_mov_b32 m0, s69
	s_nop 0
	global_load_lds_dwordx4 v[210:211], off
	s_waitcnt vmcnt(8)
	s_waitcnt lgkmcnt(0)
	s_barrier
	s_setprio 1
	s_waitcnt lgkmcnt(0)
	v_mfma_f32_16x16x32_bf16 v[60:63], v[140:143], v[180:183], v[60:63]
	v_mfma_f32_16x16x32_bf16 v[56:59], v[156:159], v[180:183], v[56:59]
	v_mfma_f32_16x16x32_bf16 v[44:47], v[140:143], v[190:193], v[44:47]
	v_mfma_f32_16x16x32_bf16 v[40:43], v[156:159], v[190:193], v[40:43]
	v_mfma_f32_16x16x32_bf16 v[28:31], v[140:143], v[198:201], v[28:31]
	v_mfma_f32_16x16x32_bf16 v[24:27], v[156:159], v[198:201], v[24:27]
	v_mfma_f32_16x16x32_bf16 v[12:15], v[140:143], v[206:209], v[12:15]
	v_mfma_f32_16x16x32_bf16 v[8:11], v[156:159], v[206:209], v[8:11]
	v_mfma_f32_16x16x32_bf16 v[60:63], v[144:147], v[184:187], v[60:63]
	v_mfma_f32_16x16x32_bf16 v[56:59], v[160:163], v[184:187], v[56:59]
	v_mfma_f32_16x16x32_bf16 v[44:47], v[144:147], v[194:197], v[44:47]
	v_mfma_f32_16x16x32_bf16 v[40:43], v[160:163], v[194:197], v[40:43]
	v_mfma_f32_16x16x32_bf16 v[28:31], v[144:147], v[202:205], v[28:31]
	v_mfma_f32_16x16x32_bf16 v[24:27], v[160:163], v[202:205], v[24:27]
	v_mfma_f32_16x16x32_bf16 v[12:15], v[144:147], v[214:217], v[12:15]
	v_mfma_f32_16x16x32_bf16 v[8:11], v[160:163], v[214:217], v[8:11]
	s_setprio 0
	s_setprio 1
	v_mfma_f32_16x16x32_bf16 v[52:55], v[164:167], v[180:183], v[52:55]
	v_mfma_f32_16x16x32_bf16 v[48:51], v[172:175], v[180:183], v[48:51]
	v_mfma_f32_16x16x32_bf16 v[36:39], v[164:167], v[190:193], v[36:39]
	v_mfma_f32_16x16x32_bf16 v[32:35], v[172:175], v[190:193], v[32:35]
	v_mfma_f32_16x16x32_bf16 v[20:23], v[164:167], v[198:201], v[20:23]
	v_mfma_f32_16x16x32_bf16 v[16:19], v[172:175], v[198:201], v[16:19]
	v_mfma_f32_16x16x32_bf16 v[4:7], v[164:167], v[206:209], v[4:7]
	v_mfma_f32_16x16x32_bf16 v[0:3], v[172:175], v[206:209], v[0:3]
	v_mfma_f32_16x16x32_bf16 v[52:55], v[168:171], v[184:187], v[52:55]
	v_mfma_f32_16x16x32_bf16 v[48:51], v[176:179], v[184:187], v[48:51]
	v_mfma_f32_16x16x32_bf16 v[36:39], v[168:171], v[194:197], v[36:39]
	v_mfma_f32_16x16x32_bf16 v[32:35], v[176:179], v[194:197], v[32:35]
	v_mfma_f32_16x16x32_bf16 v[20:23], v[168:171], v[202:205], v[20:23]
	v_mfma_f32_16x16x32_bf16 v[16:19], v[176:179], v[202:205], v[16:19]
	v_mfma_f32_16x16x32_bf16 v[4:7], v[168:171], v[214:217], v[4:7]
	v_mfma_f32_16x16x32_bf16 v[0:3], v[176:179], v[214:217], v[0:3]
	s_setprio 0
	s_barrier
	s_add_i32 s97, s97, 2
	s_add_u32 s0, s0, 0x100
	s_addc_u32 s1, s1, 0
	s_cmp_gt_u32 s97, 9
	s_mov_b64 s[14:15], s[40:41]

;     __device__ bool next(int i, Unit& u) const { if (i >= n) return false; const int q = first + i; u.pm = rowbase + q % rows; u.pn = q / rows; return true; }
; #define PG8_WAIT_V(n) asm volatile("s_waitcnt vmcnt(" #n ")" ::: "memory")
; template <class Epi, class Sched, bool ALIGN_EPI = false, bool SP2 = false>
; __device__ __forceinline__ void gemm_phase(PG8_LAS unsigned char* lds, const Gemm g, const Sched& S, const Epi& E) {
;     ...
;         const bool has_next = S.next(ui + 1, nxt);
;         const char* nA = has_next ? (const char*)g.A + (size_t)nxt.pm * tstep : cA; const char* nB = has_next ? (const char*)g.Bt + (size_t)nxt.pn * tstep : cB;
;         constexpr int NSEG = Epi::HAS_MID ? 2 : 1; const int tseg = nt / NSEG;
; #pragma unroll
;         for (int seg = 0; seg < NSEG; ++seg) {
;         if constexpr (Epi::HAS_MID) { if (seg == 1) E.mid(acc, cur, wr, wc, fr, fq); }
;         for (int t = seg * tseg; t < (seg + 1) * tseg; t += 2) {
;             const bool last = (t == nt - 2);
;             const char* a1 = cA + (size_t)(t + 1) * kstep;
;             const char* a2 = last ? nA : cA + (size_t)(t + 2) * kstep; const char* b2 = last ? nB : cB + (size_t)(t + 2) * kstep;
;             const char* a3 = a2 + kstep; const char* b3 = b2 + kstep;
;             if (last && has_next) S.a_ready(nxt);
;             if constexpr (SP2) {
;             PG8_LDB(B0, 0, 0); PG8_LDB(B1, 0, 1); PG8_SCHED; PG8_LDA(At, 0, 0); PG8_STAGE(PG8_SA(1, 1), a1 + hstep, voffA);
;             PG8_WAIT_V(8); PG8_WAIT_L(0); PG8_BAR; PG8_MMA(0, 0, At, B0); PG8_MMA(0, 1, At, B1); PG8_BAR; PG8_SCHED;
;             PG8_LDA(At, 0, 1); PG8_STAGE(PG8_SB(0, 0), b2, voffB); PG8_STAGE(PG8_SB(0, 1), b2 + hstep, voffB); PG8_STAGE(PG8_SA(0, 0), a2, voffA);
;             PG8_WAIT_V(8); PG8_WAIT_L(0); PG8_BAR; PG8_MMA(1, 0, At, B0); PG8_MMA(1, 1, At, B1); PG8_BAR; PG8_SCHED;
;             PG8_LDB(B0, 1, 0); PG8_LDB(B1, 1, 1); PG8_SCHED; PG8_LDA(At, 1, 0); PG8_STAGE(PG8_SA(0, 1), a2 + hstep, voffA);
;             PG8_WAIT_V(8); PG8_WAIT_L(0); PG8_BAR; PG8_MMA(0, 0, At, B0); PG8_MMA(0, 1, At, B1); PG8_BAR; PG8_SCHED;
;             PG8_LDA(At, 1, 1); PG8_STAGE(PG8_SB(1, 0), b3, voffB); PG8_STAGE(PG8_SB(1, 1), b3 + hstep, voffB); PG8_STAGE(PG8_SA(1, 0), a3, voffA);
;             PG8_WAIT_V(8); PG8_WAIT_L(0); PG8_BAR; PG8_MMA(1, 0, At, B0); PG8_MMA(1, 1, At, B1); PG8_BAR; PG8_SCHED;
.LBB0_534:
	s_ashr_i32 s41, s40, 31
	s_lshl_b64 s[46:47], s[40:41], 18
	s_add_u32 s46, s72, s46
	s_addc_u32 s47, s73, s47
	s_and_b64 s[60:61], s[0:1], exec
	s_cselect_b32 s41, s47, s63
	s_cselect_b32 s76, s46, s62
	s_ashr_i32 s37, s36, 31
	s_lshl_b64 s[60:61], s[36:37], 18
	s_add_u32 s60, s58, s60
	s_addc_u32 s61, s59, s61
	s_and_b64 s[0:1], s[0:1], exec
	s_cselect_b32 s0, s61, s65
	s_cselect_b32 s1, s60, s64
	s_add_u32 s62, s62, 0x20080
	s_addc_u32 s63, s63, 0
	s_add_u32 s37, s64, 0x100
	s_addc_u32 s77, s65, 0
	s_mov_b32 s78, -2
	ds_read_b128 v[140:143], v149
	ds_read_b128 v[152:155], v149 offset:1024
	ds_read_b128 v[156:159], v149 offset:2048
	ds_read_b128 v[160:163], v149 offset:3072
	ds_read_b128 v[164:167], v150
	ds_read_b128 v[168:171], v150 offset:1024
	ds_read_b128 v[172:175], v150 offset:2048
	ds_read_b128 v[176:179], v150 offset:3072
	s_add_u32 s64, s62, 0xfffe0080
	s_addc_u32 s65, s63, -1
	s_cmp_eq_u32 s78, 4
	s_cselect_b32 s67, s41, s65
	s_cselect_b32 s66, s76, s64
	s_cselect_b32 s65, s0, s77
	s_cselect_b32 s64, s1, s37
	v_lshl_add_u64 v[144:145], s[62:63], 0, v[136:137]
	s_add_i32 m0, s30, 0xc000
	ds_read_b128 v[180:183], v151
	ds_read_b128 v[184:187], v151 offset:1024
	ds_read_b128 v[190:193], v151 offset:2048
	ds_read_b128 v[194:197], v151 offset:3072
	ds_read_b128 v[198:201], v151 offset:4096
	ds_read_b128 v[202:205], v151 offset:5120
	ds_read_b128 v[206:209], v151 offset:6144
	ds_read_b128 v[214:217], v151 offset:7168
	global_load_lds_dwordx4 v[144:145], off
	v_lshl_add_u64 v[144:145], s[62:63], 0, v[138:139]
	s_add_i32 m0, s30, 0xe000
	s_nop 0
	global_load_lds_dwordx4 v[144:145], off
	s_waitcnt vmcnt(8)
	s_waitcnt lgkmcnt(0)
	s_barrier
	s_setprio 1
	s_waitcnt lgkmcnt(0)
	v_mfma_f32_16x16x32_bf16 v[124:127], v[140:143], v[180:183], 0
	v_mfma_f32_16x16x32_bf16 v[120:123], v[156:159], v[180:183], 0
	v_mfma_f32_16x16x32_bf16 v[108:111], v[140:143], v[190:193], 0
	v_mfma_f32_16x16x32_bf16 v[104:107], v[156:159], v[190:193], 0
	v_mfma_f32_16x16x32_bf16 v[92:95], v[140:143], v[198:201], 0
	v_mfma_f32_16x16x32_bf16 v[88:91], v[156:159], v[198:201], 0
	v_mfma_f32_16x16x32_bf16 v[76:79], v[140:143], v[206:209], 0
	v_mfma_f32_16x16x32_bf16 v[72:75], v[156:159], v[206:209], 0
	v_mfma_f32_16x16x32_bf16 v[124:127], v[152:155], v[184:187], v[124:127]
	v_mfma_f32_16x16x32_bf16 v[120:123], v[160:163], v[184:187], v[120:123]
	v_mfma_f32_16x16x32_bf16 v[108:111], v[152:155], v[194:197], v[108:111]
	v_mfma_f32_16x16x32_bf16 v[104:107], v[160:163], v[194:197], v[104:107]
	v_mfma_f32_16x16x32_bf16 v[92:95], v[152:155], v[202:205], v[92:95]
	v_mfma_f32_16x16x32_bf16 v[88:91], v[160:163], v[202:205], v[88:91]
	v_mfma_f32_16x16x32_bf16 v[76:79], v[152:155], v[214:217], v[76:79]
	v_mfma_f32_16x16x32_bf16 v[72:75], v[160:163], v[214:217], v[72:75]
	s_setprio 0
	s_setprio 1
	v_mfma_f32_16x16x32_bf16 v[116:119], v[164:167], v[180:183], 0
	v_mfma_f32_16x16x32_bf16 v[112:115], v[172:175], v[180:183], 0
	v_mfma_f32_16x16x32_bf16 v[100:103], v[164:167], v[190:193], 0
	v_mfma_f32_16x16x32_bf16 v[96:99], v[172:175], v[190:193], 0
	v_mfma_f32_16x16x32_bf16 v[84:87], v[164:167], v[198:201], 0
	v_mfma_f32_16x16x32_bf16 v[80:83], v[172:175], v[198:201], 0
	v_mfma_f32_16x16x32_bf16 v[68:71], v[164:167], v[206:209], 0
	v_mfma_f32_16x16x32_bf16 v[64:67], v[172:175], v[206:209], 0
	v_mfma_f32_16x16x32_bf16 v[116:119], v[168:171], v[184:187], v[116:119]
	v_mfma_f32_16x16x32_bf16 v[112:115], v[176:179], v[184:187], v[112:115]
	v_mfma_f32_16x16x32_bf16 v[100:103], v[168:171], v[194:197], v[100:103]
	v_mfma_f32_16x16x32_bf16 v[96:99], v[176:179], v[194:197], v[96:99]
	v_mfma_f32_16x16x32_bf16 v[84:87], v[168:171], v[202:205], v[84:87]
	v_mfma_f32_16x16x32_bf16 v[80:83], v[176:179], v[202:205], v[80:83]
	v_mfma_f32_16x16x32_bf16 v[68:71], v[168:171], v[214:217], v[68:71]
	v_mfma_f32_16x16x32_bf16 v[64:67], v[176:179], v[214:217], v[64:67]
	s_setprio 0
	s_barrier
	s_add_i32 s79, s31, s29
	v_lshl_add_u64 v[144:145], s[64:65], 0, v[132:133]
	s_mov_b32 m0, s79
	ds_read_b128 v[180:183], v151 offset:16384
	ds_read_b128 v[184:187], v151 offset:17408
	ds_read_b128 v[190:193], v151 offset:18432
	ds_read_b128 v[194:197], v151 offset:19456
	ds_read_b128 v[198:201], v151 offset:20480
	ds_read_b128 v[202:205], v151 offset:21504
	ds_read_b128 v[206:209], v151 offset:22528
	ds_read_b128 v[214:217], v151 offset:23552
	global_load_lds_dwordx4 v[144:145], off
	s_add_i32 m0, s79, 0x2000
	s_add_u32 s80, s64, 0x20000
	v_lshl_add_u64 v[210:211], s[64:65], 0, v[128:129]
	s_addc_u32 s81, s65, 0
	s_add_i32 s79, s74, s29
	global_load_lds_dwordx4 v[210:211], off
	v_lshl_add_u64 v[218:219], s[80:81], 0, v[132:133]
	s_mov_b32 m0, s79
	v_lshl_add_u64 v[220:221], s[66:67], 0, v[130:131]
	global_load_lds_dwordx4 v[218:219], off
	v_lshl_add_u64 v[218:219], s[80:81], 0, v[128:129]
	s_add_i32 m0, s79, 0x2000
	s_nop 0
	global_load_lds_dwordx4 v[218:219], off
	v_lshl_add_u64 v[218:219], s[66:67], 0, v[134:135]
	s_mov_b32 m0, s30
	s_nop 0
	global_load_lds_dwordx4 v[218:219], off
	s_mov_b32 m0, s33
	s_nop 0
	global_load_lds_dwordx4 v[220:221], off
	s_waitcnt vmcnt(8)
	s_waitcnt lgkmcnt(0)
	s_barrier
; #define PG8_STAGE(bufoff, gbase, voff) do { _Pragma("unroll") for (int _i = 0; _i < 2; ++_i) \
;         __builtin_amdgcn_global_load_lds((const unsigned*)((const char*)(gbase) + (voff)[_i]), (PG8_LAS unsigned*)(lds + (bufoff) + ldsw + _i * 8192), 16, 0, 0); } while (0)
; #define PG8_LDA(dst, b, h) do { _Pragma("unroll") for (int m = 0; m < 4; ++m) _Pragma("unroll") for (int k = 0; k < 2; ++k) dst[m][k] = *(const PG8_LAS bf16x8*)(lds + PG8_SA(b, h) + aoff + m * 2048 + k * 1024); } while (0)
; #define PG8_LDB(dst, b, h) do { _Pragma("unroll") for (int n = 0; n < 2; ++n) _Pragma("unroll") for (int k = 0; k < 2; ++k) dst[n][k] = *(const PG8_LAS bf16x8*)(lds + PG8_SB(b, h) + boff + n * 2048 + k * 1024); } while (0)
; #define PG8_MMA(ai, bj, At, Bt) do { __builtin_amdgcn_s_setprio(1); _Pragma("unroll") for (int m = 0; m < 4; ++m) _Pragma("unroll") for (int n = 0; n < 2; ++n) _Pragma("unroll") for (int k = 0; k < 2; ++k) \
;         acc[ai][bj][m][n] = __builtin_amdgcn_mfma_f32_16x16x32_bf16(Bt[n][k], At[m][k], acc[ai][bj][m][n], 0, 0, 0); __builtin_amdgcn_s_setprio(0); } while (0)
; #define PG8_BAR __builtin_amdgcn_s_barrier()
; template <class Epi, class Sched, bool ALIGN_EPI = false, bool SP2 = false>
; __device__ __forceinline__ void gemm_phase(PG8_LAS unsigned char* lds, const Gemm g, const Sched& S, const Epi& E) {
;     ...
;             if constexpr (SP2) {
;             PG8_LDB(B0, 0, 0); PG8_LDB(B1, 0, 1); PG8_SCHED; PG8_LDA(At, 0, 0); PG8_STAGE(PG8_SA(1, 1), a1 + hstep, voffA);
;             PG8_WAIT_V(8); PG8_WAIT_L(0); PG8_BAR; PG8_MMA(0, 0, At, B0); PG8_MMA(0, 1, At, B1); PG8_BAR; PG8_SCHED;
;             PG8_LDA(At, 0, 1); PG8_STAGE(PG8_SB(0, 0), b2, voffB); PG8_STAGE(PG8_SB(0, 1), b2 + hstep, voffB); PG8_STAGE(PG8_SA(0, 0), a2, voffA);
;             PG8_WAIT_V(8); PG8_WAIT_L(0); PG8_BAR; PG8_MMA(1, 0, At, B0); PG8_MMA(1, 1, At, B1); PG8_BAR; PG8_SCHED;
;             PG8_LDB(B0, 1, 0); PG8_LDB(B1, 1, 1); PG8_SCHED; PG8_LDA(At, 1, 0); PG8_STAGE(PG8_SA(0, 1), a2 + hstep, voffA);
;             PG8_WAIT_V(8); PG8_WAIT_L(0); PG8_BAR; PG8_MMA(0, 0, At, B0); PG8_MMA(0, 1, At, B1); PG8_BAR; PG8_SCHED;
;             PG8_LDA(At, 1, 1); PG8_STAGE(PG8_SB(1, 0), b3, voffB); PG8_STAGE(PG8_SB(1, 1), b3 + hstep, voffB); PG8_STAGE(PG8_SA(1, 0), a3, voffA);
;             PG8_WAIT_V(8); PG8_WAIT_L(0); PG8_BAR; PG8_MMA(1, 0, At, B0); PG8_MMA(1, 1, At, B1); PG8_BAR; PG8_SCHED;
	s_setprio 1
	s_waitcnt lgkmcnt(0)
	v_mfma_f32_16x16x32_bf16 v[60:63], v[140:143], v[180:183], 0
	v_mfma_f32_16x16x32_bf16 v[56:59], v[156:159], v[180:183], 0
	v_mfma_f32_16x16x32_bf16 v[44:47], v[140:143], v[190:193], 0
	v_mfma_f32_16x16x32_bf16 v[40:43], v[156:159], v[190:193], 0
	v_mfma_f32_16x16x32_bf16 v[28:31], v[140:143], v[198:201], 0
	v_mfma_f32_16x16x32_bf16 v[24:27], v[156:159], v[198:201], 0
	v_mfma_f32_16x16x32_bf16 v[12:15], v[140:143], v[206:209], 0
	v_mfma_f32_16x16x32_bf16 v[8:11], v[156:159], v[206:209], 0
	v_mfma_f32_16x16x32_bf16 v[60:63], v[152:155], v[184:187], v[60:63]
	v_mfma_f32_16x16x32_bf16 v[56:59], v[160:163], v[184:187], v[56:59]
	v_mfma_f32_16x16x32_bf16 v[44:47], v[152:155], v[194:197], v[44:47]
	v_mfma_f32_16x16x32_bf16 v[40:43], v[160:163], v[194:197], v[40:43]
	v_mfma_f32_16x16x32_bf16 v[28:31], v[152:155], v[202:205], v[28:31]
	v_mfma_f32_16x16x32_bf16 v[24:27], v[160:163], v[202:205], v[24:27]
	v_mfma_f32_16x16x32_bf16 v[12:15], v[152:155], v[214:217], v[12:15]
	v_mfma_f32_16x16x32_bf16 v[8:11], v[160:163], v[214:217], v[8:11]
	s_setprio 0
	s_setprio 1
	v_mfma_f32_16x16x32_bf16 v[52:55], v[164:167], v[180:183], 0
	v_mfma_f32_16x16x32_bf16 v[48:51], v[172:175], v[180:183], 0
	v_mfma_f32_16x16x32_bf16 v[36:39], v[164:167], v[190:193], 0
	v_mfma_f32_16x16x32_bf16 v[32:35], v[172:175], v[190:193], 0
	v_mfma_f32_16x16x32_bf16 v[20:23], v[164:167], v[198:201], 0
	v_mfma_f32_16x16x32_bf16 v[16:19], v[172:175], v[198:201], 0
	v_mfma_f32_16x16x32_bf16 v[4:7], v[164:167], v[206:209], 0
	v_mfma_f32_16x16x32_bf16 v[0:3], v[172:175], v[206:209], 0
	v_mfma_f32_16x16x32_bf16 v[52:55], v[168:171], v[184:187], v[52:55]
	v_mfma_f32_16x16x32_bf16 v[48:51], v[176:179], v[184:187], v[48:51]
	v_mfma_f32_16x16x32_bf16 v[36:39], v[168:171], v[194:197], v[36:39]
	v_mfma_f32_16x16x32_bf16 v[32:35], v[176:179], v[194:197], v[32:35]
	v_mfma_f32_16x16x32_bf16 v[20:23], v[168:171], v[202:205], v[20:23]
	v_mfma_f32_16x16x32_bf16 v[16:19], v[176:179], v[202:205], v[16:19]
	v_mfma_f32_16x16x32_bf16 v[4:7], v[168:171], v[214:217], v[4:7]
	v_mfma_f32_16x16x32_bf16 v[0:3], v[176:179], v[214:217], v[0:3]
	s_setprio 0
	s_barrier
	v_add_u32_e32 v160, s75, v147
	v_add_u32_e32 v176, s84, v147
	ds_read_b128 v[140:143], v160
	ds_read_b128 v[152:155], v160 offset:1024
	ds_read_b128 v[156:159], v160 offset:2048
	ds_read_b128 v[160:163], v160 offset:3072
	ds_read_b128 v[164:167], v176
	ds_read_b128 v[168:171], v176 offset:1024
	ds_read_b128 v[172:175], v176 offset:2048
	ds_read_b128 v[176:179], v176 offset:3072
	s_add_u32 s66, s66, 0x20000
	s_addc_u32 s67, s67, 0
	s_mov_b32 m0, s56
	v_lshl_add_u64 v[222:223], s[66:67], 0, v[134:135]
	ds_read_b128 v[180:183], v151 offset:32768
	ds_read_b128 v[184:187], v151 offset:33792
	ds_read_b128 v[190:193], v151 offset:34816
	ds_read_b128 v[194:197], v151 offset:35840
	ds_read_b128 v[198:201], v151 offset:36864
	ds_read_b128 v[202:205], v151 offset:37888
	ds_read_b128 v[206:209], v151 offset:38912
	ds_read_b128 v[214:217], v151 offset:39936
	global_load_lds_dwordx4 v[222:223], off
	v_lshl_add_u64 v[222:223], s[66:67], 0, v[130:131]
	s_mov_b32 m0, s57
	s_nop 0
	global_load_lds_dwordx4 v[222:223], off
	s_waitcnt vmcnt(8)
	s_waitcnt lgkmcnt(0)
	s_barrier
	s_setprio 1
	s_waitcnt lgkmcnt(0)
	v_mfma_f32_16x16x32_bf16 v[124:127], v[140:143], v[180:183], v[124:127]
	v_mfma_f32_16x16x32_bf16 v[120:123], v[156:159], v[180:183], v[120:123]
	v_mfma_f32_16x16x32_bf16 v[108:111], v[140:143], v[190:193], v[108:111]
	v_mfma_f32_16x16x32_bf16 v[104:107], v[156:159], v[190:193], v[104:107]
	v_mfma_f32_16x16x32_bf16 v[92:95], v[140:143], v[198:201], v[92:95]
	v_mfma_f32_16x16x32_bf16 v[88:91], v[156:159], v[198:201], v[88:91]
	v_mfma_f32_16x16x32_bf16 v[76:79], v[140:143], v[206:209], v[76:79]
	v_mfma_f32_16x16x32_bf16 v[72:75], v[156:159], v[206:209], v[72:75]
	v_mfma_f32_16x16x32_bf16 v[124:127], v[152:155], v[184:187], v[124:127]
	v_mfma_f32_16x16x32_bf16 v[120:123], v[160:163], v[184:187], v[120:123]
	v_mfma_f32_16x16x32_bf16 v[108:111], v[152:155], v[194:197], v[108:111]
	v_mfma_f32_16x16x32_bf16 v[104:107], v[160:163], v[194:197], v[104:107]
	v_mfma_f32_16x16x32_bf16 v[92:95], v[152:155], v[202:205], v[92:95]
	v_mfma_f32_16x16x32_bf16 v[88:91], v[160:163], v[202:205], v[88:91]
	v_mfma_f32_16x16x32_bf16 v[76:79], v[152:155], v[214:217], v[76:79]
	v_mfma_f32_16x16x32_bf16 v[72:75], v[160:163], v[214:217], v[72:75]
	s_setprio 0
	s_setprio 1
	v_mfma_f32_16x16x32_bf16 v[116:119], v[164:167], v[180:183], v[116:119]
	v_mfma_f32_16x16x32_bf16 v[112:115], v[172:175], v[180:183], v[112:115]
	v_mfma_f32_16x16x32_bf16 v[100:103], v[164:167], v[190:193], v[100:103]
	v_mfma_f32_16x16x32_bf16 v[96:99], v[172:175], v[190:193], v[96:99]
	v_mfma_f32_16x16x32_bf16 v[84:87], v[164:167], v[198:201], v[84:87]
	v_mfma_f32_16x16x32_bf16 v[80:83], v[172:175], v[198:201], v[80:83]
	v_mfma_f32_16x16x32_bf16 v[68:71], v[164:167], v[206:209], v[68:71]
	v_mfma_f32_16x16x32_bf16 v[64:67], v[172:175], v[206:209], v[64:67]
	v_mfma_f32_16x16x32_bf16 v[116:119], v[168:171], v[184:187], v[116:119]
	v_mfma_f32_16x16x32_bf16 v[112:115], v[176:179], v[184:187], v[112:115]
	v_mfma_f32_16x16x32_bf16 v[100:103], v[168:171], v[194:197], v[100:103]
	v_mfma_f32_16x16x32_bf16 v[96:99], v[176:179], v[194:197], v[96:99]
	v_mfma_f32_16x16x32_bf16 v[84:87], v[168:171], v[202:205], v[84:87]
	v_mfma_f32_16x16x32_bf16 v[80:83], v[176:179], v[202:205], v[80:83]
	v_mfma_f32_16x16x32_bf16 v[68:71], v[168:171], v[214:217], v[68:71]
	v_mfma_f32_16x16x32_bf16 v[64:67], v[176:179], v[214:217], v[64:67]
	s_setprio 0
	s_barrier
; #define PG8_STAGE(bufoff, gbase, voff) do { _Pragma("unroll") for (int _i = 0; _i < 2; ++_i) \
;         __builtin_amdgcn_global_load_lds((const unsigned*)((const char*)(gbase) + (voff)[_i]), (PG8_LAS unsigned*)(lds + (bufoff) + ldsw + _i * 8192), 16, 0, 0); } while (0)
; #define PG8_LDA(dst, b, h) do { _Pragma("unroll") for (int m = 0; m < 4; ++m) _Pragma("unroll") for (int k = 0; k < 2; ++k) dst[m][k] = *(const PG8_LAS bf16x8*)(lds + PG8_SA(b, h) + aoff + m * 2048 + k * 1024); } while (0)
; #define PG8_LDB(dst, b, h) do { _Pragma("unroll") for (int n = 0; n < 2; ++n) _Pragma("unroll") for (int k = 0; k < 2; ++k) dst[n][k] = *(const PG8_LAS bf16x8*)(lds + PG8_SB(b, h) + boff + n * 2048 + k * 1024); } while (0)
; #define PG8_MMA(ai, bj, At, Bt) do { __builtin_amdgcn_s_setprio(1); _Pragma("unroll") for (int m = 0; m < 4; ++m) _Pragma("unroll") for (int n = 0; n < 2; ++n) _Pragma("unroll") for (int k = 0; k < 2; ++k) \
;         acc[ai][bj][m][n] = __builtin_amdgcn_mfma_f32_16x16x32_bf16(Bt[n][k], At[m][k], acc[ai][bj][m][n], 0, 0, 0); __builtin_amdgcn_s_setprio(0); } while (0)
; #define PG8_BAR __builtin_amdgcn_s_barrier()
; template <class Epi, class Sched, bool ALIGN_EPI = false, bool SP2 = false>
; __device__ __forceinline__ void gemm_phase(PG8_LAS unsigned char* lds, const Gemm g, const Sched& S, const Epi& E) {
;     ...
;             if constexpr (SP2) {
;             PG8_LDB(B0, 0, 0); PG8_LDB(B1, 0, 1); PG8_SCHED; PG8_LDA(At, 0, 0); PG8_STAGE(PG8_SA(1, 1), a1 + hstep, voffA);
;             PG8_WAIT_V(8); PG8_WAIT_L(0); PG8_BAR; PG8_MMA(0, 0, At, B0); PG8_MMA(0, 1, At, B1); PG8_BAR; PG8_SCHED;
;             PG8_LDA(At, 0, 1); PG8_STAGE(PG8_SB(0, 0), b2, voffB); PG8_STAGE(PG8_SB(0, 1), b2 + hstep, voffB); PG8_STAGE(PG8_SA(0, 0), a2, voffA);
;             PG8_WAIT_V(8); PG8_WAIT_L(0); PG8_BAR; PG8_MMA(1, 0, At, B0); PG8_MMA(1, 1, At, B1); PG8_BAR; PG8_SCHED;
;             PG8_LDB(B0, 1, 0); PG8_LDB(B1, 1, 1); PG8_SCHED; PG8_LDA(At, 1, 0); PG8_STAGE(PG8_SA(0, 1), a2 + hstep, voffA);
;             PG8_WAIT_V(8); PG8_WAIT_L(0); PG8_BAR; PG8_MMA(0, 0, At, B0); PG8_MMA(0, 1, At, B1); PG8_BAR; PG8_SCHED;
;             PG8_LDA(At, 1, 1); PG8_STAGE(PG8_SB(1, 0), b3, voffB); PG8_STAGE(PG8_SB(1, 1), b3 + hstep, voffB); PG8_STAGE(PG8_SA(1, 0), a3, voffA);
;             PG8_WAIT_V(8); PG8_WAIT_L(0); PG8_BAR; PG8_MMA(1, 0, At, B0); PG8_MMA(1, 1, At, B1); PG8_BAR; PG8_SCHED;
	s_add_i32 s66, s75, s29
	v_lshl_add_u64 v[144:145], v[144:145], 0, s[12:13]
	s_mov_b32 m0, s66
	ds_read_b128 v[180:183], v151 offset:49152
	ds_read_b128 v[184:187], v151 offset:50176
	ds_read_b128 v[190:193], v151 offset:51200
	ds_read_b128 v[194:197], v151 offset:52224
	ds_read_b128 v[198:201], v151 offset:53248
	ds_read_b128 v[202:205], v151 offset:54272
	ds_read_b128 v[206:209], v151 offset:55296
	ds_read_b128 v[214:217], v151 offset:56320
	global_load_lds_dwordx4 v[144:145], off
	s_add_i32 m0, s66, 0x2000
	s_add_u32 s64, s64, 0x20080
	v_lshl_add_u64 v[144:145], v[210:211], 0, s[12:13]
	s_addc_u32 s65, s65, 0
	s_add_i32 s66, s84, s29
	global_load_lds_dwordx4 v[144:145], off
	v_lshl_add_u64 v[144:145], s[64:65], 0, v[132:133]
	s_mov_b32 m0, s66
	s_nop 0
	global_load_lds_dwordx4 v[144:145], off
	v_lshl_add_u64 v[144:145], s[64:65], 0, v[128:129]
	s_add_i32 m0, s66, 0x2000
	s_nop 0
	global_load_lds_dwordx4 v[144:145], off
	v_lshl_add_u64 v[144:145], v[218:219], 0, s[12:13]
	s_mov_b32 m0, s68
	s_nop 0
	global_load_lds_dwordx4 v[144:145], off
	v_lshl_add_u64 v[144:145], v[220:221], 0, s[12:13]
	s_mov_b32 m0, s69
	s_nop 0
	global_load_lds_dwordx4 v[144:145], off
	s_waitcnt vmcnt(8)
	s_waitcnt lgkmcnt(0)
	s_barrier
	s_setprio 1
	s_waitcnt lgkmcnt(0)
	v_mfma_f32_16x16x32_bf16 v[60:63], v[140:143], v[180:183], v[60:63]
	v_mfma_f32_16x16x32_bf16 v[56:59], v[156:159], v[180:183], v[56:59]
	v_mfma_f32_16x16x32_bf16 v[44:47], v[140:143], v[190:193], v[44:47]
	v_mfma_f32_16x16x32_bf16 v[40:43], v[156:159], v[190:193], v[40:43]
	v_mfma_f32_16x16x32_bf16 v[28:31], v[140:143], v[198:201], v[28:31]
	v_mfma_f32_16x16x32_bf16 v[24:27], v[156:159], v[198:201], v[24:27]
	v_mfma_f32_16x16x32_bf16 v[12:15], v[140:143], v[206:209], v[12:15]
	v_mfma_f32_16x16x32_bf16 v[8:11], v[156:159], v[206:209], v[8:11]
	v_mfma_f32_16x16x32_bf16 v[60:63], v[152:155], v[184:187], v[60:63]
	v_mfma_f32_16x16x32_bf16 v[56:59], v[160:163], v[184:187], v[56:59]
	v_mfma_f32_16x16x32_bf16 v[44:47], v[152:155], v[194:197], v[44:47]
	v_mfma_f32_16x16x32_bf16 v[40:43], v[160:163], v[194:197], v[40:43]
	v_mfma_f32_16x16x32_bf16 v[28:31], v[152:155], v[202:205], v[28:31]
	v_mfma_f32_16x16x32_bf16 v[24:27], v[160:163], v[202:205], v[24:27]
	v_mfma_f32_16x16x32_bf16 v[12:15], v[152:155], v[214:217], v[12:15]
	v_mfma_f32_16x16x32_bf16 v[8:11], v[160:163], v[214:217], v[8:11]
	s_setprio 0
	s_setprio 1
	v_mfma_f32_16x16x32_bf16 v[52:55], v[164:167], v[180:183], v[52:55]
	v_mfma_f32_16x16x32_bf16 v[48:51], v[172:175], v[180:183], v[48:51]
	v_mfma_f32_16x16x32_bf16 v[36:39], v[164:167], v[190:193], v[36:39]
	v_mfma_f32_16x16x32_bf16 v[32:35], v[172:175], v[190:193], v[32:35]
	v_mfma_f32_16x16x32_bf16 v[20:23], v[164:167], v[198:201], v[20:23]
	v_mfma_f32_16x16x32_bf16 v[16:19], v[172:175], v[198:201], v[16:19]
	v_mfma_f32_16x16x32_bf16 v[4:7], v[164:167], v[206:209], v[4:7]
	v_mfma_f32_16x16x32_bf16 v[0:3], v[172:175], v[206:209], v[0:3]
	v_mfma_f32_16x16x32_bf16 v[52:55], v[168:171], v[184:187], v[52:55]
	v_mfma_f32_16x16x32_bf16 v[48:51], v[176:179], v[184:187], v[48:51]
	v_mfma_f32_16x16x32_bf16 v[36:39], v[168:171], v[194:197], v[36:39]
	v_mfma_f32_16x16x32_bf16 v[32:35], v[176:179], v[194:197], v[32:35]
	v_mfma_f32_16x16x32_bf16 v[20:23], v[168:171], v[202:205], v[20:23]
	v_mfma_f32_16x16x32_bf16 v[16:19], v[176:179], v[202:205], v[16:19]
	v_mfma_f32_16x16x32_bf16 v[4:7], v[168:171], v[214:217], v[4:7]
	v_mfma_f32_16x16x32_bf16 v[0:3], v[176:179], v[214:217], v[0:3]
	s_setprio 0
	s_barrier
	s_add_i32 s78, s78, 2
	s_add_u32 s62, s62, 0x100
	s_addc_u32 s63, s63, 0
	s_add_u32 s37, s37, 0x100
	s_addc_u32 s77, s77, 0
	s_cmp_gt_u32 s78, 5

; #define PG8_STAGE(bufoff, gbase, voff) do { _Pragma("unroll") for (int _i = 0; _i < 2; ++_i) \
;         __builtin_amdgcn_global_load_lds((const unsigned*)((const char*)(gbase) + (voff)[_i]), (PG8_LAS unsigned*)(lds + (bufoff) + ldsw + _i * 8192), 16, 0, 0); } while (0)
; #define PG8_LDA(dst, b, h) do { _Pragma("unroll") for (int m = 0; m < 4; ++m) _Pragma("unroll") for (int k = 0; k < 2; ++k) dst[m][k] = *(const PG8_LAS bf16x8*)(lds + PG8_SA(b, h) + aoff + m * 2048 + k * 1024); } while (0)
; #define PG8_LDB(dst, b, h) do { _Pragma("unroll") for (int n = 0; n < 2; ++n) _Pragma("unroll") for (int k = 0; k < 2; ++k) dst[n][k] = *(const PG8_LAS bf16x8*)(lds + PG8_SB(b, h) + boff + n * 2048 + k * 1024); } while (0)
; #define PG8_WAIT_V(n) asm volatile("s_waitcnt vmcnt(" #n ")" ::: "memory")
; #define PG8_WAIT_L(n) asm volatile("s_waitcnt lgkmcnt(" #n ")" ::: "memory")
; #define PG8_BAR __builtin_amdgcn_s_barrier()
; #define PG8_SCHED __builtin_amdgcn_sched_barrier(0)
; template <class Epi, class Sched, bool ALIGN_EPI = false, bool SP2 = false>
; __device__ __forceinline__ void gemm_phase(PG8_LAS unsigned char* lds, const Gemm g, const Sched& S, const Epi& E) {
;     ...
;         for (int seg = 0; seg < NSEG; ++seg) {
;         if constexpr (Epi::HAS_MID) { if (seg == 1) E.mid(acc, cur, wr, wc, fr, fq); }
;         for (int t = seg * tseg; t < (seg + 1) * tseg; t += 2) {
;             const bool last = (t == nt - 2);
;             const char* a1 = cA + (size_t)(t + 1) * kstep;
;             const char* a2 = last ? nA : cA + (size_t)(t + 2) * kstep; const char* b2 = last ? nB : cB + (size_t)(t + 2) * kstep;
;             const char* a3 = a2 + kstep; const char* b3 = b2 + kstep;
;             if (last && has_next) S.a_ready(nxt);
;             if constexpr (SP2) {
;             PG8_LDB(B0, 0, 0); PG8_LDB(B1, 0, 1); PG8_SCHED; PG8_LDA(At, 0, 0); PG8_STAGE(PG8_SA(1, 1), a1 + hstep, voffA);
;             PG8_WAIT_V(8); PG8_WAIT_L(0); PG8_BAR; PG8_MMA(0, 0, At, B0); PG8_MMA(0, 1, At, B1); PG8_BAR; PG8_SCHED;
;             PG8_LDA(At, 0, 1); PG8_STAGE(PG8_SB(0, 0), b2, voffB); PG8_STAGE(PG8_SB(0, 1), b2 + hstep, voffB); PG8_STAGE(PG8_SA(0, 0), a2, voffA);
;             PG8_WAIT_V(8); PG8_WAIT_L(0); PG8_BAR; PG8_MMA(1, 0, At, B0); PG8_MMA(1, 1, At, B1); PG8_BAR; PG8_SCHED;
.LBB0_702:
	v_lshl_add_u64 v[148:149], s[62:63], 0, v[136:137]
	v_lshl_add_u64 v[150:151], s[62:63], 0, v[138:139]
	v_lshl_add_u64 v[152:153], s[60:61], 0, v[140:141]
	v_lshl_add_u64 v[154:155], s[60:61], 0, v[142:143]
	s_mov_b32 s59, -2
	s_mov_b64 s[64:65], 0
	ds_read_b128 v[162:165], v159
	ds_read_b128 v[166:169], v159 offset:1024
	ds_read_b128 v[170:173], v159 offset:2048
	ds_read_b128 v[174:177], v159 offset:3072
	ds_read_b128 v[178:181], v160
	ds_read_b128 v[182:185], v160 offset:1024
	ds_read_b128 v[190:193], v160 offset:2048
	ds_read_b128 v[194:197], v160 offset:3072
	v_lshl_add_u64 v[210:211], v[148:149], 0, s[64:65]
	s_mov_b32 m0, s77
	v_lshl_add_u64 v[186:187], v[210:211], 0, s[10:11]
	v_lshl_add_u64 v[234:235], v[150:151], 0, s[64:65]
	ds_read_b128 v[198:201], v161
	ds_read_b128 v[202:205], v161 offset:1024
	ds_read_b128 v[206:209], v161 offset:2048
	ds_read_b128 v[214:217], v161 offset:3072
	ds_read_b128 v[218:221], v161 offset:4096
	ds_read_b128 v[222:225], v161 offset:5120
	ds_read_b128 v[226:229], v161 offset:6144
	ds_read_b128 v[230:233], v161 offset:7168
	global_load_lds_dwordx4 v[186:187], off
	v_lshl_add_u64 v[186:187], v[234:235], 0, s[10:11]
	s_mov_b32 m0, s78
	s_nop 0
	global_load_lds_dwordx4 v[186:187], off
	s_waitcnt vmcnt(8)
	s_waitcnt lgkmcnt(0)
	s_barrier
	s_setprio 1
	s_waitcnt lgkmcnt(0)
	v_mfma_f32_16x16x32_bf16 v[124:127], v[162:165], v[198:201], 0
	v_mfma_f32_16x16x32_bf16 v[120:123], v[170:173], v[198:201], 0
	v_mfma_f32_16x16x32_bf16 v[116:119], v[162:165], v[206:209], 0
	v_mfma_f32_16x16x32_bf16 v[112:115], v[170:173], v[206:209], 0
	v_mfma_f32_16x16x32_bf16 v[108:111], v[162:165], v[218:221], 0
	v_mfma_f32_16x16x32_bf16 v[104:107], v[170:173], v[218:221], 0
	v_mfma_f32_16x16x32_bf16 v[100:103], v[162:165], v[226:229], 0
	v_mfma_f32_16x16x32_bf16 v[96:99], v[170:173], v[226:229], 0
	v_mfma_f32_16x16x32_bf16 v[124:127], v[166:169], v[202:205], v[124:127]
	v_mfma_f32_16x16x32_bf16 v[120:123], v[174:177], v[202:205], v[120:123]
	v_mfma_f32_16x16x32_bf16 v[116:119], v[166:169], v[214:217], v[116:119]
	v_mfma_f32_16x16x32_bf16 v[112:115], v[174:177], v[214:217], v[112:115]
	v_mfma_f32_16x16x32_bf16 v[108:111], v[166:169], v[222:225], v[108:111]
	v_mfma_f32_16x16x32_bf16 v[104:107], v[174:177], v[222:225], v[104:107]
	v_mfma_f32_16x16x32_bf16 v[100:103], v[166:169], v[230:233], v[100:103]
	v_mfma_f32_16x16x32_bf16 v[96:99], v[174:177], v[230:233], v[96:99]
	s_setprio 0
	s_setprio 1
	v_mfma_f32_16x16x32_bf16 v[88:91], v[178:181], v[198:201], 0
	v_mfma_f32_16x16x32_bf16 v[92:95], v[190:193], v[198:201], 0
	v_mfma_f32_16x16x32_bf16 v[80:83], v[178:181], v[206:209], 0
	v_mfma_f32_16x16x32_bf16 v[84:87], v[190:193], v[206:209], 0
	v_mfma_f32_16x16x32_bf16 v[72:75], v[178:181], v[218:221], 0
	v_mfma_f32_16x16x32_bf16 v[76:79], v[190:193], v[218:221], 0
	v_mfma_f32_16x16x32_bf16 v[64:67], v[178:181], v[226:229], 0
	v_mfma_f32_16x16x32_bf16 v[68:71], v[190:193], v[226:229], 0
	v_mfma_f32_16x16x32_bf16 v[88:91], v[182:185], v[202:205], v[88:91]
	v_mfma_f32_16x16x32_bf16 v[92:95], v[194:197], v[202:205], v[92:95]
	v_mfma_f32_16x16x32_bf16 v[80:83], v[182:185], v[214:217], v[80:83]
	v_mfma_f32_16x16x32_bf16 v[84:87], v[194:197], v[214:217], v[84:87]
	v_mfma_f32_16x16x32_bf16 v[72:75], v[182:185], v[222:225], v[72:75]
	v_mfma_f32_16x16x32_bf16 v[76:79], v[194:197], v[222:225], v[76:79]
	v_mfma_f32_16x16x32_bf16 v[64:67], v[182:185], v[230:233], v[64:67]
	v_mfma_f32_16x16x32_bf16 v[68:71], v[194:197], v[230:233], v[68:71]
	s_setprio 0
	s_barrier
	v_lshl_add_u64 v[236:237], v[152:153], 0, s[64:65]
	s_mov_b32 m0, s79
	v_lshl_add_u64 v[186:187], v[236:237], 0, s[14:15]
	v_lshl_add_u64 v[238:239], v[154:155], 0, s[64:65]
	ds_read_b128 v[198:201], v161 offset:16384
	ds_read_b128 v[202:205], v161 offset:17408
	ds_read_b128 v[206:209], v161 offset:18432
	ds_read_b128 v[214:217], v161 offset:19456
	ds_read_b128 v[218:221], v161 offset:20480
	ds_read_b128 v[222:225], v161 offset:21504
	ds_read_b128 v[226:229], v161 offset:22528
	ds_read_b128 v[230:233], v161 offset:23552
	global_load_lds_dwordx4 v[186:187], off
	v_lshl_add_u64 v[186:187], v[238:239], 0, s[14:15]
	s_mov_b32 m0, s80
	s_add_i32 s0, s74, s23
	global_load_lds_dwordx4 v[186:187], off
	v_lshl_add_u64 v[186:187], v[236:237], 0, s[36:37]
	s_mov_b32 m0, s0
	s_add_i32 s1, s0, 0x2000
	global_load_lds_dwordx4 v[186:187], off
	v_lshl_add_u64 v[186:187], v[238:239], 0, s[36:37]
	s_mov_b32 m0, s1
	s_nop 0
	global_load_lds_dwordx4 v[186:187], off
	v_lshl_add_u64 v[186:187], v[210:211], 0, s[14:15]
	s_mov_b32 m0, s28
	s_nop 0
	global_load_lds_dwordx4 v[186:187], off
	v_lshl_add_u64 v[186:187], v[234:235], 0, s[14:15]
	s_mov_b32 m0, s29
	s_nop 0
	global_load_lds_dwordx4 v[186:187], off
	s_waitcnt vmcnt(8)
	s_waitcnt lgkmcnt(0)
	s_barrier
; #define PG8_STAGE(bufoff, gbase, voff) do { _Pragma("unroll") for (int _i = 0; _i < 2; ++_i) \
;         __builtin_amdgcn_global_load_lds((const unsigned*)((const char*)(gbase) + (voff)[_i]), (PG8_LAS unsigned*)(lds + (bufoff) + ldsw + _i * 8192), 16, 0, 0); } while (0)
; #define PG8_LDA(dst, b, h) do { _Pragma("unroll") for (int m = 0; m < 4; ++m) _Pragma("unroll") for (int k = 0; k < 2; ++k) dst[m][k] = *(const PG8_LAS bf16x8*)(lds + PG8_SA(b, h) + aoff + m * 2048 + k * 1024); } while (0)
; #define PG8_LDB(dst, b, h) do { _Pragma("unroll") for (int n = 0; n < 2; ++n) _Pragma("unroll") for (int k = 0; k < 2; ++k) dst[n][k] = *(const PG8_LAS bf16x8*)(lds + PG8_SB(b, h) + boff + n * 2048 + k * 1024); } while (0)
; #define PG8_MMA(ai, bj, At, Bt) do { __builtin_amdgcn_s_setprio(1); _Pragma("unroll") for (int m = 0; m < 4; ++m) _Pragma("unroll") for (int n = 0; n < 2; ++n) _Pragma("unroll") for (int k = 0; k < 2; ++k) \
;         acc[ai][bj][m][n] = __builtin_amdgcn_mfma_f32_16x16x32_bf16(Bt[n][k], At[m][k], acc[ai][bj][m][n], 0, 0, 0); __builtin_amdgcn_s_setprio(0); } while (0)
; #define PG8_BAR __builtin_amdgcn_s_barrier()
; template <class Epi, class Sched, bool ALIGN_EPI = false, bool SP2 = false>
; __device__ __forceinline__ void gemm_phase(PG8_LAS unsigned char* lds, const Gemm g, const Sched& S, const Epi& E) {
;     ...
;             if constexpr (SP2) {
;             PG8_LDB(B0, 0, 0); PG8_LDB(B1, 0, 1); PG8_SCHED; PG8_LDA(At, 0, 0); PG8_STAGE(PG8_SA(1, 1), a1 + hstep, voffA);
;             PG8_WAIT_V(8); PG8_WAIT_L(0); PG8_BAR; PG8_MMA(0, 0, At, B0); PG8_MMA(0, 1, At, B1); PG8_BAR; PG8_SCHED;
;             PG8_LDA(At, 0, 1); PG8_STAGE(PG8_SB(0, 0), b2, voffB); PG8_STAGE(PG8_SB(0, 1), b2 + hstep, voffB); PG8_STAGE(PG8_SA(0, 0), a2, voffA);
;             PG8_WAIT_V(8); PG8_WAIT_L(0); PG8_BAR; PG8_MMA(1, 0, At, B0); PG8_MMA(1, 1, At, B1); PG8_BAR; PG8_SCHED;
;             PG8_LDB(B0, 1, 0); PG8_LDB(B1, 1, 1); PG8_SCHED; PG8_LDA(At, 1, 0); PG8_STAGE(PG8_SA(0, 1), a2 + hstep, voffA);
;             PG8_WAIT_V(8); PG8_WAIT_L(0); PG8_BAR; PG8_MMA(0, 0, At, B0); PG8_MMA(0, 1, At, B1); PG8_BAR; PG8_SCHED;
;             PG8_LDA(At, 1, 1); PG8_STAGE(PG8_SB(1, 0), b3, voffB); PG8_STAGE(PG8_SB(1, 1), b3 + hstep, voffB); PG8_STAGE(PG8_SA(1, 0), a3, voffA);
;             PG8_WAIT_V(8); PG8_WAIT_L(0); PG8_BAR; PG8_MMA(1, 0, At, B0); PG8_MMA(1, 1, At, B1); PG8_BAR; PG8_SCHED;
	s_setprio 1
	s_waitcnt lgkmcnt(0)
	v_mfma_f32_16x16x32_bf16 v[60:63], v[162:165], v[198:201], 0
	v_mfma_f32_16x16x32_bf16 v[56:59], v[170:173], v[198:201], 0
	v_mfma_f32_16x16x32_bf16 v[44:47], v[162:165], v[206:209], 0
	v_mfma_f32_16x16x32_bf16 v[40:43], v[170:173], v[206:209], 0
	v_mfma_f32_16x16x32_bf16 v[28:31], v[162:165], v[218:221], 0
	v_mfma_f32_16x16x32_bf16 v[24:27], v[170:173], v[218:221], 0
	v_mfma_f32_16x16x32_bf16 v[12:15], v[162:165], v[226:229], 0
	v_mfma_f32_16x16x32_bf16 v[8:11], v[170:173], v[226:229], 0
	v_mfma_f32_16x16x32_bf16 v[60:63], v[166:169], v[202:205], v[60:63]
	v_mfma_f32_16x16x32_bf16 v[56:59], v[174:177], v[202:205], v[56:59]
	v_mfma_f32_16x16x32_bf16 v[44:47], v[166:169], v[214:217], v[44:47]
	v_mfma_f32_16x16x32_bf16 v[40:43], v[174:177], v[214:217], v[40:43]
	v_mfma_f32_16x16x32_bf16 v[28:31], v[166:169], v[222:225], v[28:31]
	v_mfma_f32_16x16x32_bf16 v[24:27], v[174:177], v[222:225], v[24:27]
	v_mfma_f32_16x16x32_bf16 v[12:15], v[166:169], v[230:233], v[12:15]
	v_mfma_f32_16x16x32_bf16 v[8:11], v[174:177], v[230:233], v[8:11]
	s_setprio 0
	s_setprio 1
	v_mfma_f32_16x16x32_bf16 v[52:55], v[178:181], v[198:201], 0
	v_mfma_f32_16x16x32_bf16 v[48:51], v[190:193], v[198:201], 0
	v_mfma_f32_16x16x32_bf16 v[36:39], v[178:181], v[206:209], 0
	v_mfma_f32_16x16x32_bf16 v[32:35], v[190:193], v[206:209], 0
	v_mfma_f32_16x16x32_bf16 v[20:23], v[178:181], v[218:221], 0
	v_mfma_f32_16x16x32_bf16 v[16:19], v[190:193], v[218:221], 0
	v_mfma_f32_16x16x32_bf16 v[4:7], v[178:181], v[226:229], 0
	v_mfma_f32_16x16x32_bf16 v[0:3], v[190:193], v[226:229], 0
	v_mfma_f32_16x16x32_bf16 v[52:55], v[182:185], v[202:205], v[52:55]
	v_mfma_f32_16x16x32_bf16 v[48:51], v[194:197], v[202:205], v[48:51]
	v_mfma_f32_16x16x32_bf16 v[36:39], v[182:185], v[214:217], v[36:39]
	v_mfma_f32_16x16x32_bf16 v[32:35], v[194:197], v[214:217], v[32:35]
	v_mfma_f32_16x16x32_bf16 v[20:23], v[182:185], v[222:225], v[20:23]
	v_mfma_f32_16x16x32_bf16 v[16:19], v[194:197], v[222:225], v[16:19]
	v_mfma_f32_16x16x32_bf16 v[4:7], v[182:185], v[230:233], v[4:7]
	v_mfma_f32_16x16x32_bf16 v[0:3], v[194:197], v[230:233], v[0:3]
	s_setprio 0
	s_barrier
	v_add_u32_e32 v162, s75, v157
	v_add_u32_e32 v163, s84, v157
	ds_read_b128 v[164:167], v162
	ds_read_b128 v[168:171], v162 offset:1024
	ds_read_b128 v[172:175], v162 offset:2048
	ds_read_b128 v[176:179], v162 offset:3072
	ds_read_b128 v[180:183], v163
	ds_read_b128 v[184:187], v163 offset:1024
	ds_read_b128 v[190:193], v163 offset:2048
	ds_read_b128 v[194:197], v163 offset:3072
	s_mov_b32 m0, s30
	v_lshl_add_u64 v[240:241], v[210:211], 0, s[36:37]
	ds_read_b128 v[198:201], v161 offset:32768
	ds_read_b128 v[202:205], v161 offset:33792
	ds_read_b128 v[206:209], v161 offset:34816
	ds_read_b128 v[214:217], v161 offset:35840
	ds_read_b128 v[218:221], v161 offset:36864
	ds_read_b128 v[222:225], v161 offset:37888
	ds_read_b128 v[226:229], v161 offset:38912
	ds_read_b128 v[230:233], v161 offset:39936
	global_load_lds_dwordx4 v[240:241], off
	v_lshl_add_u64 v[240:241], v[234:235], 0, s[36:37]
	s_mov_b32 m0, s33
	s_nop 0
	global_load_lds_dwordx4 v[240:241], off
	s_waitcnt vmcnt(8)
	s_waitcnt lgkmcnt(0)
	s_barrier
	s_setprio 1
	s_waitcnt lgkmcnt(0)
	v_mfma_f32_16x16x32_bf16 v[124:127], v[164:167], v[198:201], v[124:127]
	v_mfma_f32_16x16x32_bf16 v[120:123], v[172:175], v[198:201], v[120:123]
	v_mfma_f32_16x16x32_bf16 v[116:119], v[164:167], v[206:209], v[116:119]
	v_mfma_f32_16x16x32_bf16 v[112:115], v[172:175], v[206:209], v[112:115]
	v_mfma_f32_16x16x32_bf16 v[108:111], v[164:167], v[218:221], v[108:111]
	v_mfma_f32_16x16x32_bf16 v[104:107], v[172:175], v[218:221], v[104:107]
	v_mfma_f32_16x16x32_bf16 v[100:103], v[164:167], v[226:229], v[100:103]
	v_mfma_f32_16x16x32_bf16 v[96:99], v[172:175], v[226:229], v[96:99]
	v_mfma_f32_16x16x32_bf16 v[124:127], v[168:171], v[202:205], v[124:127]
	v_mfma_f32_16x16x32_bf16 v[120:123], v[176:179], v[202:205], v[120:123]
	v_mfma_f32_16x16x32_bf16 v[116:119], v[168:171], v[214:217], v[116:119]
	v_mfma_f32_16x16x32_bf16 v[112:115], v[176:179], v[214:217], v[112:115]
	v_mfma_f32_16x16x32_bf16 v[108:111], v[168:171], v[222:225], v[108:111]
	v_mfma_f32_16x16x32_bf16 v[104:107], v[176:179], v[222:225], v[104:107]
	v_mfma_f32_16x16x32_bf16 v[100:103], v[168:171], v[230:233], v[100:103]
	v_mfma_f32_16x16x32_bf16 v[96:99], v[176:179], v[230:233], v[96:99]
	s_setprio 0
	s_setprio 1
	v_mfma_f32_16x16x32_bf16 v[88:91], v[180:183], v[198:201], v[88:91]
	v_mfma_f32_16x16x32_bf16 v[92:95], v[190:193], v[198:201], v[92:95]
	v_mfma_f32_16x16x32_bf16 v[80:83], v[180:183], v[206:209], v[80:83]
	v_mfma_f32_16x16x32_bf16 v[84:87], v[190:193], v[206:209], v[84:87]
	v_mfma_f32_16x16x32_bf16 v[72:75], v[180:183], v[218:221], v[72:75]
	v_mfma_f32_16x16x32_bf16 v[76:79], v[190:193], v[218:221], v[76:79]
	v_mfma_f32_16x16x32_bf16 v[64:67], v[180:183], v[226:229], v[64:67]
	v_mfma_f32_16x16x32_bf16 v[68:71], v[190:193], v[226:229], v[68:71]
	v_mfma_f32_16x16x32_bf16 v[88:91], v[184:187], v[202:205], v[88:91]
	v_mfma_f32_16x16x32_bf16 v[92:95], v[194:197], v[202:205], v[92:95]
	v_mfma_f32_16x16x32_bf16 v[80:83], v[184:187], v[214:217], v[80:83]
	v_mfma_f32_16x16x32_bf16 v[84:87], v[194:197], v[214:217], v[84:87]
	v_mfma_f32_16x16x32_bf16 v[72:75], v[184:187], v[222:225], v[72:75]
	v_mfma_f32_16x16x32_bf16 v[76:79], v[194:197], v[222:225], v[76:79]
	v_mfma_f32_16x16x32_bf16 v[64:67], v[184:187], v[230:233], v[64:67]
	v_mfma_f32_16x16x32_bf16 v[68:71], v[194:197], v[230:233], v[68:71]
	s_setprio 0
	s_barrier
; #define PG8_STAGE(bufoff, gbase, voff) do { _Pragma("unroll") for (int _i = 0; _i < 2; ++_i) \
;         __builtin_amdgcn_global_load_lds((const unsigned*)((const char*)(gbase) + (voff)[_i]), (PG8_LAS unsigned*)(lds + (bufoff) + ldsw + _i * 8192), 16, 0, 0); } while (0)
; #define PG8_LDA(dst, b, h) do { _Pragma("unroll") for (int m = 0; m < 4; ++m) _Pragma("unroll") for (int k = 0; k < 2; ++k) dst[m][k] = *(const PG8_LAS bf16x8*)(lds + PG8_SA(b, h) + aoff + m * 2048 + k * 1024); } while (0)
; #define PG8_LDB(dst, b, h) do { _Pragma("unroll") for (int n = 0; n < 2; ++n) _Pragma("unroll") for (int k = 0; k < 2; ++k) dst[n][k] = *(const PG8_LAS bf16x8*)(lds + PG8_SB(b, h) + boff + n * 2048 + k * 1024); } while (0)
; #define PG8_MMA(ai, bj, At, Bt) do { __builtin_amdgcn_s_setprio(1); _Pragma("unroll") for (int m = 0; m < 4; ++m) _Pragma("unroll") for (int n = 0; n < 2; ++n) _Pragma("unroll") for (int k = 0; k < 2; ++k) \
;         acc[ai][bj][m][n] = __builtin_amdgcn_mfma_f32_16x16x32_bf16(Bt[n][k], At[m][k], acc[ai][bj][m][n], 0, 0, 0); __builtin_amdgcn_s_setprio(0); } while (0)
; #define PG8_BAR __builtin_amdgcn_s_barrier()
; template <class Epi, class Sched, bool ALIGN_EPI = false, bool SP2 = false>
; __device__ __forceinline__ void gemm_phase(PG8_LAS unsigned char* lds, const Gemm g, const Sched& S, const Epi& E) {
;     ...
;             if constexpr (SP2) {
;             PG8_LDB(B0, 0, 0); PG8_LDB(B1, 0, 1); PG8_SCHED; PG8_LDA(At, 0, 0); PG8_STAGE(PG8_SA(1, 1), a1 + hstep, voffA);
;             PG8_WAIT_V(8); PG8_WAIT_L(0); PG8_BAR; PG8_MMA(0, 0, At, B0); PG8_MMA(0, 1, At, B1); PG8_BAR; PG8_SCHED;
;             PG8_LDA(At, 0, 1); PG8_STAGE(PG8_SB(0, 0), b2, voffB); PG8_STAGE(PG8_SB(0, 1), b2 + hstep, voffB); PG8_STAGE(PG8_SA(0, 0), a2, voffA);
;             PG8_WAIT_V(8); PG8_WAIT_L(0); PG8_BAR; PG8_MMA(1, 0, At, B0); PG8_MMA(1, 1, At, B1); PG8_BAR; PG8_SCHED;
;             PG8_LDB(B0, 1, 0); PG8_LDB(B1, 1, 1); PG8_SCHED; PG8_LDA(At, 1, 0); PG8_STAGE(PG8_SA(0, 1), a2 + hstep, voffA);
;             PG8_WAIT_V(8); PG8_WAIT_L(0); PG8_BAR; PG8_MMA(0, 0, At, B0); PG8_MMA(0, 1, At, B1); PG8_BAR; PG8_SCHED;
;             PG8_LDA(At, 1, 1); PG8_STAGE(PG8_SB(1, 0), b3, voffB); PG8_STAGE(PG8_SB(1, 1), b3 + hstep, voffB); PG8_STAGE(PG8_SA(1, 0), a3, voffA);
;             PG8_WAIT_V(8); PG8_WAIT_L(0); PG8_BAR; PG8_MMA(1, 0, At, B0); PG8_MMA(1, 1, At, B1); PG8_BAR; PG8_SCHED;
	s_add_i32 s82, s75, s23
	v_lshl_add_u64 v[240:241], v[236:237], 0, s[40:41]
	s_mov_b32 m0, s82
	s_add_i32 s83, s82, 0x2000
	ds_read_b128 v[198:201], v161 offset:49152
	ds_read_b128 v[202:205], v161 offset:50176
	ds_read_b128 v[206:209], v161 offset:51200
	ds_read_b128 v[214:217], v161 offset:52224
	ds_read_b128 v[218:221], v161 offset:53248
	ds_read_b128 v[222:225], v161 offset:54272
	ds_read_b128 v[226:229], v161 offset:55296
	ds_read_b128 v[230:233], v161 offset:56320
	global_load_lds_dwordx4 v[240:241], off
	v_lshl_add_u64 v[240:241], v[238:239], 0, s[40:41]
	s_mov_b32 m0, s83
	s_add_i32 s85, s84, s23
	global_load_lds_dwordx4 v[240:241], off
	v_lshl_add_u64 v[236:237], v[236:237], 0, s[46:47]
	s_mov_b32 m0, s85
	s_add_i32 s86, s85, 0x2000
	global_load_lds_dwordx4 v[236:237], off
	v_lshl_add_u64 v[236:237], v[238:239], 0, s[46:47]
	s_mov_b32 m0, s86
	v_lshl_add_u64 v[210:211], v[210:211], 0, s[40:41]
	global_load_lds_dwordx4 v[236:237], off
	s_mov_b32 m0, s71
	s_nop 0
	global_load_lds_dwordx4 v[210:211], off
	v_lshl_add_u64 v[210:211], v[234:235], 0, s[40:41]
	s_mov_b32 m0, s76
	s_nop 0
	global_load_lds_dwordx4 v[210:211], off
	s_waitcnt vmcnt(8)
	s_waitcnt lgkmcnt(0)
	s_barrier
	s_setprio 1
	s_waitcnt lgkmcnt(0)
	v_mfma_f32_16x16x32_bf16 v[60:63], v[164:167], v[198:201], v[60:63]
	v_mfma_f32_16x16x32_bf16 v[56:59], v[172:175], v[198:201], v[56:59]
	v_mfma_f32_16x16x32_bf16 v[44:47], v[164:167], v[206:209], v[44:47]
	v_mfma_f32_16x16x32_bf16 v[40:43], v[172:175], v[206:209], v[40:43]
	v_mfma_f32_16x16x32_bf16 v[28:31], v[164:167], v[218:221], v[28:31]
	v_mfma_f32_16x16x32_bf16 v[24:27], v[172:175], v[218:221], v[24:27]
	v_mfma_f32_16x16x32_bf16 v[12:15], v[164:167], v[226:229], v[12:15]
	v_mfma_f32_16x16x32_bf16 v[8:11], v[172:175], v[226:229], v[8:11]
	v_mfma_f32_16x16x32_bf16 v[60:63], v[168:171], v[202:205], v[60:63]
	v_mfma_f32_16x16x32_bf16 v[56:59], v[176:179], v[202:205], v[56:59]
	v_mfma_f32_16x16x32_bf16 v[44:47], v[168:171], v[214:217], v[44:47]
	v_mfma_f32_16x16x32_bf16 v[40:43], v[176:179], v[214:217], v[40:43]
	v_mfma_f32_16x16x32_bf16 v[28:31], v[168:171], v[222:225], v[28:31]
	v_mfma_f32_16x16x32_bf16 v[24:27], v[176:179], v[222:225], v[24:27]
	v_mfma_f32_16x16x32_bf16 v[12:15], v[168:171], v[230:233], v[12:15]
	v_mfma_f32_16x16x32_bf16 v[8:11], v[176:179], v[230:233], v[8:11]
	s_setprio 0
	s_setprio 1
	v_mfma_f32_16x16x32_bf16 v[52:55], v[180:183], v[198:201], v[52:55]
	v_mfma_f32_16x16x32_bf16 v[48:51], v[190:193], v[198:201], v[48:51]
	v_mfma_f32_16x16x32_bf16 v[36:39], v[180:183], v[206:209], v[36:39]
	v_mfma_f32_16x16x32_bf16 v[32:35], v[190:193], v[206:209], v[32:35]
	v_mfma_f32_16x16x32_bf16 v[20:23], v[180:183], v[218:221], v[20:23]
	v_mfma_f32_16x16x32_bf16 v[16:19], v[190:193], v[218:221], v[16:19]
	v_mfma_f32_16x16x32_bf16 v[4:7], v[180:183], v[226:229], v[4:7]
	v_mfma_f32_16x16x32_bf16 v[0:3], v[190:193], v[226:229], v[0:3]
	v_mfma_f32_16x16x32_bf16 v[52:55], v[184:187], v[202:205], v[52:55]
	v_mfma_f32_16x16x32_bf16 v[48:51], v[194:197], v[202:205], v[48:51]
	v_mfma_f32_16x16x32_bf16 v[36:39], v[184:187], v[214:217], v[36:39]
	v_mfma_f32_16x16x32_bf16 v[32:35], v[194:197], v[214:217], v[32:35]
	v_mfma_f32_16x16x32_bf16 v[20:23], v[184:187], v[222:225], v[20:23]
	v_mfma_f32_16x16x32_bf16 v[16:19], v[194:197], v[222:225], v[16:19]
	v_mfma_f32_16x16x32_bf16 v[4:7], v[184:187], v[230:233], v[4:7]
	v_mfma_f32_16x16x32_bf16 v[0:3], v[194:197], v[230:233], v[0:3]
	s_setprio 0
	s_barrier
	s_add_i32 s59, s59, 2
	s_add_u32 s64, s64, 0x100
	s_addc_u32 s65, s65, 0
	s_cmp_gt_u32 s59, 13

;     __device__ bool next(int i, Unit& u) const { if (i >= n) return false; const int q = first + i; u.pm = rowbase + q % rows; u.pn = q / rows; return true; }
; #define PG8_WAIT_V(n) asm volatile("s_waitcnt vmcnt(" #n ")" ::: "memory")
; template <class Epi, class Sched, bool ALIGN_EPI = false, bool SP2 = false>
; __device__ __forceinline__ void gemm_phase(PG8_LAS unsigned char* lds, const Gemm g, const Sched& S, const Epi& E) {
;     ...
;         const bool has_next = S.next(ui + 1, nxt);
;         const char* nA = has_next ? (const char*)g.A + (size_t)nxt.pm * tstep : cA; const char* nB = has_next ? (const char*)g.Bt + (size_t)nxt.pn * tstep : cB;
;         constexpr int NSEG = Epi::HAS_MID ? 2 : 1; const int tseg = nt / NSEG;
; #pragma unroll
;         for (int seg = 0; seg < NSEG; ++seg) {
;         if constexpr (Epi::HAS_MID) { if (seg == 1) E.mid(acc, cur, wr, wc, fr, fq); }
;         for (int t = seg * tseg; t < (seg + 1) * tseg; t += 2) {
;             const bool last = (t == nt - 2);
;             const char* a1 = cA + (size_t)(t + 1) * kstep;
;             const char* a2 = last ? nA : cA + (size_t)(t + 2) * kstep; const char* b2 = last ? nB : cB + (size_t)(t + 2) * kstep;
;             const char* a3 = a2 + kstep; const char* b3 = b2 + kstep;
;             if (last && has_next) S.a_ready(nxt);
;             if constexpr (SP2) {
;             PG8_LDB(B0, 0, 0); PG8_LDB(B1, 0, 1); PG8_SCHED; PG8_LDA(At, 0, 0); PG8_STAGE(PG8_SA(1, 1), a1 + hstep, voffA);
;             PG8_WAIT_V(8); PG8_WAIT_L(0); PG8_BAR; PG8_MMA(0, 0, At, B0); PG8_MMA(0, 1, At, B1); PG8_BAR; PG8_SCHED;
;             PG8_LDA(At, 0, 1); PG8_STAGE(PG8_SB(0, 0), b2, voffB); PG8_STAGE(PG8_SB(0, 1), b2 + hstep, voffB); PG8_STAGE(PG8_SA(0, 0), a2, voffA);
;             PG8_WAIT_V(8); PG8_WAIT_L(0); PG8_BAR; PG8_MMA(1, 0, At, B0); PG8_MMA(1, 1, At, B1); PG8_BAR; PG8_SCHED;
;             PG8_LDB(B0, 1, 0); PG8_LDB(B1, 1, 1); PG8_SCHED; PG8_LDA(At, 1, 0); PG8_STAGE(PG8_SA(0, 1), a2 + hstep, voffA);
;             PG8_WAIT_V(8); PG8_WAIT_L(0); PG8_BAR; PG8_MMA(0, 0, At, B0); PG8_MMA(0, 1, At, B1); PG8_BAR; PG8_SCHED;
;             PG8_LDA(At, 1, 1); PG8_STAGE(PG8_SB(1, 0), b3, voffB); PG8_STAGE(PG8_SB(1, 1), b3 + hstep, voffB); PG8_STAGE(PG8_SA(1, 0), a3, voffA);
;             PG8_WAIT_V(8); PG8_WAIT_L(0); PG8_BAR; PG8_MMA(1, 0, At, B0); PG8_MMA(1, 1, At, B1); PG8_BAR; PG8_SCHED;
.LBB0_780:
	s_ashr_i32 s47, s46, 31
	s_lshl_b64 s[0:1], s[46:47], 20
	s_add_u32 s56, s54, s0
	s_addc_u32 s57, s55, s1
	s_and_b64 s[0:1], s[4:5], exec
	s_cselect_b32 s0, s57, s63
	s_cselect_b32 s1, s56, s62
	s_ashr_i32 s41, s40, 31
	s_lshl_b64 s[58:59], s[40:41], 20
	s_add_u32 s58, s20, s58
	s_addc_u32 s59, s21, s59
	s_and_b64 s[66:67], s[4:5], exec
	s_cselect_b32 s41, s59, s65
	s_cselect_b32 s47, s58, s64
	s_add_u32 s62, s62, 0x80080
	s_addc_u32 s63, s63, 0
	s_add_u32 s71, s64, 0x100
	s_addc_u32 s76, s65, 0
	s_mov_b32 s77, -2
	ds_read_b128 v[128:131], v169
	ds_read_b128 v[132:135], v169 offset:1024
	ds_read_b128 v[136:139], v169 offset:2048
	ds_read_b128 v[140:143], v169 offset:3072
	ds_read_b128 v[160:163], v170
	ds_read_b128 v[172:175], v170 offset:1024
	ds_read_b128 v[176:179], v170 offset:2048
	ds_read_b128 v[180:183], v170 offset:3072
	s_add_u32 s64, s62, 0xfff80080
	s_addc_u32 s65, s63, -1
	s_cmp_eq_u32 s77, 28
	s_cselect_b32 s67, s0, s65
	s_cselect_b32 s66, s1, s64
	s_cselect_b32 s65, s41, s76
	s_cselect_b32 s64, s47, s71
	v_lshl_add_u64 v[164:165], s[62:63], 0, v[152:153]
	s_add_i32 m0, s3, 0xc000
	ds_read_b128 v[184:187], v171
	ds_read_b128 v[190:193], v171 offset:1024
	ds_read_b128 v[194:197], v171 offset:2048
	ds_read_b128 v[198:201], v171 offset:3072
	ds_read_b128 v[202:205], v171 offset:4096
	ds_read_b128 v[206:209], v171 offset:5120
	ds_read_b128 v[214:217], v171 offset:6144
	ds_read_b128 v[218:221], v171 offset:7168
	global_load_lds_dwordx4 v[164:165], off
	v_lshl_add_u64 v[164:165], s[62:63], 0, v[154:155]
	s_add_i32 m0, s3, 0xe000
	s_nop 0
	global_load_lds_dwordx4 v[164:165], off
	s_waitcnt vmcnt(8)
	s_waitcnt lgkmcnt(0)
	s_barrier
	s_setprio 1
	s_waitcnt lgkmcnt(0)
	v_mfma_f32_16x16x32_bf16 v[124:127], v[128:131], v[184:187], 0
	v_mfma_f32_16x16x32_bf16 v[120:123], v[136:139], v[184:187], 0
	v_mfma_f32_16x16x32_bf16 v[108:111], v[128:131], v[194:197], 0
	v_mfma_f32_16x16x32_bf16 v[104:107], v[136:139], v[194:197], 0
	v_mfma_f32_16x16x32_bf16 v[92:95], v[128:131], v[202:205], 0
	v_mfma_f32_16x16x32_bf16 v[88:91], v[136:139], v[202:205], 0
	v_mfma_f32_16x16x32_bf16 v[76:79], v[128:131], v[214:217], 0
	v_mfma_f32_16x16x32_bf16 v[72:75], v[136:139], v[214:217], 0
	v_mfma_f32_16x16x32_bf16 v[124:127], v[132:135], v[190:193], v[124:127]
	v_mfma_f32_16x16x32_bf16 v[120:123], v[140:143], v[190:193], v[120:123]
	v_mfma_f32_16x16x32_bf16 v[108:111], v[132:135], v[198:201], v[108:111]
	v_mfma_f32_16x16x32_bf16 v[104:107], v[140:143], v[198:201], v[104:107]
	v_mfma_f32_16x16x32_bf16 v[92:95], v[132:135], v[206:209], v[92:95]
	v_mfma_f32_16x16x32_bf16 v[88:91], v[140:143], v[206:209], v[88:91]
	v_mfma_f32_16x16x32_bf16 v[76:79], v[132:135], v[218:221], v[76:79]
	v_mfma_f32_16x16x32_bf16 v[72:75], v[140:143], v[218:221], v[72:75]
	s_setprio 0
	s_setprio 1
	v_mfma_f32_16x16x32_bf16 v[116:119], v[160:163], v[184:187], 0
	v_mfma_f32_16x16x32_bf16 v[112:115], v[176:179], v[184:187], 0
	v_mfma_f32_16x16x32_bf16 v[100:103], v[160:163], v[194:197], 0
	v_mfma_f32_16x16x32_bf16 v[96:99], v[176:179], v[194:197], 0
	v_mfma_f32_16x16x32_bf16 v[84:87], v[160:163], v[202:205], 0
	v_mfma_f32_16x16x32_bf16 v[80:83], v[176:179], v[202:205], 0
	v_mfma_f32_16x16x32_bf16 v[68:71], v[160:163], v[214:217], 0
	v_mfma_f32_16x16x32_bf16 v[64:67], v[176:179], v[214:217], 0
	v_mfma_f32_16x16x32_bf16 v[116:119], v[172:175], v[190:193], v[116:119]
	v_mfma_f32_16x16x32_bf16 v[112:115], v[180:183], v[190:193], v[112:115]
	v_mfma_f32_16x16x32_bf16 v[100:103], v[172:175], v[198:201], v[100:103]
	v_mfma_f32_16x16x32_bf16 v[96:99], v[180:183], v[198:201], v[96:99]
	v_mfma_f32_16x16x32_bf16 v[84:87], v[172:175], v[206:209], v[84:87]
	v_mfma_f32_16x16x32_bf16 v[80:83], v[180:183], v[206:209], v[80:83]
	v_mfma_f32_16x16x32_bf16 v[68:71], v[172:175], v[218:221], v[68:71]
	v_mfma_f32_16x16x32_bf16 v[64:67], v[180:183], v[218:221], v[64:67]
	s_setprio 0
	s_barrier
	s_add_i32 s78, s31, s2
	v_lshl_add_u64 v[164:165], s[64:65], 0, v[146:147]
	s_mov_b32 m0, s78
	ds_read_b128 v[184:187], v171 offset:16384
	ds_read_b128 v[190:193], v171 offset:17408
	ds_read_b128 v[194:197], v171 offset:18432
	ds_read_b128 v[198:201], v171 offset:19456
	ds_read_b128 v[202:205], v171 offset:20480
	ds_read_b128 v[206:209], v171 offset:21504
	ds_read_b128 v[214:217], v171 offset:22528
	ds_read_b128 v[218:221], v171 offset:23552
	global_load_lds_dwordx4 v[164:165], off
	s_add_i32 m0, s78, 0x2000
	s_add_u32 s78, s64, 0x80000
	v_lshl_add_u64 v[210:211], s[64:65], 0, v[150:151]
	s_addc_u32 s79, s65, 0
	s_add_i32 s80, s74, s2
	global_load_lds_dwordx4 v[210:211], off
	v_lshl_add_u64 v[222:223], s[78:79], 0, v[146:147]
	s_mov_b32 m0, s80
	v_lshl_add_u64 v[224:225], s[66:67], 0, v[148:149]
	global_load_lds_dwordx4 v[222:223], off
	v_lshl_add_u64 v[222:223], s[78:79], 0, v[150:151]
	s_add_i32 m0, s80, 0x2000
	s_nop 0
	global_load_lds_dwordx4 v[222:223], off
	v_lshl_add_u64 v[222:223], s[66:67], 0, v[144:145]
	s_mov_b32 m0, s3
	s_nop 0
	global_load_lds_dwordx4 v[222:223], off
	s_mov_b32 m0, s23
	s_nop 0
	global_load_lds_dwordx4 v[224:225], off
	s_waitcnt vmcnt(8)
	s_waitcnt lgkmcnt(0)
	s_barrier
; #define PG8_STAGE(bufoff, gbase, voff) do { _Pragma("unroll") for (int _i = 0; _i < 2; ++_i) \
;         __builtin_amdgcn_global_load_lds((const unsigned*)((const char*)(gbase) + (voff)[_i]), (PG8_LAS unsigned*)(lds + (bufoff) + ldsw + _i * 8192), 16, 0, 0); } while (0)
; #define PG8_LDA(dst, b, h) do { _Pragma("unroll") for (int m = 0; m < 4; ++m) _Pragma("unroll") for (int k = 0; k < 2; ++k) dst[m][k] = *(const PG8_LAS bf16x8*)(lds + PG8_SA(b, h) + aoff + m * 2048 + k * 1024); } while (0)
; #define PG8_LDB(dst, b, h) do { _Pragma("unroll") for (int n = 0; n < 2; ++n) _Pragma("unroll") for (int k = 0; k < 2; ++k) dst[n][k] = *(const PG8_LAS bf16x8*)(lds + PG8_SB(b, h) + boff + n * 2048 + k * 1024); } while (0)
; #define PG8_MMA(ai, bj, At, Bt) do { __builtin_amdgcn_s_setprio(1); _Pragma("unroll") for (int m = 0; m < 4; ++m) _Pragma("unroll") for (int n = 0; n < 2; ++n) _Pragma("unroll") for (int k = 0; k < 2; ++k) \
;         acc[ai][bj][m][n] = __builtin_amdgcn_mfma_f32_16x16x32_bf16(Bt[n][k], At[m][k], acc[ai][bj][m][n], 0, 0, 0); __builtin_amdgcn_s_setprio(0); } while (0)
; #define PG8_BAR __builtin_amdgcn_s_barrier()
; template <class Epi, class Sched, bool ALIGN_EPI = false, bool SP2 = false>
; __device__ __forceinline__ void gemm_phase(PG8_LAS unsigned char* lds, const Gemm g, const Sched& S, const Epi& E) {
;     ...
;             if constexpr (SP2) {
;             PG8_LDB(B0, 0, 0); PG8_LDB(B1, 0, 1); PG8_SCHED; PG8_LDA(At, 0, 0); PG8_STAGE(PG8_SA(1, 1), a1 + hstep, voffA);
;             PG8_WAIT_V(8); PG8_WAIT_L(0); PG8_BAR; PG8_MMA(0, 0, At, B0); PG8_MMA(0, 1, At, B1); PG8_BAR; PG8_SCHED;
;             PG8_LDA(At, 0, 1); PG8_STAGE(PG8_SB(0, 0), b2, voffB); PG8_STAGE(PG8_SB(0, 1), b2 + hstep, voffB); PG8_STAGE(PG8_SA(0, 0), a2, voffA);
;             PG8_WAIT_V(8); PG8_WAIT_L(0); PG8_BAR; PG8_MMA(1, 0, At, B0); PG8_MMA(1, 1, At, B1); PG8_BAR; PG8_SCHED;
;             PG8_LDB(B0, 1, 0); PG8_LDB(B1, 1, 1); PG8_SCHED; PG8_LDA(At, 1, 0); PG8_STAGE(PG8_SA(0, 1), a2 + hstep, voffA);
;             PG8_WAIT_V(8); PG8_WAIT_L(0); PG8_BAR; PG8_MMA(0, 0, At, B0); PG8_MMA(0, 1, At, B1); PG8_BAR; PG8_SCHED;
;             PG8_LDA(At, 1, 1); PG8_STAGE(PG8_SB(1, 0), b3, voffB); PG8_STAGE(PG8_SB(1, 1), b3 + hstep, voffB); PG8_STAGE(PG8_SA(1, 0), a3, voffA);
;             PG8_WAIT_V(8); PG8_WAIT_L(0); PG8_BAR; PG8_MMA(1, 0, At, B0); PG8_MMA(1, 1, At, B1); PG8_BAR; PG8_SCHED;
	s_setprio 1
	s_waitcnt lgkmcnt(0)
	v_mfma_f32_16x16x32_bf16 v[60:63], v[128:131], v[184:187], 0
	v_mfma_f32_16x16x32_bf16 v[56:59], v[136:139], v[184:187], 0
	v_mfma_f32_16x16x32_bf16 v[44:47], v[128:131], v[194:197], 0
	v_mfma_f32_16x16x32_bf16 v[40:43], v[136:139], v[194:197], 0
	v_mfma_f32_16x16x32_bf16 v[28:31], v[128:131], v[202:205], 0
	v_mfma_f32_16x16x32_bf16 v[24:27], v[136:139], v[202:205], 0
	v_mfma_f32_16x16x32_bf16 v[12:15], v[128:131], v[214:217], 0
	v_mfma_f32_16x16x32_bf16 v[8:11], v[136:139], v[214:217], 0
	v_mfma_f32_16x16x32_bf16 v[60:63], v[132:135], v[190:193], v[60:63]
	v_mfma_f32_16x16x32_bf16 v[56:59], v[140:143], v[190:193], v[56:59]
	v_mfma_f32_16x16x32_bf16 v[44:47], v[132:135], v[198:201], v[44:47]
	v_mfma_f32_16x16x32_bf16 v[40:43], v[140:143], v[198:201], v[40:43]
	v_mfma_f32_16x16x32_bf16 v[28:31], v[132:135], v[206:209], v[28:31]
	v_mfma_f32_16x16x32_bf16 v[24:27], v[140:143], v[206:209], v[24:27]
	v_mfma_f32_16x16x32_bf16 v[12:15], v[132:135], v[218:221], v[12:15]
	v_mfma_f32_16x16x32_bf16 v[8:11], v[140:143], v[218:221], v[8:11]
	s_setprio 0
	s_setprio 1
	v_mfma_f32_16x16x32_bf16 v[52:55], v[160:163], v[184:187], 0
	v_mfma_f32_16x16x32_bf16 v[48:51], v[176:179], v[184:187], 0
	v_mfma_f32_16x16x32_bf16 v[36:39], v[160:163], v[194:197], 0
	v_mfma_f32_16x16x32_bf16 v[32:35], v[176:179], v[194:197], 0
	v_mfma_f32_16x16x32_bf16 v[20:23], v[160:163], v[202:205], 0
	v_mfma_f32_16x16x32_bf16 v[16:19], v[176:179], v[202:205], 0
	v_mfma_f32_16x16x32_bf16 v[4:7], v[160:163], v[214:217], 0
	v_mfma_f32_16x16x32_bf16 v[0:3], v[176:179], v[214:217], 0
	v_mfma_f32_16x16x32_bf16 v[52:55], v[172:175], v[190:193], v[52:55]
	v_mfma_f32_16x16x32_bf16 v[48:51], v[180:183], v[190:193], v[48:51]
	v_mfma_f32_16x16x32_bf16 v[36:39], v[172:175], v[198:201], v[36:39]
	v_mfma_f32_16x16x32_bf16 v[32:35], v[180:183], v[198:201], v[32:35]
	v_mfma_f32_16x16x32_bf16 v[20:23], v[172:175], v[206:209], v[20:23]
	v_mfma_f32_16x16x32_bf16 v[16:19], v[180:183], v[206:209], v[16:19]
	v_mfma_f32_16x16x32_bf16 v[4:7], v[172:175], v[218:221], v[4:7]
	v_mfma_f32_16x16x32_bf16 v[0:3], v[180:183], v[218:221], v[0:3]
	s_setprio 0
	s_barrier
	v_add_u32_e32 v140, s75, v167
	v_add_u32_e32 v180, s84, v167
	ds_read_b128 v[128:131], v140
	ds_read_b128 v[132:135], v140 offset:1024
	ds_read_b128 v[136:139], v140 offset:2048
	ds_read_b128 v[140:143], v140 offset:3072
	ds_read_b128 v[160:163], v180
	ds_read_b128 v[172:175], v180 offset:1024
	ds_read_b128 v[176:179], v180 offset:2048
	ds_read_b128 v[180:183], v180 offset:3072
	s_add_u32 s66, s66, 0x80000
	s_addc_u32 s67, s67, 0
	s_mov_b32 m0, s28
	v_lshl_add_u64 v[226:227], s[66:67], 0, v[144:145]
	ds_read_b128 v[184:187], v171 offset:32768
	ds_read_b128 v[190:193], v171 offset:33792
	ds_read_b128 v[194:197], v171 offset:34816
	ds_read_b128 v[198:201], v171 offset:35840
	ds_read_b128 v[202:205], v171 offset:36864
	ds_read_b128 v[206:209], v171 offset:37888
	ds_read_b128 v[214:217], v171 offset:38912
	ds_read_b128 v[218:221], v171 offset:39936
	global_load_lds_dwordx4 v[226:227], off
	v_lshl_add_u64 v[226:227], s[66:67], 0, v[148:149]
	s_mov_b32 m0, s29
	s_nop 0
	global_load_lds_dwordx4 v[226:227], off
	s_waitcnt vmcnt(8)
	s_waitcnt lgkmcnt(0)
	s_barrier
	s_setprio 1
	s_waitcnt lgkmcnt(0)
	v_mfma_f32_16x16x32_bf16 v[124:127], v[128:131], v[184:187], v[124:127]
	v_mfma_f32_16x16x32_bf16 v[120:123], v[136:139], v[184:187], v[120:123]
	v_mfma_f32_16x16x32_bf16 v[108:111], v[128:131], v[194:197], v[108:111]
	v_mfma_f32_16x16x32_bf16 v[104:107], v[136:139], v[194:197], v[104:107]
	v_mfma_f32_16x16x32_bf16 v[92:95], v[128:131], v[202:205], v[92:95]
	v_mfma_f32_16x16x32_bf16 v[88:91], v[136:139], v[202:205], v[88:91]
	v_mfma_f32_16x16x32_bf16 v[76:79], v[128:131], v[214:217], v[76:79]
	v_mfma_f32_16x16x32_bf16 v[72:75], v[136:139], v[214:217], v[72:75]
	v_mfma_f32_16x16x32_bf16 v[124:127], v[132:135], v[190:193], v[124:127]
	v_mfma_f32_16x16x32_bf16 v[120:123], v[140:143], v[190:193], v[120:123]
	v_mfma_f32_16x16x32_bf16 v[108:111], v[132:135], v[198:201], v[108:111]
	v_mfma_f32_16x16x32_bf16 v[104:107], v[140:143], v[198:201], v[104:107]
	v_mfma_f32_16x16x32_bf16 v[92:95], v[132:135], v[206:209], v[92:95]
	v_mfma_f32_16x16x32_bf16 v[88:91], v[140:143], v[206:209], v[88:91]
	v_mfma_f32_16x16x32_bf16 v[76:79], v[132:135], v[218:221], v[76:79]
	v_mfma_f32_16x16x32_bf16 v[72:75], v[140:143], v[218:221], v[72:75]
	s_setprio 0
	s_setprio 1
	v_mfma_f32_16x16x32_bf16 v[116:119], v[160:163], v[184:187], v[116:119]
	v_mfma_f32_16x16x32_bf16 v[112:115], v[176:179], v[184:187], v[112:115]
	v_mfma_f32_16x16x32_bf16 v[100:103], v[160:163], v[194:197], v[100:103]
	v_mfma_f32_16x16x32_bf16 v[96:99], v[176:179], v[194:197], v[96:99]
	v_mfma_f32_16x16x32_bf16 v[84:87], v[160:163], v[202:205], v[84:87]
	v_mfma_f32_16x16x32_bf16 v[80:83], v[176:179], v[202:205], v[80:83]
	v_mfma_f32_16x16x32_bf16 v[68:71], v[160:163], v[214:217], v[68:71]
	v_mfma_f32_16x16x32_bf16 v[64:67], v[176:179], v[214:217], v[64:67]
	v_mfma_f32_16x16x32_bf16 v[116:119], v[172:175], v[190:193], v[116:119]
	v_mfma_f32_16x16x32_bf16 v[112:115], v[180:183], v[190:193], v[112:115]
	v_mfma_f32_16x16x32_bf16 v[100:103], v[172:175], v[198:201], v[100:103]
	v_mfma_f32_16x16x32_bf16 v[96:99], v[180:183], v[198:201], v[96:99]
	v_mfma_f32_16x16x32_bf16 v[84:87], v[172:175], v[206:209], v[84:87]
	v_mfma_f32_16x16x32_bf16 v[80:83], v[180:183], v[206:209], v[80:83]
	v_mfma_f32_16x16x32_bf16 v[68:71], v[172:175], v[218:221], v[68:71]
	v_mfma_f32_16x16x32_bf16 v[64:67], v[180:183], v[218:221], v[64:67]
	s_setprio 0
	s_barrier
; #define PG8_STAGE(bufoff, gbase, voff) do { _Pragma("unroll") for (int _i = 0; _i < 2; ++_i) \
;         __builtin_amdgcn_global_load_lds((const unsigned*)((const char*)(gbase) + (voff)[_i]), (PG8_LAS unsigned*)(lds + (bufoff) + ldsw + _i * 8192), 16, 0, 0); } while (0)
; #define PG8_LDA(dst, b, h) do { _Pragma("unroll") for (int m = 0; m < 4; ++m) _Pragma("unroll") for (int k = 0; k < 2; ++k) dst[m][k] = *(const PG8_LAS bf16x8*)(lds + PG8_SA(b, h) + aoff + m * 2048 + k * 1024); } while (0)
; #define PG8_LDB(dst, b, h) do { _Pragma("unroll") for (int n = 0; n < 2; ++n) _Pragma("unroll") for (int k = 0; k < 2; ++k) dst[n][k] = *(const PG8_LAS bf16x8*)(lds + PG8_SB(b, h) + boff + n * 2048 + k * 1024); } while (0)
; #define PG8_MMA(ai, bj, At, Bt) do { __builtin_amdgcn_s_setprio(1); _Pragma("unroll") for (int m = 0; m < 4; ++m) _Pragma("unroll") for (int n = 0; n < 2; ++n) _Pragma("unroll") for (int k = 0; k < 2; ++k) \
;         acc[ai][bj][m][n] = __builtin_amdgcn_mfma_f32_16x16x32_bf16(Bt[n][k], At[m][k], acc[ai][bj][m][n], 0, 0, 0); __builtin_amdgcn_s_setprio(0); } while (0)
; #define PG8_BAR __builtin_amdgcn_s_barrier()
; template <class Epi, class Sched, bool ALIGN_EPI = false, bool SP2 = false>
; __device__ __forceinline__ void gemm_phase(PG8_LAS unsigned char* lds, const Gemm g, const Sched& S, const Epi& E) {
;     ...
;             if constexpr (SP2) {
;             PG8_LDB(B0, 0, 0); PG8_LDB(B1, 0, 1); PG8_SCHED; PG8_LDA(At, 0, 0); PG8_STAGE(PG8_SA(1, 1), a1 + hstep, voffA);
;             PG8_WAIT_V(8); PG8_WAIT_L(0); PG8_BAR; PG8_MMA(0, 0, At, B0); PG8_MMA(0, 1, At, B1); PG8_BAR; PG8_SCHED;
;             PG8_LDA(At, 0, 1); PG8_STAGE(PG8_SB(0, 0), b2, voffB); PG8_STAGE(PG8_SB(0, 1), b2 + hstep, voffB); PG8_STAGE(PG8_SA(0, 0), a2, voffA);
;             PG8_WAIT_V(8); PG8_WAIT_L(0); PG8_BAR; PG8_MMA(1, 0, At, B0); PG8_MMA(1, 1, At, B1); PG8_BAR; PG8_SCHED;
;             PG8_LDB(B0, 1, 0); PG8_LDB(B1, 1, 1); PG8_SCHED; PG8_LDA(At, 1, 0); PG8_STAGE(PG8_SA(0, 1), a2 + hstep, voffA);
;             PG8_WAIT_V(8); PG8_WAIT_L(0); PG8_BAR; PG8_MMA(0, 0, At, B0); PG8_MMA(0, 1, At, B1); PG8_BAR; PG8_SCHED;
;             PG8_LDA(At, 1, 1); PG8_STAGE(PG8_SB(1, 0), b3, voffB); PG8_STAGE(PG8_SB(1, 1), b3 + hstep, voffB); PG8_STAGE(PG8_SA(1, 0), a3, voffA);
;             PG8_WAIT_V(8); PG8_WAIT_L(0); PG8_BAR; PG8_MMA(1, 0, At, B0); PG8_MMA(1, 1, At, B1); PG8_BAR; PG8_SCHED;
	s_add_i32 s66, s75, s2
	v_lshl_add_u64 v[164:165], v[164:165], 0, s[8:9]
	s_mov_b32 m0, s66
	ds_read_b128 v[184:187], v171 offset:49152
	ds_read_b128 v[190:193], v171 offset:50176
	ds_read_b128 v[194:197], v171 offset:51200
	ds_read_b128 v[198:201], v171 offset:52224
	ds_read_b128 v[202:205], v171 offset:53248
	ds_read_b128 v[206:209], v171 offset:54272
	ds_read_b128 v[214:217], v171 offset:55296
	ds_read_b128 v[218:221], v171 offset:56320
	global_load_lds_dwordx4 v[164:165], off
	s_add_i32 m0, s66, 0x2000
	s_add_u32 s64, s64, 0x80080
	v_lshl_add_u64 v[164:165], v[210:211], 0, s[8:9]
	s_addc_u32 s65, s65, 0
	s_add_i32 s66, s84, s2
	global_load_lds_dwordx4 v[164:165], off
	v_lshl_add_u64 v[164:165], s[64:65], 0, v[146:147]
	s_mov_b32 m0, s66
	s_nop 0
	global_load_lds_dwordx4 v[164:165], off
	v_lshl_add_u64 v[164:165], s[64:65], 0, v[150:151]
	s_add_i32 m0, s66, 0x2000
	s_nop 0
	global_load_lds_dwordx4 v[164:165], off
	v_lshl_add_u64 v[164:165], v[222:223], 0, s[8:9]
	s_mov_b32 m0, s68
	s_nop 0
	global_load_lds_dwordx4 v[164:165], off
	v_lshl_add_u64 v[164:165], v[224:225], 0, s[8:9]
	s_mov_b32 m0, s69
	s_nop 0
	global_load_lds_dwordx4 v[164:165], off
	s_waitcnt vmcnt(8)
	s_waitcnt lgkmcnt(0)
	s_barrier
	s_setprio 1
	s_waitcnt lgkmcnt(0)
	v_mfma_f32_16x16x32_bf16 v[60:63], v[128:131], v[184:187], v[60:63]
	v_mfma_f32_16x16x32_bf16 v[56:59], v[136:139], v[184:187], v[56:59]
	v_mfma_f32_16x16x32_bf16 v[44:47], v[128:131], v[194:197], v[44:47]
	v_mfma_f32_16x16x32_bf16 v[40:43], v[136:139], v[194:197], v[40:43]
	v_mfma_f32_16x16x32_bf16 v[28:31], v[128:131], v[202:205], v[28:31]
	v_mfma_f32_16x16x32_bf16 v[24:27], v[136:139], v[202:205], v[24:27]
	v_mfma_f32_16x16x32_bf16 v[12:15], v[128:131], v[214:217], v[12:15]
	v_mfma_f32_16x16x32_bf16 v[8:11], v[136:139], v[214:217], v[8:11]
	v_mfma_f32_16x16x32_bf16 v[60:63], v[132:135], v[190:193], v[60:63]
	v_mfma_f32_16x16x32_bf16 v[56:59], v[140:143], v[190:193], v[56:59]
	v_mfma_f32_16x16x32_bf16 v[44:47], v[132:135], v[198:201], v[44:47]
	v_mfma_f32_16x16x32_bf16 v[40:43], v[140:143], v[198:201], v[40:43]
	v_mfma_f32_16x16x32_bf16 v[28:31], v[132:135], v[206:209], v[28:31]
	v_mfma_f32_16x16x32_bf16 v[24:27], v[140:143], v[206:209], v[24:27]
	v_mfma_f32_16x16x32_bf16 v[12:15], v[132:135], v[218:221], v[12:15]
	v_mfma_f32_16x16x32_bf16 v[8:11], v[140:143], v[218:221], v[8:11]
	s_setprio 0
	s_setprio 1
	v_mfma_f32_16x16x32_bf16 v[52:55], v[160:163], v[184:187], v[52:55]
	v_mfma_f32_16x16x32_bf16 v[48:51], v[176:179], v[184:187], v[48:51]
	v_mfma_f32_16x16x32_bf16 v[36:39], v[160:163], v[194:197], v[36:39]
	v_mfma_f32_16x16x32_bf16 v[32:35], v[176:179], v[194:197], v[32:35]
	v_mfma_f32_16x16x32_bf16 v[20:23], v[160:163], v[202:205], v[20:23]
	v_mfma_f32_16x16x32_bf16 v[16:19], v[176:179], v[202:205], v[16:19]
	v_mfma_f32_16x16x32_bf16 v[4:7], v[160:163], v[214:217], v[4:7]
	v_mfma_f32_16x16x32_bf16 v[0:3], v[176:179], v[214:217], v[0:3]
	v_mfma_f32_16x16x32_bf16 v[52:55], v[172:175], v[190:193], v[52:55]
	v_mfma_f32_16x16x32_bf16 v[48:51], v[180:183], v[190:193], v[48:51]
	v_mfma_f32_16x16x32_bf16 v[36:39], v[172:175], v[198:201], v[36:39]
	v_mfma_f32_16x16x32_bf16 v[32:35], v[180:183], v[198:201], v[32:35]
	v_mfma_f32_16x16x32_bf16 v[20:23], v[172:175], v[206:209], v[20:23]
	v_mfma_f32_16x16x32_bf16 v[16:19], v[180:183], v[206:209], v[16:19]
	v_mfma_f32_16x16x32_bf16 v[4:7], v[172:175], v[218:221], v[4:7]
	v_mfma_f32_16x16x32_bf16 v[0:3], v[180:183], v[218:221], v[0:3]
	s_setprio 0
	s_barrier
	s_add_i32 s77, s77, 2
	s_add_u32 s62, s62, 0x100
	s_addc_u32 s63, s63, 0
	s_add_u32 s71, s71, 0x100
	s_addc_u32 s76, s76, 0
	s_cmp_gt_u32 s77, 29

;     __device__ bool next(int i, Unit& u) const { if (i >= n) return false; const int q = first + i; u.pm = rowbase + q % rows; u.pn = q / rows; return true; }
; #define PG8_WAIT_V(n) asm volatile("s_waitcnt vmcnt(" #n ")" ::: "memory")
; template <class Epi, class Sched, bool ALIGN_EPI = false, bool SP2 = false>
; __device__ __forceinline__ void gemm_phase(PG8_LAS unsigned char* lds, const Gemm g, const Sched& S, const Epi& E) {
;     ...
;         const bool has_next = S.next(ui + 1, nxt);
;         const char* nA = has_next ? (const char*)g.A + (size_t)nxt.pm * tstep : cA; const char* nB = has_next ? (const char*)g.Bt + (size_t)nxt.pn * tstep : cB;
;         constexpr int NSEG = Epi::HAS_MID ? 2 : 1; const int tseg = nt / NSEG;
; #pragma unroll
;         for (int seg = 0; seg < NSEG; ++seg) {
;         if constexpr (Epi::HAS_MID) { if (seg == 1) E.mid(acc, cur, wr, wc, fr, fq); }
;         for (int t = seg * tseg; t < (seg + 1) * tseg; t += 2) {
;             const bool last = (t == nt - 2);
;             const char* a1 = cA + (size_t)(t + 1) * kstep;
;             const char* a2 = last ? nA : cA + (size_t)(t + 2) * kstep; const char* b2 = last ? nB : cB + (size_t)(t + 2) * kstep;
;             const char* a3 = a2 + kstep; const char* b3 = b2 + kstep;
;             if (last && has_next) S.a_ready(nxt);
;             if constexpr (SP2) {
;             PG8_LDB(B0, 0, 0); PG8_LDB(B1, 0, 1); PG8_SCHED; PG8_LDA(At, 0, 0); PG8_STAGE(PG8_SA(1, 1), a1 + hstep, voffA);
;             PG8_WAIT_V(8); PG8_WAIT_L(0); PG8_BAR; PG8_MMA(0, 0, At, B0); PG8_MMA(0, 1, At, B1); PG8_BAR; PG8_SCHED;
;             PG8_LDA(At, 0, 1); PG8_STAGE(PG8_SB(0, 0), b2, voffB); PG8_STAGE(PG8_SB(0, 1), b2 + hstep, voffB); PG8_STAGE(PG8_SA(0, 0), a2, voffA);
;             PG8_WAIT_V(8); PG8_WAIT_L(0); PG8_BAR; PG8_MMA(1, 0, At, B0); PG8_MMA(1, 1, At, B1); PG8_BAR; PG8_SCHED;
;             PG8_LDB(B0, 1, 0); PG8_LDB(B1, 1, 1); PG8_SCHED; PG8_LDA(At, 1, 0); PG8_STAGE(PG8_SA(0, 1), a2 + hstep, voffA);
;             PG8_WAIT_V(8); PG8_WAIT_L(0); PG8_BAR; PG8_MMA(0, 0, At, B0); PG8_MMA(0, 1, At, B1); PG8_BAR; PG8_SCHED;
;             PG8_LDA(At, 1, 1); PG8_STAGE(PG8_SB(1, 0), b3, voffB); PG8_STAGE(PG8_SB(1, 1), b3 + hstep, voffB); PG8_STAGE(PG8_SA(1, 0), a3, voffA);
;             PG8_WAIT_V(8); PG8_WAIT_L(0); PG8_BAR; PG8_MMA(1, 0, At, B0); PG8_MMA(1, 1, At, B1); PG8_BAR; PG8_SCHED;
.LBB0_927:
	s_ashr_i32 s89, s88, 31
	s_lshl_b64 s[0:1], s[88:89], 20
	s_add_u32 s90, s54, s0
	s_addc_u32 s91, s55, s1
	s_and_b64 s[0:1], s[12:13], exec
	s_cselect_b32 s0, s91, s17
	s_cselect_b32 s1, s90, s16
	s_ashr_i32 s87, s86, 31
	s_lshl_b64 s[20:21], s[86:87], 20
	v_readlane_b32 s56, v242, 24
	v_readlane_b32 s57, v242, 25
	s_add_u32 s92, s56, s20
	s_addc_u32 s93, s57, s21
	s_and_b64 s[20:21], s[12:13], exec
	s_cselect_b32 s15, s93, s19
	s_cselect_b32 s87, s92, s18
	s_add_u32 s16, s16, 0x80080
	s_addc_u32 s17, s17, 0
	s_add_u32 s89, s18, 0x100
	s_addc_u32 s96, s19, 0
	s_mov_b32 s97, -2
	ds_read_b128 v[118:121], v225
	ds_read_b128 v[122:125], v225 offset:1024
	ds_read_b128 v[126:129], v225 offset:2048
	ds_read_b128 v[130:133], v225 offset:3072
	ds_read_b128 v[134:137], v226
	ds_read_b128 v[138:141], v226 offset:1024
	ds_read_b128 v[142:145], v226 offset:2048
	ds_read_b128 v[146:149], v226 offset:3072
	s_add_u32 s18, s16, 0xfff80080
	s_addc_u32 s19, s17, -1
	s_cmp_eq_u32 s97, 28
	s_cselect_b32 s21, s0, s19
	s_cselect_b32 s20, s1, s18
	s_cselect_b32 s19, s15, s96
	s_cselect_b32 s18, s87, s89
	v_lshl_add_u64 v[112:113], s[16:17], 0, v[190:191]
	s_add_i32 m0, s29, 0xc000
	ds_read_b128 v[162:165], v227
	ds_read_b128 v[166:169], v227 offset:1024
	ds_read_b128 v[170:173], v227 offset:2048
	ds_read_b128 v[174:177], v227 offset:3072
	ds_read_b128 v[198:201], v227 offset:4096
	ds_read_b128 v[202:205], v227 offset:5120
	ds_read_b128 v[206:209], v227 offset:6144
	ds_read_b128 v[228:231], v227 offset:7168
	global_load_lds_dwordx4 v[112:113], off
	v_lshl_add_u64 v[112:113], s[16:17], 0, v[192:193]
	s_add_i32 m0, s29, 0xe000
	s_nop 0
	global_load_lds_dwordx4 v[112:113], off
	s_waitcnt vmcnt(8)
	s_waitcnt lgkmcnt(0)
	s_barrier
	s_setprio 1
	s_waitcnt lgkmcnt(0)
	v_mfma_f32_16x16x32_bf16 v[158:161], v[118:121], v[162:165], 0
	v_mfma_f32_16x16x32_bf16 v[60:63], v[126:129], v[162:165], 0
	v_mfma_f32_16x16x32_bf16 v[154:157], v[118:121], v[170:173], 0
	v_mfma_f32_16x16x32_bf16 v[52:55], v[126:129], v[170:173], 0
	v_mfma_f32_16x16x32_bf16 v[112:115], v[118:121], v[198:201], 0
	v_mfma_f32_16x16x32_bf16 v[44:47], v[126:129], v[198:201], 0
	v_mfma_f32_16x16x32_bf16 v[100:103], v[118:121], v[206:209], 0
	v_mfma_f32_16x16x32_bf16 v[36:39], v[126:129], v[206:209], 0
	v_mfma_f32_16x16x32_bf16 v[158:161], v[122:125], v[166:169], v[158:161]
	v_mfma_f32_16x16x32_bf16 v[60:63], v[130:133], v[166:169], v[60:63]
	v_mfma_f32_16x16x32_bf16 v[154:157], v[122:125], v[174:177], v[154:157]
	v_mfma_f32_16x16x32_bf16 v[52:55], v[130:133], v[174:177], v[52:55]
	v_mfma_f32_16x16x32_bf16 v[112:115], v[122:125], v[202:205], v[112:115]
	v_mfma_f32_16x16x32_bf16 v[44:47], v[130:133], v[202:205], v[44:47]
	v_mfma_f32_16x16x32_bf16 v[100:103], v[122:125], v[228:231], v[100:103]
	v_mfma_f32_16x16x32_bf16 v[36:39], v[130:133], v[228:231], v[36:39]
	s_setprio 0
	s_setprio 1
	v_mfma_f32_16x16x32_bf16 v[108:111], v[134:137], v[162:165], 0
	v_mfma_f32_16x16x32_bf16 v[56:59], v[142:145], v[162:165], 0
	v_mfma_f32_16x16x32_bf16 v[150:153], v[134:137], v[170:173], 0
	v_mfma_f32_16x16x32_bf16 v[48:51], v[142:145], v[170:173], 0
	v_mfma_f32_16x16x32_bf16 v[104:107], v[134:137], v[198:201], 0
	v_mfma_f32_16x16x32_bf16 v[40:43], v[142:145], v[198:201], 0
	v_mfma_f32_16x16x32_bf16 v[96:99], v[134:137], v[206:209], 0
	v_mfma_f32_16x16x32_bf16 v[32:35], v[142:145], v[206:209], 0
	v_mfma_f32_16x16x32_bf16 v[108:111], v[138:141], v[166:169], v[108:111]
	v_mfma_f32_16x16x32_bf16 v[56:59], v[146:149], v[166:169], v[56:59]
	v_mfma_f32_16x16x32_bf16 v[150:153], v[138:141], v[174:177], v[150:153]
	v_mfma_f32_16x16x32_bf16 v[48:51], v[146:149], v[174:177], v[48:51]
	v_mfma_f32_16x16x32_bf16 v[104:107], v[138:141], v[202:205], v[104:107]
	v_mfma_f32_16x16x32_bf16 v[40:43], v[146:149], v[202:205], v[40:43]
	v_mfma_f32_16x16x32_bf16 v[96:99], v[138:141], v[228:231], v[96:99]
	v_mfma_f32_16x16x32_bf16 v[32:35], v[146:149], v[228:231], v[32:35]
	s_setprio 0
	s_barrier
	s_add_i32 vcc_lo, s31, s28
	v_lshl_add_u64 v[210:211], s[18:19], 0, v[180:181]
	s_mov_b32 m0, vcc_lo
	ds_read_b128 v[162:165], v227 offset:16384
	ds_read_b128 v[166:169], v227 offset:17408
	ds_read_b128 v[170:173], v227 offset:18432
	ds_read_b128 v[174:177], v227 offset:19456
	ds_read_b128 v[198:201], v227 offset:20480
	ds_read_b128 v[202:205], v227 offset:21504
	ds_read_b128 v[206:209], v227 offset:22528
	ds_read_b128 v[228:231], v227 offset:23552
	global_load_lds_dwordx4 v[210:211], off
	s_add_i32 m0, vcc_lo, 0x2000
	s_add_u32 vcc_lo, s18, 0x80000
	v_lshl_add_u64 v[232:233], s[18:19], 0, v[184:185]
	s_addc_u32 vcc_hi, s19, 0
	s_add_i32 s22, s74, s28
	global_load_lds_dwordx4 v[232:233], off
	v_lshl_add_u64 v[116:117], vcc, 0, v[180:181]
	s_mov_b32 m0, s22
	v_lshl_add_u64 v[234:235], s[20:21], 0, v[178:179]
	global_load_lds_dwordx4 v[116:117], off
	v_lshl_add_u64 v[116:117], vcc, 0, v[184:185]
	s_add_i32 m0, s22, 0x2000
	v_lshl_add_u64 v[236:237], s[20:21], 0, v[182:183]
	global_load_lds_dwordx4 v[116:117], off
	s_mov_b32 m0, s29
	s_nop 0
	global_load_lds_dwordx4 v[234:235], off
	s_mov_b32 m0, s85
	s_nop 0
	global_load_lds_dwordx4 v[236:237], off
	s_waitcnt vmcnt(8)
	s_waitcnt lgkmcnt(0)
	s_barrier
; #define PG8_STAGE(bufoff, gbase, voff) do { _Pragma("unroll") for (int _i = 0; _i < 2; ++_i) \
;         __builtin_amdgcn_global_load_lds((const unsigned*)((const char*)(gbase) + (voff)[_i]), (PG8_LAS unsigned*)(lds + (bufoff) + ldsw + _i * 8192), 16, 0, 0); } while (0)
; #define PG8_LDA(dst, b, h) do { _Pragma("unroll") for (int m = 0; m < 4; ++m) _Pragma("unroll") for (int k = 0; k < 2; ++k) dst[m][k] = *(const PG8_LAS bf16x8*)(lds + PG8_SA(b, h) + aoff + m * 2048 + k * 1024); } while (0)
; #define PG8_LDB(dst, b, h) do { _Pragma("unroll") for (int n = 0; n < 2; ++n) _Pragma("unroll") for (int k = 0; k < 2; ++k) dst[n][k] = *(const PG8_LAS bf16x8*)(lds + PG8_SB(b, h) + boff + n * 2048 + k * 1024); } while (0)
; #define PG8_MMA(ai, bj, At, Bt) do { __builtin_amdgcn_s_setprio(1); _Pragma("unroll") for (int m = 0; m < 4; ++m) _Pragma("unroll") for (int n = 0; n < 2; ++n) _Pragma("unroll") for (int k = 0; k < 2; ++k) \
;         acc[ai][bj][m][n] = __builtin_amdgcn_mfma_f32_16x16x32_bf16(Bt[n][k], At[m][k], acc[ai][bj][m][n], 0, 0, 0); __builtin_amdgcn_s_setprio(0); } while (0)
; #define PG8_BAR __builtin_amdgcn_s_barrier()
; template <class Epi, class Sched, bool ALIGN_EPI = false, bool SP2 = false>
; __device__ __forceinline__ void gemm_phase(PG8_LAS unsigned char* lds, const Gemm g, const Sched& S, const Epi& E) {
;     ...
;             if constexpr (SP2) {
;             PG8_LDB(B0, 0, 0); PG8_LDB(B1, 0, 1); PG8_SCHED; PG8_LDA(At, 0, 0); PG8_STAGE(PG8_SA(1, 1), a1 + hstep, voffA);
;             PG8_WAIT_V(8); PG8_WAIT_L(0); PG8_BAR; PG8_MMA(0, 0, At, B0); PG8_MMA(0, 1, At, B1); PG8_BAR; PG8_SCHED;
;             PG8_LDA(At, 0, 1); PG8_STAGE(PG8_SB(0, 0), b2, voffB); PG8_STAGE(PG8_SB(0, 1), b2 + hstep, voffB); PG8_STAGE(PG8_SA(0, 0), a2, voffA);
;             PG8_WAIT_V(8); PG8_WAIT_L(0); PG8_BAR; PG8_MMA(1, 0, At, B0); PG8_MMA(1, 1, At, B1); PG8_BAR; PG8_SCHED;
;             PG8_LDB(B0, 1, 0); PG8_LDB(B1, 1, 1); PG8_SCHED; PG8_LDA(At, 1, 0); PG8_STAGE(PG8_SA(0, 1), a2 + hstep, voffA);
;             PG8_WAIT_V(8); PG8_WAIT_L(0); PG8_BAR; PG8_MMA(0, 0, At, B0); PG8_MMA(0, 1, At, B1); PG8_BAR; PG8_SCHED;
;             PG8_LDA(At, 1, 1); PG8_STAGE(PG8_SB(1, 0), b3, voffB); PG8_STAGE(PG8_SB(1, 1), b3 + hstep, voffB); PG8_STAGE(PG8_SA(1, 0), a3, voffA);
;             PG8_WAIT_V(8); PG8_WAIT_L(0); PG8_BAR; PG8_MMA(1, 0, At, B0); PG8_MMA(1, 1, At, B1); PG8_BAR; PG8_SCHED;
	s_setprio 1
	s_waitcnt lgkmcnt(0)
	v_mfma_f32_16x16x32_bf16 v[92:95], v[118:121], v[162:165], 0
	v_mfma_f32_16x16x32_bf16 v[28:31], v[126:129], v[162:165], 0
	v_mfma_f32_16x16x32_bf16 v[84:87], v[118:121], v[170:173], 0
	v_mfma_f32_16x16x32_bf16 v[20:23], v[126:129], v[170:173], 0
	v_mfma_f32_16x16x32_bf16 v[76:79], v[118:121], v[198:201], 0
	v_mfma_f32_16x16x32_bf16 v[12:15], v[126:129], v[198:201], 0
	v_mfma_f32_16x16x32_bf16 v[68:71], v[118:121], v[206:209], 0
	v_mfma_f32_16x16x32_bf16 v[4:7], v[126:129], v[206:209], 0
	v_mfma_f32_16x16x32_bf16 v[92:95], v[122:125], v[166:169], v[92:95]
	v_mfma_f32_16x16x32_bf16 v[28:31], v[130:133], v[166:169], v[28:31]
	v_mfma_f32_16x16x32_bf16 v[84:87], v[122:125], v[174:177], v[84:87]
	v_mfma_f32_16x16x32_bf16 v[20:23], v[130:133], v[174:177], v[20:23]
	v_mfma_f32_16x16x32_bf16 v[76:79], v[122:125], v[202:205], v[76:79]
	v_mfma_f32_16x16x32_bf16 v[12:15], v[130:133], v[202:205], v[12:15]
	v_mfma_f32_16x16x32_bf16 v[68:71], v[122:125], v[228:231], v[68:71]
	v_mfma_f32_16x16x32_bf16 v[4:7], v[130:133], v[228:231], v[4:7]
	s_setprio 0
	s_setprio 1
	v_mfma_f32_16x16x32_bf16 v[88:91], v[134:137], v[162:165], 0
	v_mfma_f32_16x16x32_bf16 v[24:27], v[142:145], v[162:165], 0
	v_mfma_f32_16x16x32_bf16 v[80:83], v[134:137], v[170:173], 0
	v_mfma_f32_16x16x32_bf16 v[16:19], v[142:145], v[170:173], 0
	v_mfma_f32_16x16x32_bf16 v[72:75], v[134:137], v[198:201], 0
	v_mfma_f32_16x16x32_bf16 v[8:11], v[142:145], v[198:201], 0
	v_mfma_f32_16x16x32_bf16 v[64:67], v[134:137], v[206:209], 0
	v_mfma_f32_16x16x32_bf16 v[0:3], v[142:145], v[206:209], 0
	v_mfma_f32_16x16x32_bf16 v[88:91], v[138:141], v[166:169], v[88:91]
	v_mfma_f32_16x16x32_bf16 v[24:27], v[146:149], v[166:169], v[24:27]
	v_mfma_f32_16x16x32_bf16 v[80:83], v[138:141], v[174:177], v[80:83]
	v_mfma_f32_16x16x32_bf16 v[16:19], v[146:149], v[174:177], v[16:19]
	v_mfma_f32_16x16x32_bf16 v[72:75], v[138:141], v[202:205], v[72:75]
	v_mfma_f32_16x16x32_bf16 v[8:11], v[146:149], v[202:205], v[8:11]
	v_mfma_f32_16x16x32_bf16 v[64:67], v[138:141], v[228:231], v[64:67]
	v_mfma_f32_16x16x32_bf16 v[0:3], v[146:149], v[228:231], v[0:3]
	s_setprio 0
	s_barrier
	v_add_u32_e32 v116, s75, v214
	ds_read_b128 v[118:121], v116
	ds_read_b128 v[122:125], v116 offset:1024
	ds_read_b128 v[126:129], v116 offset:2048
	ds_read_b128 v[130:133], v116 offset:3072
	v_add_u32_e32 v116, s84, v214
	ds_read_b128 v[134:137], v116
	ds_read_b128 v[138:141], v116 offset:1024
	ds_read_b128 v[142:145], v116 offset:2048
	ds_read_b128 v[146:149], v116 offset:3072
	s_add_u32 s20, s20, 0x80000
	s_addc_u32 s21, s21, 0
	s_mov_b32 m0, s95
	v_lshl_add_u64 v[116:117], s[20:21], 0, v[178:179]
	ds_read_b128 v[162:165], v227 offset:32768
	ds_read_b128 v[166:169], v227 offset:33792
	ds_read_b128 v[170:173], v227 offset:34816
	ds_read_b128 v[174:177], v227 offset:35840
	ds_read_b128 v[198:201], v227 offset:36864
	ds_read_b128 v[202:205], v227 offset:37888
	ds_read_b128 v[206:209], v227 offset:38912
	ds_read_b128 v[228:231], v227 offset:39936
	global_load_lds_dwordx4 v[116:117], off
	v_lshl_add_u64 v[116:117], s[20:21], 0, v[182:183]
	s_mov_b32 m0, s2
	s_nop 0
	global_load_lds_dwordx4 v[116:117], off
	s_waitcnt vmcnt(8)
	s_waitcnt lgkmcnt(0)
	s_barrier
	s_setprio 1
	s_waitcnt lgkmcnt(0)
	v_mfma_f32_16x16x32_bf16 v[158:161], v[118:121], v[162:165], v[158:161]
	v_mfma_f32_16x16x32_bf16 v[60:63], v[126:129], v[162:165], v[60:63]
	v_mfma_f32_16x16x32_bf16 v[154:157], v[118:121], v[170:173], v[154:157]
	v_mfma_f32_16x16x32_bf16 v[52:55], v[126:129], v[170:173], v[52:55]
	v_mfma_f32_16x16x32_bf16 v[112:115], v[118:121], v[198:201], v[112:115]
	v_mfma_f32_16x16x32_bf16 v[44:47], v[126:129], v[198:201], v[44:47]
	v_mfma_f32_16x16x32_bf16 v[100:103], v[118:121], v[206:209], v[100:103]
	v_mfma_f32_16x16x32_bf16 v[36:39], v[126:129], v[206:209], v[36:39]
	v_mfma_f32_16x16x32_bf16 v[158:161], v[122:125], v[166:169], v[158:161]
	v_mfma_f32_16x16x32_bf16 v[60:63], v[130:133], v[166:169], v[60:63]
	v_mfma_f32_16x16x32_bf16 v[154:157], v[122:125], v[174:177], v[154:157]
	v_mfma_f32_16x16x32_bf16 v[52:55], v[130:133], v[174:177], v[52:55]
	v_mfma_f32_16x16x32_bf16 v[114:117], v[122:125], v[202:205], v[112:115]
	v_mfma_f32_16x16x32_bf16 v[44:47], v[130:133], v[202:205], v[44:47]
	v_mfma_f32_16x16x32_bf16 v[100:103], v[122:125], v[228:231], v[100:103]
	v_mfma_f32_16x16x32_bf16 v[36:39], v[130:133], v[228:231], v[36:39]
	s_setprio 0
	s_setprio 1
	v_mfma_f32_16x16x32_bf16 v[108:111], v[134:137], v[162:165], v[108:111]
	v_mfma_f32_16x16x32_bf16 v[56:59], v[142:145], v[162:165], v[56:59]
	v_mfma_f32_16x16x32_bf16 v[150:153], v[134:137], v[170:173], v[150:153]
	v_mfma_f32_16x16x32_bf16 v[48:51], v[142:145], v[170:173], v[48:51]
	v_mfma_f32_16x16x32_bf16 v[104:107], v[134:137], v[198:201], v[104:107]
	v_mfma_f32_16x16x32_bf16 v[40:43], v[142:145], v[198:201], v[40:43]
	v_mfma_f32_16x16x32_bf16 v[96:99], v[134:137], v[206:209], v[96:99]
	v_mfma_f32_16x16x32_bf16 v[32:35], v[142:145], v[206:209], v[32:35]
	v_mfma_f32_16x16x32_bf16 v[108:111], v[138:141], v[166:169], v[108:111]
	v_mfma_f32_16x16x32_bf16 v[56:59], v[146:149], v[166:169], v[56:59]
	v_mfma_f32_16x16x32_bf16 v[150:153], v[138:141], v[174:177], v[150:153]
	v_mfma_f32_16x16x32_bf16 v[48:51], v[146:149], v[174:177], v[48:51]
	v_mfma_f32_16x16x32_bf16 v[104:107], v[138:141], v[202:205], v[104:107]
	v_mfma_f32_16x16x32_bf16 v[40:43], v[146:149], v[202:205], v[40:43]
	v_mfma_f32_16x16x32_bf16 v[96:99], v[138:141], v[228:231], v[96:99]
	v_mfma_f32_16x16x32_bf16 v[32:35], v[146:149], v[228:231], v[32:35]
	s_setprio 0
	s_barrier
; #define PG8_STAGE(bufoff, gbase, voff) do { _Pragma("unroll") for (int _i = 0; _i < 2; ++_i) \
;         __builtin_amdgcn_global_load_lds((const unsigned*)((const char*)(gbase) + (voff)[_i]), (PG8_LAS unsigned*)(lds + (bufoff) + ldsw + _i * 8192), 16, 0, 0); } while (0)
; #define PG8_LDA(dst, b, h) do { _Pragma("unroll") for (int m = 0; m < 4; ++m) _Pragma("unroll") for (int k = 0; k < 2; ++k) dst[m][k] = *(const PG8_LAS bf16x8*)(lds + PG8_SA(b, h) + aoff + m * 2048 + k * 1024); } while (0)
; #define PG8_LDB(dst, b, h) do { _Pragma("unroll") for (int n = 0; n < 2; ++n) _Pragma("unroll") for (int k = 0; k < 2; ++k) dst[n][k] = *(const PG8_LAS bf16x8*)(lds + PG8_SB(b, h) + boff + n * 2048 + k * 1024); } while (0)
; #define PG8_MMA(ai, bj, At, Bt) do { __builtin_amdgcn_s_setprio(1); _Pragma("unroll") for (int m = 0; m < 4; ++m) _Pragma("unroll") for (int n = 0; n < 2; ++n) _Pragma("unroll") for (int k = 0; k < 2; ++k) \
;         acc[ai][bj][m][n] = __builtin_amdgcn_mfma_f32_16x16x32_bf16(Bt[n][k], At[m][k], acc[ai][bj][m][n], 0, 0, 0); __builtin_amdgcn_s_setprio(0); } while (0)
; #define PG8_BAR __builtin_amdgcn_s_barrier()
; template <class Epi, class Sched, bool ALIGN_EPI = false, bool SP2 = false>
; __device__ __forceinline__ void gemm_phase(PG8_LAS unsigned char* lds, const Gemm g, const Sched& S, const Epi& E) {
;     ...
;             if constexpr (SP2) {
;             PG8_LDB(B0, 0, 0); PG8_LDB(B1, 0, 1); PG8_SCHED; PG8_LDA(At, 0, 0); PG8_STAGE(PG8_SA(1, 1), a1 + hstep, voffA);
;             PG8_WAIT_V(8); PG8_WAIT_L(0); PG8_BAR; PG8_MMA(0, 0, At, B0); PG8_MMA(0, 1, At, B1); PG8_BAR; PG8_SCHED;
;             PG8_LDA(At, 0, 1); PG8_STAGE(PG8_SB(0, 0), b2, voffB); PG8_STAGE(PG8_SB(0, 1), b2 + hstep, voffB); PG8_STAGE(PG8_SA(0, 0), a2, voffA);
;             PG8_WAIT_V(8); PG8_WAIT_L(0); PG8_BAR; PG8_MMA(1, 0, At, B0); PG8_MMA(1, 1, At, B1); PG8_BAR; PG8_SCHED;
;             PG8_LDB(B0, 1, 0); PG8_LDB(B1, 1, 1); PG8_SCHED; PG8_LDA(At, 1, 0); PG8_STAGE(PG8_SA(0, 1), a2 + hstep, voffA);
;             PG8_WAIT_V(8); PG8_WAIT_L(0); PG8_BAR; PG8_MMA(0, 0, At, B0); PG8_MMA(0, 1, At, B1); PG8_BAR; PG8_SCHED;
;             PG8_LDA(At, 1, 1); PG8_STAGE(PG8_SB(1, 0), b3, voffB); PG8_STAGE(PG8_SB(1, 1), b3 + hstep, voffB); PG8_STAGE(PG8_SA(1, 0), a3, voffA);
;             PG8_WAIT_V(8); PG8_WAIT_L(0); PG8_BAR; PG8_MMA(1, 0, At, B0); PG8_MMA(1, 1, At, B1); PG8_BAR; PG8_SCHED;
	s_add_i32 s20, s75, s28
	v_lshl_add_u64 v[112:113], v[210:211], 0, s[46:47]
	s_mov_b32 m0, s20
	ds_read_b128 v[162:165], v227 offset:49152
	ds_read_b128 v[166:169], v227 offset:50176
	ds_read_b128 v[170:173], v227 offset:51200
	ds_read_b128 v[174:177], v227 offset:52224
	ds_read_b128 v[198:201], v227 offset:53248
	ds_read_b128 v[202:205], v227 offset:54272
	ds_read_b128 v[206:209], v227 offset:55296
	ds_read_b128 v[228:231], v227 offset:56320
	global_load_lds_dwordx4 v[112:113], off
	s_add_i32 m0, s20, 0x2000
	s_add_u32 s18, s18, 0x80080
	v_lshl_add_u64 v[112:113], v[232:233], 0, s[46:47]
	s_addc_u32 s19, s19, 0
	s_add_i32 s20, s84, s28
	global_load_lds_dwordx4 v[112:113], off
	v_lshl_add_u64 v[112:113], s[18:19], 0, v[180:181]
	s_mov_b32 m0, s20
	s_nop 0
	global_load_lds_dwordx4 v[112:113], off
	v_lshl_add_u64 v[112:113], s[18:19], 0, v[184:185]
	s_add_i32 m0, s20, 0x2000
	s_nop 0
	global_load_lds_dwordx4 v[112:113], off
	v_lshl_add_u64 v[112:113], v[234:235], 0, s[46:47]
	s_mov_b32 m0, s30
	s_nop 0
	global_load_lds_dwordx4 v[112:113], off
	v_lshl_add_u64 v[112:113], v[236:237], 0, s[46:47]
	s_mov_b32 m0, s23
	s_nop 0
	global_load_lds_dwordx4 v[112:113], off
	s_waitcnt vmcnt(8)
	s_waitcnt lgkmcnt(0)
	s_barrier
	s_setprio 1
	s_waitcnt lgkmcnt(0)
	v_mfma_f32_16x16x32_bf16 v[92:95], v[118:121], v[162:165], v[92:95]
	v_mfma_f32_16x16x32_bf16 v[28:31], v[126:129], v[162:165], v[28:31]
	v_mfma_f32_16x16x32_bf16 v[84:87], v[118:121], v[170:173], v[84:87]
	v_mfma_f32_16x16x32_bf16 v[20:23], v[126:129], v[170:173], v[20:23]
	v_mfma_f32_16x16x32_bf16 v[76:79], v[118:121], v[198:201], v[76:79]
	v_mfma_f32_16x16x32_bf16 v[12:15], v[126:129], v[198:201], v[12:15]
	v_mfma_f32_16x16x32_bf16 v[68:71], v[118:121], v[206:209], v[68:71]
	v_mfma_f32_16x16x32_bf16 v[4:7], v[126:129], v[206:209], v[4:7]
	v_mfma_f32_16x16x32_bf16 v[92:95], v[122:125], v[166:169], v[92:95]
	v_mfma_f32_16x16x32_bf16 v[28:31], v[130:133], v[166:169], v[28:31]
	v_mfma_f32_16x16x32_bf16 v[84:87], v[122:125], v[174:177], v[84:87]
	v_mfma_f32_16x16x32_bf16 v[20:23], v[130:133], v[174:177], v[20:23]
	v_mfma_f32_16x16x32_bf16 v[76:79], v[122:125], v[202:205], v[76:79]
	v_mfma_f32_16x16x32_bf16 v[12:15], v[130:133], v[202:205], v[12:15]
	v_mfma_f32_16x16x32_bf16 v[68:71], v[122:125], v[228:231], v[68:71]
	v_mfma_f32_16x16x32_bf16 v[4:7], v[130:133], v[228:231], v[4:7]
	s_setprio 0
	s_setprio 1
	v_mfma_f32_16x16x32_bf16 v[88:91], v[134:137], v[162:165], v[88:91]
	v_mfma_f32_16x16x32_bf16 v[24:27], v[142:145], v[162:165], v[24:27]
	v_mfma_f32_16x16x32_bf16 v[80:83], v[134:137], v[170:173], v[80:83]
	v_mfma_f32_16x16x32_bf16 v[16:19], v[142:145], v[170:173], v[16:19]
	v_mfma_f32_16x16x32_bf16 v[72:75], v[134:137], v[198:201], v[72:75]
	v_mfma_f32_16x16x32_bf16 v[8:11], v[142:145], v[198:201], v[8:11]
	v_mfma_f32_16x16x32_bf16 v[64:67], v[134:137], v[206:209], v[64:67]
	v_mfma_f32_16x16x32_bf16 v[0:3], v[142:145], v[206:209], v[0:3]
	v_mfma_f32_16x16x32_bf16 v[88:91], v[138:141], v[166:169], v[88:91]
	v_mfma_f32_16x16x32_bf16 v[24:27], v[146:149], v[166:169], v[24:27]
	v_mfma_f32_16x16x32_bf16 v[80:83], v[138:141], v[174:177], v[80:83]
	v_mfma_f32_16x16x32_bf16 v[16:19], v[146:149], v[174:177], v[16:19]
	v_mfma_f32_16x16x32_bf16 v[72:75], v[138:141], v[202:205], v[72:75]
	v_mfma_f32_16x16x32_bf16 v[8:11], v[146:149], v[202:205], v[8:11]
	v_mfma_f32_16x16x32_bf16 v[64:67], v[138:141], v[228:231], v[64:67]
	v_mfma_f32_16x16x32_bf16 v[0:3], v[146:149], v[228:231], v[0:3]
	s_setprio 0
	s_barrier
	s_add_i32 s97, s97, 2
	s_add_u32 s16, s16, 0x100
	s_addc_u32 s17, s17, 0
	s_add_u32 s89, s89, 0x100
	s_addc_u32 s96, s96, 0
	s_cmp_gt_u32 s97, 29

; #define PG8_STAGE(bufoff, gbase, voff) do { _Pragma("unroll") for (int _i = 0; _i < 2; ++_i) \
;         __builtin_amdgcn_global_load_lds((const unsigned*)((const char*)(gbase) + (voff)[_i]), (PG8_LAS unsigned*)(lds + (bufoff) + ldsw + _i * 8192), 16, 0, 0); } while (0)
; #define PG8_LDA(dst, b, h) do { _Pragma("unroll") for (int m = 0; m < 4; ++m) _Pragma("unroll") for (int k = 0; k < 2; ++k) dst[m][k] = *(const PG8_LAS bf16x8*)(lds + PG8_SA(b, h) + aoff + m * 2048 + k * 1024); } while (0)
; #define PG8_LDB(dst, b, h) do { _Pragma("unroll") for (int n = 0; n < 2; ++n) _Pragma("unroll") for (int k = 0; k < 2; ++k) dst[n][k] = *(const PG8_LAS bf16x8*)(lds + PG8_SB(b, h) + boff + n * 2048 + k * 1024); } while (0)
; #define PG8_WAIT_V(n) asm volatile("s_waitcnt vmcnt(" #n ")" ::: "memory")
; #define PG8_BAR __builtin_amdgcn_s_barrier()
; template <class Epi, class Sched, bool ALIGN_EPI = false, bool SP2 = false>
; __device__ __forceinline__ void gemm_phase(PG8_LAS unsigned char* lds, const Gemm g, const Sched& S, const Epi& E) {
;     ...
;             if constexpr (SP2) {
;             PG8_LDB(B0, 0, 0); PG8_LDB(B1, 0, 1); PG8_SCHED; PG8_LDA(At, 0, 0); PG8_STAGE(PG8_SA(1, 1), a1 + hstep, voffA);
;             PG8_WAIT_V(8); PG8_WAIT_L(0); PG8_BAR; PG8_MMA(0, 0, At, B0); PG8_MMA(0, 1, At, B1); PG8_BAR; PG8_SCHED;
;             PG8_LDA(At, 0, 1); PG8_STAGE(PG8_SB(0, 0), b2, voffB); PG8_STAGE(PG8_SB(0, 1), b2 + hstep, voffB); PG8_STAGE(PG8_SA(0, 0), a2, voffA);
;             PG8_WAIT_V(8); PG8_WAIT_L(0); PG8_BAR; PG8_MMA(1, 0, At, B0); PG8_MMA(1, 1, At, B1); PG8_BAR; PG8_SCHED;
;             PG8_LDB(B0, 1, 0); PG8_LDB(B1, 1, 1); PG8_SCHED; PG8_LDA(At, 1, 0); PG8_STAGE(PG8_SA(0, 1), a2 + hstep, voffA);
;             PG8_WAIT_V(8); PG8_WAIT_L(0); PG8_BAR; PG8_MMA(0, 0, At, B0); PG8_MMA(0, 1, At, B1); PG8_BAR; PG8_SCHED;
;             PG8_LDA(At, 1, 1); PG8_STAGE(PG8_SB(1, 0), b3, voffB); PG8_STAGE(PG8_SB(1, 1), b3 + hstep, voffB); PG8_STAGE(PG8_SA(1, 0), a3, voffA);
;             PG8_WAIT_V(8); PG8_WAIT_L(0); PG8_BAR; PG8_MMA(1, 0, At, B0); PG8_MMA(1, 1, At, B1); PG8_BAR; PG8_SCHED;
;     ...
;         for (int a = 0; a < 2; ++a)
; #pragma unroll
;             for (int b = 0; b < 2; ++b)
; #pragma unroll
;                 for (int m = 0; m < 4; ++m)
; #pragma unroll
;                     for (int n = 0; n < 2; ++n) acc[a][b][m][n] = (f32x4){0.f, 0.f, 0.f, 0.f};
.LBB0_1100:
	s_add_u32 s0, s38, 0x100
	s_addc_u32 s1, s39, 0
	s_mov_b32 s59, -2
	ds_read_b128 v[120:123], v169
	ds_read_b128 v[124:127], v169 offset:1024
	ds_read_b128 v[128:131], v169 offset:2048
	ds_read_b128 v[132:135], v169 offset:3072
	ds_read_b128 v[160:163], v170
	ds_read_b128 v[172:175], v170 offset:1024
	ds_read_b128 v[176:179], v170 offset:2048
	ds_read_b128 v[180:183], v170 offset:3072
	s_add_u32 s38, s34, 0x100
	s_addc_u32 s39, s35, 0
	s_cmpk_eq_i32 s59, 0x54
	s_cselect_b32 s43, s5, s39
	s_cselect_b32 s42, s4, s38
	s_cselect_b32 s41, s21, s1
	s_cselect_b32 s40, s20, s0
	v_lshl_add_u64 v[164:165], s[34:35], 0, v[152:153]
	s_add_i32 m0, s28, 0xc000
	ds_read_b128 v[184:187], v171
	ds_read_b128 v[190:193], v171 offset:1024
	ds_read_b128 v[194:197], v171 offset:2048
	ds_read_b128 v[198:201], v171 offset:3072
	ds_read_b128 v[202:205], v171 offset:4096
	ds_read_b128 v[206:209], v171 offset:5120
	ds_read_b128 v[214:217], v171 offset:6144
	ds_read_b128 v[218:221], v171 offset:7168
	global_load_lds_dwordx4 v[164:165], off
	v_lshl_add_u64 v[164:165], s[34:35], 0, v[154:155]
	s_add_i32 m0, s28, 0xe000
	s_nop 0
	global_load_lds_dwordx4 v[164:165], off
	s_waitcnt vmcnt(8)
	s_waitcnt lgkmcnt(0)
	s_barrier
	s_setprio 1
	s_waitcnt lgkmcnt(0)
	v_mfma_f32_16x16x32_bf16 v[140:143], v[120:123], v[184:187], 0
	v_mfma_f32_16x16x32_bf16 v[136:139], v[128:131], v[184:187], 0
	v_mfma_f32_16x16x32_bf16 v[116:119], v[120:123], v[194:197], 0
	v_mfma_f32_16x16x32_bf16 v[104:107], v[128:131], v[194:197], 0
	v_mfma_f32_16x16x32_bf16 v[100:103], v[120:123], v[202:205], 0
	v_mfma_f32_16x16x32_bf16 v[88:91], v[128:131], v[202:205], 0
	v_mfma_f32_16x16x32_bf16 v[84:87], v[120:123], v[214:217], 0
	v_mfma_f32_16x16x32_bf16 v[72:75], v[128:131], v[214:217], 0
	v_mfma_f32_16x16x32_bf16 v[140:143], v[124:127], v[190:193], v[140:143]
	v_mfma_f32_16x16x32_bf16 v[136:139], v[132:135], v[190:193], v[136:139]
	v_mfma_f32_16x16x32_bf16 v[116:119], v[124:127], v[198:201], v[116:119]
	v_mfma_f32_16x16x32_bf16 v[104:107], v[132:135], v[198:201], v[104:107]
	v_mfma_f32_16x16x32_bf16 v[100:103], v[124:127], v[206:209], v[100:103]
	v_mfma_f32_16x16x32_bf16 v[88:91], v[132:135], v[206:209], v[88:91]
	v_mfma_f32_16x16x32_bf16 v[84:87], v[124:127], v[218:221], v[84:87]
	v_mfma_f32_16x16x32_bf16 v[72:75], v[132:135], v[218:221], v[72:75]
	s_setprio 0
	s_setprio 1
	v_mfma_f32_16x16x32_bf16 v[112:115], v[160:163], v[184:187], 0
	v_mfma_f32_16x16x32_bf16 v[108:111], v[176:179], v[184:187], 0
	v_mfma_f32_16x16x32_bf16 v[96:99], v[160:163], v[194:197], 0
	v_mfma_f32_16x16x32_bf16 v[92:95], v[176:179], v[194:197], 0
	v_mfma_f32_16x16x32_bf16 v[80:83], v[160:163], v[202:205], 0
	v_mfma_f32_16x16x32_bf16 v[76:79], v[176:179], v[202:205], 0
	v_mfma_f32_16x16x32_bf16 v[68:71], v[160:163], v[214:217], 0
	v_mfma_f32_16x16x32_bf16 v[64:67], v[176:179], v[214:217], 0
	v_mfma_f32_16x16x32_bf16 v[112:115], v[172:175], v[190:193], v[112:115]
	v_mfma_f32_16x16x32_bf16 v[108:111], v[180:183], v[190:193], v[108:111]
	v_mfma_f32_16x16x32_bf16 v[96:99], v[172:175], v[198:201], v[96:99]
	v_mfma_f32_16x16x32_bf16 v[92:95], v[180:183], v[198:201], v[92:95]
	v_mfma_f32_16x16x32_bf16 v[80:83], v[172:175], v[206:209], v[80:83]
	v_mfma_f32_16x16x32_bf16 v[76:79], v[180:183], v[206:209], v[76:79]
	v_mfma_f32_16x16x32_bf16 v[68:71], v[172:175], v[218:221], v[68:71]
	v_mfma_f32_16x16x32_bf16 v[64:67], v[180:183], v[218:221], v[64:67]
	s_setprio 0
	s_barrier
	s_add_i32 s22, s31, s23
	v_lshl_add_u64 v[164:165], s[40:41], 0, v[146:147]
	s_mov_b32 m0, s22
	ds_read_b128 v[184:187], v171 offset:16384
	ds_read_b128 v[190:193], v171 offset:17408
	ds_read_b128 v[194:197], v171 offset:18432
	ds_read_b128 v[198:201], v171 offset:19456
	ds_read_b128 v[202:205], v171 offset:20480
	ds_read_b128 v[206:209], v171 offset:21504
	ds_read_b128 v[214:217], v171 offset:22528
	ds_read_b128 v[218:221], v171 offset:23552
	global_load_lds_dwordx4 v[164:165], off
	s_add_i32 m0, s22, 0x2000
	s_add_u32 s34, s40, 0x160000
	v_lshl_add_u64 v[210:211], s[40:41], 0, v[150:151]
	s_addc_u32 s35, s41, 0
	s_add_i32 s22, s74, s23
	global_load_lds_dwordx4 v[210:211], off
	v_lshl_add_u64 v[222:223], s[34:35], 0, v[146:147]
	s_mov_b32 m0, s22
	v_lshl_add_u64 v[224:225], s[42:43], 0, v[148:149]
	global_load_lds_dwordx4 v[222:223], off
	v_lshl_add_u64 v[222:223], s[34:35], 0, v[150:151]
	s_add_i32 m0, s22, 0x2000
	s_nop 0
	global_load_lds_dwordx4 v[222:223], off
	v_lshl_add_u64 v[222:223], s[42:43], 0, v[144:145]
	s_mov_b32 m0, s28
	s_nop 0
	global_load_lds_dwordx4 v[222:223], off
	s_mov_b32 m0, s29
	s_nop 0
	global_load_lds_dwordx4 v[224:225], off
	s_waitcnt vmcnt(8)
	s_waitcnt lgkmcnt(0)
	s_barrier
; #define PG8_STAGE(bufoff, gbase, voff) do { _Pragma("unroll") for (int _i = 0; _i < 2; ++_i) \
;         __builtin_amdgcn_global_load_lds((const unsigned*)((const char*)(gbase) + (voff)[_i]), (PG8_LAS unsigned*)(lds + (bufoff) + ldsw + _i * 8192), 16, 0, 0); } while (0)
; #define PG8_LDA(dst, b, h) do { _Pragma("unroll") for (int m = 0; m < 4; ++m) _Pragma("unroll") for (int k = 0; k < 2; ++k) dst[m][k] = *(const PG8_LAS bf16x8*)(lds + PG8_SA(b, h) + aoff + m * 2048 + k * 1024); } while (0)
; #define PG8_LDB(dst, b, h) do { _Pragma("unroll") for (int n = 0; n < 2; ++n) _Pragma("unroll") for (int k = 0; k < 2; ++k) dst[n][k] = *(const PG8_LAS bf16x8*)(lds + PG8_SB(b, h) + boff + n * 2048 + k * 1024); } while (0)
; #define PG8_MMA(ai, bj, At, Bt) do { __builtin_amdgcn_s_setprio(1); _Pragma("unroll") for (int m = 0; m < 4; ++m) _Pragma("unroll") for (int n = 0; n < 2; ++n) _Pragma("unroll") for (int k = 0; k < 2; ++k) \
;         acc[ai][bj][m][n] = __builtin_amdgcn_mfma_f32_16x16x32_bf16(Bt[n][k], At[m][k], acc[ai][bj][m][n], 0, 0, 0); __builtin_amdgcn_s_setprio(0); } while (0)
; #define PG8_BAR __builtin_amdgcn_s_barrier()
; template <class Epi, class Sched, bool ALIGN_EPI = false, bool SP2 = false>
; __device__ __forceinline__ void gemm_phase(PG8_LAS unsigned char* lds, const Gemm g, const Sched& S, const Epi& E) {
;     ...
;             if constexpr (SP2) {
;             PG8_LDB(B0, 0, 0); PG8_LDB(B1, 0, 1); PG8_SCHED; PG8_LDA(At, 0, 0); PG8_STAGE(PG8_SA(1, 1), a1 + hstep, voffA);
;             PG8_WAIT_V(8); PG8_WAIT_L(0); PG8_BAR; PG8_MMA(0, 0, At, B0); PG8_MMA(0, 1, At, B1); PG8_BAR; PG8_SCHED;
;             PG8_LDA(At, 0, 1); PG8_STAGE(PG8_SB(0, 0), b2, voffB); PG8_STAGE(PG8_SB(0, 1), b2 + hstep, voffB); PG8_STAGE(PG8_SA(0, 0), a2, voffA);
;             PG8_WAIT_V(8); PG8_WAIT_L(0); PG8_BAR; PG8_MMA(1, 0, At, B0); PG8_MMA(1, 1, At, B1); PG8_BAR; PG8_SCHED;
;             PG8_LDB(B0, 1, 0); PG8_LDB(B1, 1, 1); PG8_SCHED; PG8_LDA(At, 1, 0); PG8_STAGE(PG8_SA(0, 1), a2 + hstep, voffA);
;             PG8_WAIT_V(8); PG8_WAIT_L(0); PG8_BAR; PG8_MMA(0, 0, At, B0); PG8_MMA(0, 1, At, B1); PG8_BAR; PG8_SCHED;
;             PG8_LDA(At, 1, 1); PG8_STAGE(PG8_SB(1, 0), b3, voffB); PG8_STAGE(PG8_SB(1, 1), b3 + hstep, voffB); PG8_STAGE(PG8_SA(1, 0), a3, voffA);
;             PG8_WAIT_V(8); PG8_WAIT_L(0); PG8_BAR; PG8_MMA(1, 0, At, B0); PG8_MMA(1, 1, At, B1); PG8_BAR; PG8_SCHED;
	s_setprio 1
	s_waitcnt lgkmcnt(0)
	v_mfma_f32_16x16x32_bf16 v[60:63], v[120:123], v[184:187], 0
	v_mfma_f32_16x16x32_bf16 v[56:59], v[128:131], v[184:187], 0
	v_mfma_f32_16x16x32_bf16 v[52:55], v[120:123], v[194:197], 0
	v_mfma_f32_16x16x32_bf16 v[40:43], v[128:131], v[194:197], 0
	v_mfma_f32_16x16x32_bf16 v[36:39], v[120:123], v[202:205], 0
	v_mfma_f32_16x16x32_bf16 v[24:27], v[128:131], v[202:205], 0
	v_mfma_f32_16x16x32_bf16 v[20:23], v[120:123], v[214:217], 0
	v_mfma_f32_16x16x32_bf16 v[8:11], v[128:131], v[214:217], 0
	v_mfma_f32_16x16x32_bf16 v[60:63], v[124:127], v[190:193], v[60:63]
	v_mfma_f32_16x16x32_bf16 v[56:59], v[132:135], v[190:193], v[56:59]
	v_mfma_f32_16x16x32_bf16 v[52:55], v[124:127], v[198:201], v[52:55]
	v_mfma_f32_16x16x32_bf16 v[40:43], v[132:135], v[198:201], v[40:43]
	v_mfma_f32_16x16x32_bf16 v[36:39], v[124:127], v[206:209], v[36:39]
	v_mfma_f32_16x16x32_bf16 v[24:27], v[132:135], v[206:209], v[24:27]
	v_mfma_f32_16x16x32_bf16 v[20:23], v[124:127], v[218:221], v[20:23]
	v_mfma_f32_16x16x32_bf16 v[8:11], v[132:135], v[218:221], v[8:11]
	s_setprio 0
	s_setprio 1
	v_mfma_f32_16x16x32_bf16 v[48:51], v[160:163], v[184:187], 0
	v_mfma_f32_16x16x32_bf16 v[44:47], v[176:179], v[184:187], 0
	v_mfma_f32_16x16x32_bf16 v[32:35], v[160:163], v[194:197], 0
	v_mfma_f32_16x16x32_bf16 v[28:31], v[176:179], v[194:197], 0
	v_mfma_f32_16x16x32_bf16 v[16:19], v[160:163], v[202:205], 0
	v_mfma_f32_16x16x32_bf16 v[12:15], v[176:179], v[202:205], 0
	v_mfma_f32_16x16x32_bf16 v[4:7], v[160:163], v[214:217], 0
	v_mfma_f32_16x16x32_bf16 v[0:3], v[176:179], v[214:217], 0
	v_mfma_f32_16x16x32_bf16 v[48:51], v[172:175], v[190:193], v[48:51]
	v_mfma_f32_16x16x32_bf16 v[44:47], v[180:183], v[190:193], v[44:47]
	v_mfma_f32_16x16x32_bf16 v[32:35], v[172:175], v[198:201], v[32:35]
	v_mfma_f32_16x16x32_bf16 v[28:31], v[180:183], v[198:201], v[28:31]
	v_mfma_f32_16x16x32_bf16 v[16:19], v[172:175], v[206:209], v[16:19]
	v_mfma_f32_16x16x32_bf16 v[12:15], v[180:183], v[206:209], v[12:15]
	v_mfma_f32_16x16x32_bf16 v[4:7], v[172:175], v[218:221], v[4:7]
	v_mfma_f32_16x16x32_bf16 v[0:3], v[180:183], v[218:221], v[0:3]
	s_setprio 0
	s_barrier
	v_add_u32_e32 v132, s75, v167
	v_add_u32_e32 v180, s84, v167
	ds_read_b128 v[120:123], v132
	ds_read_b128 v[124:127], v132 offset:1024
	ds_read_b128 v[128:131], v132 offset:2048
	ds_read_b128 v[132:135], v132 offset:3072
	ds_read_b128 v[160:163], v180
	ds_read_b128 v[172:175], v180 offset:1024
	ds_read_b128 v[176:179], v180 offset:2048
	ds_read_b128 v[180:183], v180 offset:3072
	s_add_u32 s34, s42, 0x160000
	s_addc_u32 s35, s43, 0
	s_mov_b32 m0, s30
	v_lshl_add_u64 v[226:227], s[34:35], 0, v[144:145]
	ds_read_b128 v[184:187], v171 offset:32768
	ds_read_b128 v[190:193], v171 offset:33792
	ds_read_b128 v[194:197], v171 offset:34816
	ds_read_b128 v[198:201], v171 offset:35840
	ds_read_b128 v[202:205], v171 offset:36864
	ds_read_b128 v[206:209], v171 offset:37888
	ds_read_b128 v[214:217], v171 offset:38912
	ds_read_b128 v[218:221], v171 offset:39936
	global_load_lds_dwordx4 v[226:227], off
	v_lshl_add_u64 v[226:227], s[34:35], 0, v[148:149]
	s_mov_b32 m0, s33
	s_nop 0
	global_load_lds_dwordx4 v[226:227], off
	s_waitcnt vmcnt(8)
	s_waitcnt lgkmcnt(0)
	s_barrier
	s_setprio 1
	s_waitcnt lgkmcnt(0)
	v_mfma_f32_16x16x32_bf16 v[140:143], v[120:123], v[184:187], v[140:143]
	v_mfma_f32_16x16x32_bf16 v[136:139], v[128:131], v[184:187], v[136:139]
	v_mfma_f32_16x16x32_bf16 v[116:119], v[120:123], v[194:197], v[116:119]
	v_mfma_f32_16x16x32_bf16 v[104:107], v[128:131], v[194:197], v[104:107]
	v_mfma_f32_16x16x32_bf16 v[100:103], v[120:123], v[202:205], v[100:103]
	v_mfma_f32_16x16x32_bf16 v[88:91], v[128:131], v[202:205], v[88:91]
	v_mfma_f32_16x16x32_bf16 v[84:87], v[120:123], v[214:217], v[84:87]
	v_mfma_f32_16x16x32_bf16 v[72:75], v[128:131], v[214:217], v[72:75]
	v_mfma_f32_16x16x32_bf16 v[140:143], v[124:127], v[190:193], v[140:143]
	v_mfma_f32_16x16x32_bf16 v[136:139], v[132:135], v[190:193], v[136:139]
	v_mfma_f32_16x16x32_bf16 v[116:119], v[124:127], v[198:201], v[116:119]
	v_mfma_f32_16x16x32_bf16 v[104:107], v[132:135], v[198:201], v[104:107]
	v_mfma_f32_16x16x32_bf16 v[100:103], v[124:127], v[206:209], v[100:103]
	v_mfma_f32_16x16x32_bf16 v[88:91], v[132:135], v[206:209], v[88:91]
	v_mfma_f32_16x16x32_bf16 v[84:87], v[124:127], v[218:221], v[84:87]
	v_mfma_f32_16x16x32_bf16 v[72:75], v[132:135], v[218:221], v[72:75]
	s_setprio 0
	s_setprio 1
	v_mfma_f32_16x16x32_bf16 v[112:115], v[160:163], v[184:187], v[112:115]
	v_mfma_f32_16x16x32_bf16 v[108:111], v[176:179], v[184:187], v[108:111]
	v_mfma_f32_16x16x32_bf16 v[96:99], v[160:163], v[194:197], v[96:99]
	v_mfma_f32_16x16x32_bf16 v[92:95], v[176:179], v[194:197], v[92:95]
	v_mfma_f32_16x16x32_bf16 v[80:83], v[160:163], v[202:205], v[80:83]
	v_mfma_f32_16x16x32_bf16 v[76:79], v[176:179], v[202:205], v[76:79]
	v_mfma_f32_16x16x32_bf16 v[68:71], v[160:163], v[214:217], v[68:71]
	v_mfma_f32_16x16x32_bf16 v[64:67], v[176:179], v[214:217], v[64:67]
	v_mfma_f32_16x16x32_bf16 v[112:115], v[172:175], v[190:193], v[112:115]
	v_mfma_f32_16x16x32_bf16 v[108:111], v[180:183], v[190:193], v[108:111]
	v_mfma_f32_16x16x32_bf16 v[96:99], v[172:175], v[198:201], v[96:99]
	v_mfma_f32_16x16x32_bf16 v[92:95], v[180:183], v[198:201], v[92:95]
	v_mfma_f32_16x16x32_bf16 v[80:83], v[172:175], v[206:209], v[80:83]
	v_mfma_f32_16x16x32_bf16 v[76:79], v[180:183], v[206:209], v[76:79]
	v_mfma_f32_16x16x32_bf16 v[68:71], v[172:175], v[218:221], v[68:71]
	v_mfma_f32_16x16x32_bf16 v[64:67], v[180:183], v[218:221], v[64:67]
	s_setprio 0
	s_barrier
; #define PG8_STAGE(bufoff, gbase, voff) do { _Pragma("unroll") for (int _i = 0; _i < 2; ++_i) \
;         __builtin_amdgcn_global_load_lds((const unsigned*)((const char*)(gbase) + (voff)[_i]), (PG8_LAS unsigned*)(lds + (bufoff) + ldsw + _i * 8192), 16, 0, 0); } while (0)
; #define PG8_LDA(dst, b, h) do { _Pragma("unroll") for (int m = 0; m < 4; ++m) _Pragma("unroll") for (int k = 0; k < 2; ++k) dst[m][k] = *(const PG8_LAS bf16x8*)(lds + PG8_SA(b, h) + aoff + m * 2048 + k * 1024); } while (0)
; #define PG8_LDB(dst, b, h) do { _Pragma("unroll") for (int n = 0; n < 2; ++n) _Pragma("unroll") for (int k = 0; k < 2; ++k) dst[n][k] = *(const PG8_LAS bf16x8*)(lds + PG8_SB(b, h) + boff + n * 2048 + k * 1024); } while (0)
; #define PG8_MMA(ai, bj, At, Bt) do { __builtin_amdgcn_s_setprio(1); _Pragma("unroll") for (int m = 0; m < 4; ++m) _Pragma("unroll") for (int n = 0; n < 2; ++n) _Pragma("unroll") for (int k = 0; k < 2; ++k) \
;         acc[ai][bj][m][n] = __builtin_amdgcn_mfma_f32_16x16x32_bf16(Bt[n][k], At[m][k], acc[ai][bj][m][n], 0, 0, 0); __builtin_amdgcn_s_setprio(0); } while (0)
; #define PG8_BAR __builtin_amdgcn_s_barrier()
; template <class Epi, class Sched, bool ALIGN_EPI = false, bool SP2 = false>
; __device__ __forceinline__ void gemm_phase(PG8_LAS unsigned char* lds, const Gemm g, const Sched& S, const Epi& E) {
;     ...
;             if constexpr (SP2) {
;             PG8_LDB(B0, 0, 0); PG8_LDB(B1, 0, 1); PG8_SCHED; PG8_LDA(At, 0, 0); PG8_STAGE(PG8_SA(1, 1), a1 + hstep, voffA);
;             PG8_WAIT_V(8); PG8_WAIT_L(0); PG8_BAR; PG8_MMA(0, 0, At, B0); PG8_MMA(0, 1, At, B1); PG8_BAR; PG8_SCHED;
;             PG8_LDA(At, 0, 1); PG8_STAGE(PG8_SB(0, 0), b2, voffB); PG8_STAGE(PG8_SB(0, 1), b2 + hstep, voffB); PG8_STAGE(PG8_SA(0, 0), a2, voffA);
;             PG8_WAIT_V(8); PG8_WAIT_L(0); PG8_BAR; PG8_MMA(1, 0, At, B0); PG8_MMA(1, 1, At, B1); PG8_BAR; PG8_SCHED;
;             PG8_LDB(B0, 1, 0); PG8_LDB(B1, 1, 1); PG8_SCHED; PG8_LDA(At, 1, 0); PG8_STAGE(PG8_SA(0, 1), a2 + hstep, voffA);
;             PG8_WAIT_V(8); PG8_WAIT_L(0); PG8_BAR; PG8_MMA(0, 0, At, B0); PG8_MMA(0, 1, At, B1); PG8_BAR; PG8_SCHED;
;             PG8_LDA(At, 1, 1); PG8_STAGE(PG8_SB(1, 0), b3, voffB); PG8_STAGE(PG8_SB(1, 1), b3 + hstep, voffB); PG8_STAGE(PG8_SA(1, 0), a3, voffA);
;             PG8_WAIT_V(8); PG8_WAIT_L(0); PG8_BAR; PG8_MMA(1, 0, At, B0); PG8_MMA(1, 1, At, B1); PG8_BAR; PG8_SCHED;
	s_add_i32 s22, s75, s23
	v_lshl_add_u64 v[164:165], v[164:165], 0, s[8:9]
	s_mov_b32 m0, s22
	ds_read_b128 v[184:187], v171 offset:49152
	ds_read_b128 v[190:193], v171 offset:50176
	ds_read_b128 v[194:197], v171 offset:51200
	ds_read_b128 v[198:201], v171 offset:52224
	ds_read_b128 v[202:205], v171 offset:53248
	ds_read_b128 v[206:209], v171 offset:54272
	ds_read_b128 v[214:217], v171 offset:55296
	ds_read_b128 v[218:221], v171 offset:56320
	global_load_lds_dwordx4 v[164:165], off
	s_add_i32 m0, s22, 0x2000
	s_add_u32 s34, s40, 0x160080
	v_lshl_add_u64 v[164:165], v[210:211], 0, s[8:9]
	s_addc_u32 s35, s41, 0
	s_add_i32 s22, s84, s23
	global_load_lds_dwordx4 v[164:165], off
	v_lshl_add_u64 v[164:165], s[34:35], 0, v[146:147]
	s_mov_b32 m0, s22
	s_nop 0
	global_load_lds_dwordx4 v[164:165], off
	v_lshl_add_u64 v[164:165], s[34:35], 0, v[150:151]
	s_add_i32 m0, s22, 0x2000
	s_nop 0
	global_load_lds_dwordx4 v[164:165], off
	v_lshl_add_u64 v[164:165], v[222:223], 0, s[8:9]
	s_mov_b32 m0, s47
	s_nop 0
	global_load_lds_dwordx4 v[164:165], off
	v_lshl_add_u64 v[164:165], v[224:225], 0, s[8:9]
	s_mov_b32 m0, s52
	s_nop 0
	global_load_lds_dwordx4 v[164:165], off
	s_waitcnt vmcnt(8)
	s_waitcnt lgkmcnt(0)
	s_barrier
	s_setprio 1
	s_waitcnt lgkmcnt(0)
	v_mfma_f32_16x16x32_bf16 v[60:63], v[120:123], v[184:187], v[60:63]
	v_mfma_f32_16x16x32_bf16 v[56:59], v[128:131], v[184:187], v[56:59]
	v_mfma_f32_16x16x32_bf16 v[52:55], v[120:123], v[194:197], v[52:55]
	v_mfma_f32_16x16x32_bf16 v[40:43], v[128:131], v[194:197], v[40:43]
	v_mfma_f32_16x16x32_bf16 v[36:39], v[120:123], v[202:205], v[36:39]
	v_mfma_f32_16x16x32_bf16 v[24:27], v[128:131], v[202:205], v[24:27]
	v_mfma_f32_16x16x32_bf16 v[20:23], v[120:123], v[214:217], v[20:23]
	v_mfma_f32_16x16x32_bf16 v[8:11], v[128:131], v[214:217], v[8:11]
	v_mfma_f32_16x16x32_bf16 v[60:63], v[124:127], v[190:193], v[60:63]
	v_mfma_f32_16x16x32_bf16 v[56:59], v[132:135], v[190:193], v[56:59]
	v_mfma_f32_16x16x32_bf16 v[52:55], v[124:127], v[198:201], v[52:55]
	v_mfma_f32_16x16x32_bf16 v[40:43], v[132:135], v[198:201], v[40:43]
	v_mfma_f32_16x16x32_bf16 v[36:39], v[124:127], v[206:209], v[36:39]
	v_mfma_f32_16x16x32_bf16 v[24:27], v[132:135], v[206:209], v[24:27]
	v_mfma_f32_16x16x32_bf16 v[20:23], v[124:127], v[218:221], v[20:23]
	v_mfma_f32_16x16x32_bf16 v[8:11], v[132:135], v[218:221], v[8:11]
	s_setprio 0
	s_setprio 1
	v_mfma_f32_16x16x32_bf16 v[48:51], v[160:163], v[184:187], v[48:51]
	v_mfma_f32_16x16x32_bf16 v[44:47], v[176:179], v[184:187], v[44:47]
	v_mfma_f32_16x16x32_bf16 v[32:35], v[160:163], v[194:197], v[32:35]
	v_mfma_f32_16x16x32_bf16 v[28:31], v[176:179], v[194:197], v[28:31]
	v_mfma_f32_16x16x32_bf16 v[16:19], v[160:163], v[202:205], v[16:19]
	v_mfma_f32_16x16x32_bf16 v[12:15], v[176:179], v[202:205], v[12:15]
	v_mfma_f32_16x16x32_bf16 v[4:7], v[160:163], v[214:217], v[4:7]
	v_mfma_f32_16x16x32_bf16 v[0:3], v[176:179], v[214:217], v[0:3]
	v_mfma_f32_16x16x32_bf16 v[48:51], v[172:175], v[190:193], v[48:51]
	v_mfma_f32_16x16x32_bf16 v[44:47], v[180:183], v[190:193], v[44:47]
	v_mfma_f32_16x16x32_bf16 v[32:35], v[172:175], v[198:201], v[32:35]
	v_mfma_f32_16x16x32_bf16 v[28:31], v[180:183], v[198:201], v[28:31]
	v_mfma_f32_16x16x32_bf16 v[16:19], v[172:175], v[206:209], v[16:19]
	v_mfma_f32_16x16x32_bf16 v[12:15], v[180:183], v[206:209], v[12:15]
	v_mfma_f32_16x16x32_bf16 v[4:7], v[172:175], v[218:221], v[4:7]
	v_mfma_f32_16x16x32_bf16 v[0:3], v[180:183], v[218:221], v[0:3]
	s_setprio 0
	s_barrier
	s_add_i32 s59, s59, 2
	s_add_u32 s0, s0, 0x100
	s_addc_u32 s1, s1, 0
	s_cmpk_gt_u32 s59, 0x55
	s_mov_b64 s[34:35], s[38:39]
